# SWA tile loop: unmasked tiles run a copy of the body without band-mask instructions; MLP-up epilogue self-max removed; hyena bias wait deferred
# speedup vs baseline: 1.0069x; 1.0042x over previous
.LBB0_1211:
	s_bitcmp1_b32 s10, 0
	s_cselect_b32 s11, 0xb800, 0
	s_setprio 1
	v_or_b32_e32 v80, s11, v94
	v_add_u32_e32 v109, v80, v187
	ds_read_b128 v[220:223], v109
	ds_read_b128 v[224:227], v109 offset:64
	ds_read_b128 v[228:231], v109 offset:3328
	ds_read_b128 v[232:235], v109 offset:6656
	ds_read_b128 v[236:239], v109 offset:9984
	ds_read_b128 v[240:243], v109 offset:3392
	ds_read_b128 v[244:247], v109 offset:6720
	ds_read_b128 v[248:251], v109 offset:10048
	s_waitcnt lgkmcnt(7)
	v_mfma_f32_16x16x32_bf16 v[112:115], v[220:223], v[4:7], v[0:3]
	v_mfma_f32_16x16x32_bf16 v[82:85], v[220:223], v[16:19], v[0:3]
	ds_read_b128 v[220:223], v109 offset:128
	s_waitcnt lgkmcnt(7)
	v_mfma_f32_16x16x32_bf16 v[112:115], v[224:227], v[8:11], v[112:115]
	v_mfma_f32_16x16x32_bf16 v[82:85], v[224:227], v[20:23], v[82:85]
	ds_read_b128 v[224:227], v109 offset:3456
	s_waitcnt lgkmcnt(7)
	v_mfma_f32_16x16x32_bf16 v[120:123], v[228:231], v[4:7], v[0:3]
	v_mfma_f32_16x16x32_bf16 v[116:119], v[228:231], v[16:19], v[0:3]
	ds_read_b128 v[228:231], v109 offset:6784
	s_waitcnt lgkmcnt(5)
	v_mfma_f32_16x16x32_bf16 v[120:123], v[240:243], v[8:11], v[120:123]
	v_mfma_f32_16x16x32_bf16 v[116:119], v[240:243], v[20:23], v[116:119]
	ds_read_b128 v[240:243], v109 offset:10112
	v_mfma_f32_16x16x32_bf16 v[128:131], v[232:235], v[4:7], v[0:3]
	v_mfma_f32_16x16x32_bf16 v[124:127], v[232:235], v[16:19], v[0:3]
	s_waitcnt lgkmcnt(5)
	v_mfma_f32_16x16x32_bf16 v[128:131], v[244:247], v[8:11], v[128:131]
	v_mfma_f32_16x16x32_bf16 v[124:127], v[244:247], v[20:23], v[124:127]
	v_mfma_f32_16x16x32_bf16 v[136:139], v[236:239], v[4:7], v[0:3]
	v_mfma_f32_16x16x32_bf16 v[132:135], v[236:239], v[16:19], v[0:3]
	s_waitcnt lgkmcnt(4)
	v_mfma_f32_16x16x32_bf16 v[136:139], v[248:251], v[8:11], v[136:139]
	v_mfma_f32_16x16x32_bf16 v[132:135], v[248:251], v[20:23], v[132:135]
	s_waitcnt lgkmcnt(3)
	v_mfma_f32_16x16x32_bf16 v[148:151], v[220:223], v[24:27], v[82:85]
	s_waitcnt lgkmcnt(2)
	v_mfma_f32_16x16x32_bf16 v[120:123], v[224:227], v[12:15], v[120:123]
	v_mfma_f32_16x16x32_bf16 v[84:87], v[224:227], v[24:27], v[116:119]
	s_waitcnt lgkmcnt(1)
	v_mfma_f32_16x16x32_bf16 v[152:155], v[228:231], v[12:15], v[128:131]
	v_mfma_f32_16x16x32_bf16 v[156:159], v[228:231], v[24:27], v[124:127]
	v_mfma_f32_16x16x32_bf16 v[112:115], v[220:223], v[12:15], v[112:115]
	s_waitcnt lgkmcnt(0)
	v_mfma_f32_16x16x32_bf16 v[160:163], v[240:243], v[12:15], v[136:139]
	v_mfma_f32_16x16x32_bf16 v[164:167], v[240:243], v[24:27], v[132:135]
	s_nop 2
	s_setprio 0
	s_nop 3
	v_max3_f32 v80, v112, v113, v114
	v_max3_f32 v80, v80, v115, v120
	v_max3_f32 v80, v80, v121, v122
	v_max3_f32 v80, v80, v123, v152
	v_max3_f32 v80, v80, v153, v154
	v_max3_f32 v80, v80, v155, v160
	v_max3_f32 v80, v80, v161, v162
	v_max_f32_e32 v80, v80, v163
	v_mul_f32_e32 v80, 0x3e16c740, v80
	v_max_f32_e32 v80, s71, v80
	v_mov_b32_e32 v82, v80
	s_nop 1
	v_permlane16_swap_b32_e32 v80, v82
	v_max_f32_e32 v80, v80, v82
	v_mov_b32_e32 v82, v80
	s_nop 1
	v_permlane32_swap_b32_e32 v80, v82
	v_max3_f32 v144, v81, v80, v82
	v_sub_f32_e32 v80, v81, v144
	v_fma_f32 v81, v112, s70, -v144
	v_exp_f32_e32 v143, v81
	v_fma_f32 v81, v113, s70, -v144
	v_exp_f32_e32 v141, v81
	v_fma_f32 v81, v114, s70, -v144
	v_max3_f32 v112, v148, v149, v150
	v_max3_f32 v112, v112, v151, v84
	v_max3_f32 v112, v112, v85, v86
	v_max3_f32 v112, v112, v87, v156
	v_max3_f32 v112, v112, v157, v158
	v_max3_f32 v112, v112, v159, v164
	v_max3_f32 v112, v112, v165, v166
	v_max_f32_e32 v112, v112, v167
	v_mul_f32_e32 v112, 0x3e16c740, v112
	v_max_f32_e32 v112, s71, v112
	v_mov_b32_e32 v114, v112
	s_nop 1
	v_permlane16_swap_b32_e32 v112, v114
	v_max_f32_e32 v112, v112, v114
	v_mov_b32_e32 v114, v112
	v_exp_f32_e32 v139, v81
	v_fma_f32 v81, v115, s70, -v144
	v_permlane32_swap_b32_e32 v112, v114
	v_exp_f32_e32 v137, v81
	v_fma_f32 v81, v120, s70, -v144
	v_max3_f32 v146, v190, v112, v114
	v_exp_f32_e32 v135, v81
	v_fma_f32 v81, v121, s70, -v144
	v_fma_f32 v84, v84, s70, -v146
	v_exp_f32_e32 v133, v81
	v_fma_f32 v81, v122, s70, -v144
	v_exp_f32_e32 v134, v84
	v_fma_f32 v84, v85, s70, -v146
	v_exp_f32_e32 v131, v81
	v_fma_f32 v81, v123, s70, -v144
	v_exp_f32_e32 v132, v84
	v_fma_f32 v84, v86, s70, -v146
	v_exp_f32_e32 v129, v81
	v_fma_f32 v81, v152, s70, -v144
	v_exp_f32_e32 v130, v84
	v_fma_f32 v84, v87, s70, -v146
	v_exp_f32_e32 v127, v81
	v_fma_f32 v81, v153, s70, -v144
	v_exp_f32_e32 v128, v84
	v_fma_f32 v84, v156, s70, -v146
	v_exp_f32_e32 v125, v81
	v_fma_f32 v81, v154, s70, -v144
	v_exp_f32_e32 v126, v84
	v_fma_f32 v84, v157, s70, -v146
	v_exp_f32_e32 v123, v81
	v_fma_f32 v81, v155, s70, -v144
	v_fma_f32 v112, v148, s70, -v146
	v_exp_f32_e32 v124, v84
	v_fma_f32 v84, v158, s70, -v146
	v_exp_f32_e32 v119, v81
	v_fma_f32 v81, v160, s70, -v144
	v_exp_f32_e32 v142, v112
	v_fma_f32 v112, v149, s70, -v146
	v_exp_f32_e32 v122, v84
	v_fma_f32 v84, v159, s70, -v146
	v_exp_f32_e32 v115, v81
	v_fma_f32 v81, v161, s70, -v144
	v_exp_f32_e32 v140, v112
	v_fma_f32 v112, v150, s70, -v146
	v_exp_f32_e32 v118, v84
	v_fma_f32 v84, v164, s70, -v146
	v_fma_f32 v85, v166, s70, -v146
	v_exp_f32_e32 v113, v81
	v_fma_f32 v81, v162, s70, -v144
	v_exp_f32_e32 v110, v80
	v_fma_f32 v80, v163, s70, -v144
	v_sub_f32_e32 v116, v190, v146
	v_exp_f32_e32 v138, v112
	v_fma_f32 v112, v151, s70, -v146
	v_exp_f32_e32 v114, v84
	v_fma_f32 v84, v165, s70, -v146
	v_exp_f32_e32 v120, v85
	v_fma_f32 v85, v167, s70, -v146
	v_exp_f32_e32 v121, v81
	v_exp_f32_e32 v117, v80
	v_exp_f32_e32 v136, v112
	v_exp_f32_e32 v112, v84
	v_exp_f32_e32 v84, v116
	v_exp_f32_e32 v116, v85
	v_pk_mul_f32 v[70:71], v[70:71], v[110:111] op_sel_hi:[1,0]
	v_pk_mul_f32 v[68:69], v[68:69], v[110:111] op_sel_hi:[1,0]
	v_pk_mul_f32 v[66:67], v[66:67], v[110:111] op_sel_hi:[1,0]
	v_pk_mul_f32 v[64:65], v[64:65], v[110:111] op_sel_hi:[1,0]
	v_pk_mul_f32 v[74:75], v[74:75], v[110:111] op_sel_hi:[1,0]
	v_pk_mul_f32 v[72:73], v[72:73], v[110:111] op_sel_hi:[1,0]
	v_pk_mul_f32 v[82:83], v[78:79], v[110:111] op_sel_hi:[1,0]
	v_pk_mul_f32 v[80:81], v[76:77], v[110:111] op_sel_hi:[1,0]
	v_cvt_pk_bf16_f32 v152, v143, v141
	v_cvt_pk_bf16_f32 v153, v139, v137
	v_cvt_pk_bf16_f32 v154, v135, v133
	v_cvt_pk_bf16_f32 v155, v131, v129
	v_cvt_pk_bf16_f32 v76, v127, v125
	v_cvt_pk_bf16_f32 v77, v123, v119
	v_cvt_pk_bf16_f32 v78, v115, v113
	v_cvt_pk_bf16_f32 v79, v121, v117
	v_pk_mul_f32 v[54:55], v[54:55], v[84:85] op_sel_hi:[1,0]
	v_pk_mul_f32 v[52:53], v[52:53], v[84:85] op_sel_hi:[1,0]
	v_pk_mul_f32 v[50:51], v[50:51], v[84:85] op_sel_hi:[1,0]
	v_pk_mul_f32 v[48:49], v[48:49], v[84:85] op_sel_hi:[1,0]
	v_pk_mul_f32 v[58:59], v[58:59], v[84:85] op_sel_hi:[1,0]
	v_pk_mul_f32 v[56:57], v[56:57], v[84:85] op_sel_hi:[1,0]
	v_pk_mul_f32 v[62:63], v[62:63], v[84:85] op_sel_hi:[1,0]
	v_pk_mul_f32 v[60:61], v[60:61], v[84:85] op_sel_hi:[1,0]
	v_cvt_pk_bf16_f32 v148, v142, v140
	v_cvt_pk_bf16_f32 v149, v138, v136
	v_cvt_pk_bf16_f32 v150, v134, v132
	v_cvt_pk_bf16_f32 v151, v130, v128
	v_cvt_pk_bf16_f32 v156, v126, v124
	v_cvt_pk_bf16_f32 v157, v122, v118
	v_cvt_pk_bf16_f32 v158, v114, v112
	v_cvt_pk_bf16_f32 v159, v120, v116
	s_setprio 1
	v_add3_u32 v85, s11, v188, v189
	ds_read_b64_tr_b16 v[222:223], v85 offset:29184
	ds_read_b64_tr_b16 v[220:221], v85 offset:26624
	ds_read_b64_tr_b16 v[224:225], v85 offset:26656
	ds_read_b64_tr_b16 v[226:227], v85 offset:29216
	ds_read_b64_tr_b16 v[228:229], v85 offset:31744
	ds_read_b64_tr_b16 v[230:231], v85 offset:34304
	ds_read_b64_tr_b16 v[232:233], v85 offset:31776
	ds_read_b64_tr_b16 v[234:235], v85 offset:34336
	ds_read_b64_tr_b16 v[236:237], v85 offset:26688
	ds_read_b64_tr_b16 v[238:239], v85 offset:29248
	ds_read_b64_tr_b16 v[240:241], v85 offset:31808
	ds_read_b64_tr_b16 v[242:243], v85 offset:34368
	ds_read_b64_tr_b16 v[244:245], v85 offset:26720
	ds_read_b64_tr_b16 v[246:247], v85 offset:29280
	ds_read_b64_tr_b16 v[248:249], v85 offset:31840
	ds_read_b64_tr_b16 v[250:251], v85 offset:34400
	s_waitcnt lgkmcnt(14)
	v_mfma_f32_16x16x32_bf16 v[68:71], v[220:223], v[152:155], v[68:71]
	v_mfma_f32_16x16x32_bf16 v[52:55], v[220:223], v[148:151], v[52:55]
	s_waitcnt lgkmcnt(10)
	v_mfma_f32_16x16x32_bf16 v[68:71], v[228:231], v[76:79], v[68:71]
	v_mfma_f32_16x16x32_bf16 v[52:55], v[228:231], v[156:159], v[52:55]
	v_mfma_f32_16x16x32_bf16 v[64:67], v[224:227], v[152:155], v[64:67]
	v_mfma_f32_16x16x32_bf16 v[48:51], v[224:227], v[148:151], v[48:51]
	s_waitcnt lgkmcnt(8)
	v_mfma_f32_16x16x32_bf16 v[64:67], v[232:235], v[76:79], v[64:67]
	v_mfma_f32_16x16x32_bf16 v[48:51], v[232:235], v[156:159], v[48:51]
	s_waitcnt lgkmcnt(6)
	v_mfma_f32_16x16x32_bf16 v[72:75], v[236:239], v[152:155], v[72:75]
	v_mfma_f32_16x16x32_bf16 v[56:59], v[236:239], v[148:151], v[56:59]
	s_waitcnt lgkmcnt(4)
	v_mfma_f32_16x16x32_bf16 v[72:75], v[240:243], v[76:79], v[72:75]
	v_mfma_f32_16x16x32_bf16 v[56:59], v[240:243], v[156:159], v[56:59]
	s_waitcnt lgkmcnt(2)
	v_mfma_f32_16x16x32_bf16 v[60:63], v[244:247], v[148:151], v[60:63]
	v_mfma_f32_16x16x32_bf16 v[80:83], v[244:247], v[152:155], v[80:83]
	s_waitcnt lgkmcnt(0)
	v_mfma_f32_16x16x32_bf16 v[76:79], v[248:251], v[76:79], v[80:83]
	v_mfma_f32_16x16x32_bf16 v[60:63], v[248:251], v[156:159], v[60:63]
	s_nop 3
	s_setprio 0
	s_setprio 1
	ds_read_b128 v[220:223], v109 offset:13312
	ds_read_b128 v[224:227], v109 offset:13376
	ds_read_b128 v[228:231], v109 offset:16640
	ds_read_b128 v[232:235], v109 offset:19968
	ds_read_b128 v[236:239], v109 offset:23296
	ds_read_b128 v[240:243], v109 offset:16704
	ds_read_b128 v[244:247], v109 offset:20032
	ds_read_b128 v[248:251], v109 offset:23360
	s_waitcnt lgkmcnt(7)
	v_mfma_f32_16x16x32_bf16 v[148:151], v[220:223], v[4:7], v[0:3]
	v_mfma_f32_16x16x32_bf16 v[80:83], v[220:223], v[16:19], v[0:3]
	ds_read_b128 v[220:223], v109 offset:13440
	s_waitcnt lgkmcnt(7)
	v_mfma_f32_16x16x32_bf16 v[148:151], v[224:227], v[8:11], v[148:151]
	v_mfma_f32_16x16x32_bf16 v[80:83], v[224:227], v[20:23], v[80:83]
	ds_read_b128 v[224:227], v109 offset:16768
	s_waitcnt lgkmcnt(7)
	v_mfma_f32_16x16x32_bf16 v[156:159], v[228:231], v[4:7], v[0:3]
	v_mfma_f32_16x16x32_bf16 v[152:155], v[228:231], v[16:19], v[0:3]
	ds_read_b128 v[228:231], v109 offset:20096
	s_waitcnt lgkmcnt(5)
	v_mfma_f32_16x16x32_bf16 v[156:159], v[240:243], v[8:11], v[156:159]
	v_mfma_f32_16x16x32_bf16 v[152:155], v[240:243], v[20:23], v[152:155]
	ds_read_b128 v[240:243], v109 offset:23424
	v_mfma_f32_16x16x32_bf16 v[164:167], v[232:235], v[4:7], v[0:3]
	v_mfma_f32_16x16x32_bf16 v[160:163], v[232:235], v[16:19], v[0:3]
	s_waitcnt lgkmcnt(5)
	v_mfma_f32_16x16x32_bf16 v[164:167], v[244:247], v[8:11], v[164:167]
	v_mfma_f32_16x16x32_bf16 v[160:163], v[244:247], v[20:23], v[160:163]
	v_mfma_f32_16x16x32_bf16 v[190:193], v[236:239], v[4:7], v[0:3]
	v_mfma_f32_16x16x32_bf16 v[168:171], v[236:239], v[16:19], v[0:3]
	s_waitcnt lgkmcnt(4)
	v_mfma_f32_16x16x32_bf16 v[190:193], v[248:251], v[8:11], v[190:193]
	v_mfma_f32_16x16x32_bf16 v[168:171], v[248:251], v[20:23], v[168:171]
	s_waitcnt lgkmcnt(3)
	v_mfma_f32_16x16x32_bf16 v[148:151], v[220:223], v[12:15], v[148:151]
	v_mfma_f32_16x16x32_bf16 v[194:197], v[220:223], v[24:27], v[80:83]
	s_waitcnt lgkmcnt(2)
	v_mfma_f32_16x16x32_bf16 v[198:201], v[224:227], v[12:15], v[156:159]
	v_mfma_f32_16x16x32_bf16 v[202:205], v[224:227], v[24:27], v[152:155]
	s_waitcnt lgkmcnt(1)
	v_mfma_f32_16x16x32_bf16 v[206:209], v[228:231], v[12:15], v[164:167]
	v_mfma_f32_16x16x32_bf16 v[210:213], v[228:231], v[24:27], v[160:163]
	s_waitcnt lgkmcnt(0)
	v_mfma_f32_16x16x32_bf16 v[190:193], v[240:243], v[12:15], v[190:193]
	v_mfma_f32_16x16x32_bf16 v[214:217], v[240:243], v[24:27], v[168:171]
	s_nop 1
	s_setprio 0
	v_max3_f32 v80, v148, v149, v150
	v_max3_f32 v80, v80, v151, v198
	v_max3_f32 v80, v80, v199, v200
	v_max3_f32 v80, v80, v201, v206
	v_max3_f32 v80, v80, v207, v208
	v_max3_f32 v80, v80, v209, v190
	v_max3_f32 v80, v80, v191, v192
	v_max_f32_e32 v80, v80, v193
	v_mul_f32_e32 v80, 0x3e16c740, v80
	v_max_f32_e32 v80, s71, v80
	v_mov_b32_e32 v81, v80
	s_nop 1
	v_permlane16_swap_b32_e32 v80, v81
	v_max_f32_e32 v80, v80, v81
	v_mov_b32_e32 v81, v80
	s_nop 1
	v_permlane32_swap_b32_e32 v80, v81
	v_max3_f32 v81, v144, v80, v81
	v_fma_f32 v82, v148, s70, -v81
	v_exp_f32_e32 v171, v82
	v_fma_f32 v82, v149, s70, -v81
	v_exp_f32_e32 v169, v82
	v_fma_f32 v82, v150, s70, -v81
	v_exp_f32_e32 v167, v82
	v_fma_f32 v82, v151, s70, -v81
	v_exp_f32_e32 v165, v82
	v_fma_f32 v82, v198, s70, -v81
	v_exp_f32_e32 v163, v82
	v_fma_f32 v82, v199, s70, -v81
	v_exp_f32_e32 v161, v82
	v_fma_f32 v82, v200, s70, -v81
	v_exp_f32_e32 v159, v82
	v_fma_f32 v82, v201, s70, -v81
	v_exp_f32_e32 v157, v82
	v_fma_f32 v82, v206, s70, -v81
	v_exp_f32_e32 v155, v82
	v_fma_f32 v82, v207, s70, -v81
	v_exp_f32_e32 v153, v82
	v_fma_f32 v82, v208, s70, -v81
	v_exp_f32_e32 v151, v82
	v_fma_f32 v82, v209, s70, -v81
	v_exp_f32_e32 v147, v82
	v_fma_f32 v82, v190, s70, -v81
	v_exp_f32_e32 v87, v82
	v_fma_f32 v82, v191, s70, -v81
	v_exp_f32_e32 v83, v82
	v_fma_f32 v82, v192, s70, -v81
	v_exp_f32_e32 v149, v82
	v_fma_f32 v82, v193, s70, -v81
	v_exp_f32_e32 v145, v82
	v_max3_f32 v82, v194, v195, v196
	v_max3_f32 v82, v82, v197, v202
	v_max3_f32 v82, v82, v203, v204
	v_max3_f32 v82, v82, v205, v210
	v_max3_f32 v82, v82, v211, v212
	v_max3_f32 v82, v82, v213, v214
	v_max3_f32 v82, v82, v215, v216
	v_max_f32_e32 v82, v82, v217
	v_mul_f32_e32 v82, 0x3e16c740, v82
	v_max_f32_e32 v82, s71, v82
	v_mov_b32_e32 v86, v82
	s_nop 1
	v_permlane16_swap_b32_e32 v82, v86
	v_max_f32_e32 v82, v82, v86
	v_mov_b32_e32 v86, v82
	s_nop 1
	v_permlane32_swap_b32_e32 v82, v86
	v_max3_f32 v190, v146, v82, v86
	v_fma_f32 v82, v194, s70, -v190
	v_exp_f32_e32 v170, v82
	v_fma_f32 v82, v195, s70, -v190
	v_exp_f32_e32 v168, v82
	v_fma_f32 v82, v196, s70, -v190
	v_exp_f32_e32 v166, v82
	v_fma_f32 v82, v197, s70, -v190
	v_exp_f32_e32 v164, v82
	v_fma_f32 v82, v202, s70, -v190
	v_exp_f32_e32 v162, v82
	v_fma_f32 v82, v203, s70, -v190
	v_exp_f32_e32 v160, v82
	v_fma_f32 v82, v204, s70, -v190
	v_exp_f32_e32 v158, v82
	v_fma_f32 v82, v205, s70, -v190
	v_exp_f32_e32 v156, v82
	v_fma_f32 v82, v210, s70, -v190
	v_exp_f32_e32 v154, v82
	v_fma_f32 v82, v211, s70, -v190
	v_exp_f32_e32 v152, v82
	v_fma_f32 v82, v212, s70, -v190
	v_exp_f32_e32 v150, v82
	v_fma_f32 v82, v213, s70, -v190
	v_sub_f32_e32 v80, v144, v81
	v_sub_f32_e32 v109, v146, v190
	v_exp_f32_e32 v146, v82
	v_fma_f32 v82, v214, s70, -v190
	v_exp_f32_e32 v80, v80
	v_exp_f32_e32 v86, v82
	v_fma_f32 v82, v215, s70, -v190
	v_fma_f32 v144, v216, s70, -v190
	v_exp_f32_e32 v172, v109
	v_fma_f32 v109, v217, s70, -v190
	v_exp_f32_e32 v82, v82
	v_exp_f32_e32 v148, v144
	v_exp_f32_e32 v144, v109
	v_pk_mul_f32 v[70:71], v[70:71], v[80:81] op_sel_hi:[1,0]
	v_pk_mul_f32 v[68:69], v[68:69], v[80:81] op_sel_hi:[1,0]
	v_pk_mul_f32 v[66:67], v[66:67], v[80:81] op_sel_hi:[1,0]
	v_pk_mul_f32 v[64:65], v[64:65], v[80:81] op_sel_hi:[1,0]
	v_pk_mul_f32 v[74:75], v[74:75], v[80:81] op_sel_hi:[1,0]
	v_pk_mul_f32 v[72:73], v[72:73], v[80:81] op_sel_hi:[1,0]
	v_pk_mul_f32 v[200:201], v[78:79], v[80:81] op_sel_hi:[1,0]
	v_pk_mul_f32 v[198:199], v[76:77], v[80:81] op_sel_hi:[1,0]
	v_cvt_pk_bf16_f32 v76, v155, v153
	v_cvt_pk_bf16_f32 v77, v151, v147
	v_cvt_pk_bf16_f32 v78, v87, v83
	v_cvt_pk_bf16_f32 v79, v149, v145
	v_pk_mul_f32 v[54:55], v[54:55], v[172:173] op_sel_hi:[1,0]
	v_pk_mul_f32 v[52:53], v[52:53], v[172:173] op_sel_hi:[1,0]
	v_pk_mul_f32 v[50:51], v[50:51], v[172:173] op_sel_hi:[1,0]
	v_pk_mul_f32 v[48:49], v[48:49], v[172:173] op_sel_hi:[1,0]
	v_pk_mul_f32 v[58:59], v[58:59], v[172:173] op_sel_hi:[1,0]
	v_pk_mul_f32 v[56:57], v[56:57], v[172:173] op_sel_hi:[1,0]
	v_pk_mul_f32 v[62:63], v[62:63], v[172:173] op_sel_hi:[1,0]
	v_pk_mul_f32 v[60:61], v[60:61], v[172:173] op_sel_hi:[1,0]
	v_cvt_pk_bf16_f32 v206, v171, v169
	v_cvt_pk_bf16_f32 v207, v167, v165
	v_cvt_pk_bf16_f32 v208, v163, v161
	v_cvt_pk_bf16_f32 v209, v159, v157
	v_cvt_pk_bf16_f32 v192, v170, v168
	v_cvt_pk_bf16_f32 v193, v166, v164
	v_cvt_pk_bf16_f32 v194, v162, v160
	v_cvt_pk_bf16_f32 v195, v158, v156
	v_cvt_pk_bf16_f32 v202, v154, v152
	v_cvt_pk_bf16_f32 v203, v150, v146
	v_cvt_pk_bf16_f32 v204, v86, v82
	v_cvt_pk_bf16_f32 v205, v148, v144
	s_setprio 1
	ds_read_b64_tr_b16 v[222:223], v85 offset:39424
	ds_read_b64_tr_b16 v[220:221], v85 offset:36864
	ds_read_b64_tr_b16 v[224:225], v85 offset:36896
	ds_read_b64_tr_b16 v[226:227], v85 offset:39456
	ds_read_b64_tr_b16 v[228:229], v85 offset:41984
	ds_read_b64_tr_b16 v[230:231], v85 offset:44544
	ds_read_b64_tr_b16 v[232:233], v85 offset:42016
	ds_read_b64_tr_b16 v[234:235], v85 offset:44576
	ds_read_b64_tr_b16 v[236:237], v85 offset:36928
	ds_read_b64_tr_b16 v[238:239], v85 offset:39488
	ds_read_b64_tr_b16 v[240:241], v85 offset:42048
	ds_read_b64_tr_b16 v[242:243], v85 offset:44608
	ds_read_b64_tr_b16 v[244:245], v85 offset:36960
	ds_read_b64_tr_b16 v[246:247], v85 offset:39520
	ds_read_b64_tr_b16 v[248:249], v85 offset:42080
	ds_read_b64_tr_b16 v[250:251], v85 offset:44640
	s_waitcnt lgkmcnt(14)
	v_mfma_f32_16x16x32_bf16 v[68:71], v[220:223], v[206:209], v[68:71]
	v_mfma_f32_16x16x32_bf16 v[52:55], v[220:223], v[192:195], v[52:55]
	s_waitcnt lgkmcnt(10)
	v_mfma_f32_16x16x32_bf16 v[68:71], v[228:231], v[76:79], v[68:71]
	v_mfma_f32_16x16x32_bf16 v[52:55], v[228:231], v[202:205], v[52:55]
	v_mfma_f32_16x16x32_bf16 v[64:67], v[224:227], v[206:209], v[64:67]
	v_mfma_f32_16x16x32_bf16 v[48:51], v[224:227], v[192:195], v[48:51]
	s_waitcnt lgkmcnt(8)
	v_mfma_f32_16x16x32_bf16 v[64:67], v[232:235], v[76:79], v[64:67]
	v_mfma_f32_16x16x32_bf16 v[48:51], v[232:235], v[202:205], v[48:51]
	s_waitcnt lgkmcnt(6)
	v_mfma_f32_16x16x32_bf16 v[72:75], v[236:239], v[206:209], v[72:75]
	v_mfma_f32_16x16x32_bf16 v[56:59], v[236:239], v[192:195], v[56:59]
	s_waitcnt lgkmcnt(4)
	v_mfma_f32_16x16x32_bf16 v[72:75], v[240:243], v[76:79], v[72:75]
	v_mfma_f32_16x16x32_bf16 v[56:59], v[240:243], v[202:205], v[56:59]
	s_waitcnt lgkmcnt(2)
	v_mfma_f32_16x16x32_bf16 v[60:63], v[244:247], v[192:195], v[60:63]
	v_mfma_f32_16x16x32_bf16 v[196:199], v[244:247], v[206:209], v[198:201]
	s_waitcnt lgkmcnt(0)
	v_mfma_f32_16x16x32_bf16 v[76:79], v[248:251], v[76:79], v[196:199]
	v_mfma_f32_16x16x32_bf16 v[60:63], v[248:251], v[202:205], v[60:63]
	s_nop 3
	s_setprio 0
	s_add_i32 s22, s10, 1
	s_cmp_ge_u32 s22, s19
	s_cbranch_scc1 .LBB0_1213
	s_bitcmp1_b32 s22, 0
	s_cselect_b32 s11, 0xb800, 0
	v_add3_u32 v85, s11, v95, v96
	s_waitcnt vmcnt(0)
	ds_write_b128 v85, v[28:31]
	v_add3_u32 v85, s11, v99, v96
	ds_write_b128 v85, v[36:39]
	v_add3_u32 v85, s11, v185, v96
	ds_write_b128 v85, v[32:35] offset:26624
	v_add3_u32 v85, s11, v186, v96
	ds_write_b128 v85, v[40:43] offset:26624
	v_add3_u32 v85, s11, v111, v98
	ds_write_b128 v85, v[44:47] offset:128

.LBB0_1261:
	s_or_b64 exec, exec, s[6:7]
	s_ashr_i32 s12, s24, 2
	s_and_b32 s6, s12, -16
	s_max_i32 s13, s6, 64
	s_or_b32 s6, s12, 15
	s_add_i32 s18, s13, 0xffffff80
	s_min_i32 s19, s6, 64
	s_mov_b64 s[6:7], s[0:1]
	s_add_u32 s6, s6, s79
	s_addc_u32 s7, s7, s89
	s_waitcnt lgkmcnt(0)
	s_barrier
	s_load_dwordx2 s[6:7], s[6:7], 0x100
	s_ashr_i32 s11, s10, 31
	s_lshl_b64 s[10:11], s[10:11], 2
	v_bfe_u32 v4, v8, 4, 2
	v_bfi_b32 v5, -16, s12, v8
	s_waitcnt lgkmcnt(0)
	s_add_u32 s6, s6, s10
	s_addc_u32 s7, s7, s11
	global_load_dword v34, v89, s[6:7] offset:-128
	global_load_dword v35, v89, s[6:7] offset:896
	v_lshlrev_b32_e32 v4, 2, v4
	v_lshl_or_b32 v20, v5, 4, v4
	v_ashrrev_i32_e32 v21, 31, v20
	v_lshl_add_u64 v[4:5], v[20:21], 1, s[8:9]
	s_mov_b64 s[6:7], 0x7554000
	v_lshl_add_u64 v[22:23], v[4:5], 0, s[6:7]
	s_mov_b64 s[6:7], 0x7555000
	v_lshl_add_u64 v[24:25], v[4:5], 0, s[6:7]
	s_mov_b64 s[6:7], 0x7556000
	v_lshrrev_b32_e32 v7, 4, v8
	v_lshl_add_u64 v[26:27], v[4:5], 0, s[6:7]
	s_mov_b64 s[6:7], 0x7557000
	v_bfe_u32 v7, v7, 1, 1
	v_lshl_add_u64 v[28:29], v[4:5], 0, s[6:7]
	v_bfi_b32 v5, v8, 15, 1
	v_and_b32_e32 v4, 16, v8
	v_lshlrev_b32_e32 v5, 1, v5
	v_or_b32_e32 v7, s13, v7
	s_cmp_le_i32 s18, s19
	v_sub_u32_e32 v5, v4, v5
	v_lshlrev_b32_e32 v7, 5, v7
	v_and_b32_e32 v6, 15, v8
	s_cselect_b64 s[10:11], -1, 0
	v_sub_u32_e32 v5, v5, v7
	s_lshl_b32 s6, s12, 5
	v_add_u32_e32 v38, 0x183e, v5
	s_and_b32 s6, s6, 0xfffffe00
	v_lshlrev_b32_e32 v5, 5, v6
	v_or3_b32 v4, s6, v5, v4
	v_bitop3_b32 v36, v8, 1, v8 bitop3:0xc
	v_lshlrev_b32_e32 v37, 1, v20
	v_sub_u32_e32 v39, v4, v7
	s_mov_b32 s12, 0
	s_mov_b64 s[6:7], -1
	s_branch .LBB0_1263

.Lhy_lat0_done:
.LBB0_1266:
	s_waitcnt vmcnt(0)
	s_xor_b64 s[12:13], s[6:7], -1
	s_and_b64 s[16:17], s[6:7], exec
	s_cselect_b32 s16, s82, 0xddf2000
	s_add_u32 s16, s8, s16
	s_addc_u32 s17, s9, 0
	v_cndmask_b32_e64 v30, v35, v34, s[6:7]
	s_and_b64 s[6:7], s[6:7], exec
	s_mov_b32 s6, 0x9380
	s_cselect_b32 s6, 0x4380, s6
	v_lshl_add_u64 v[32:33], v[20:21], 1, s[16:17]
	v_lshl_add_u32 v31, v20, 1, s6
	s_movk_i32 s6, 0x2000
	v_add_co_u32_e32 v42, vcc, s6, v32
	ds_read_b64 v[40:41], v31
	s_nop 0
	v_addc_co_u32_e32 v43, vcc, 0, v33, vcc
	v_mov_b32_e32 v49, v18
	s_waitcnt lgkmcnt(0)
	v_lshlrev_b32_e32 v47, 16, v41
	v_lshlrev_b32_e32 v46, 16, v40
	v_and_b32_e32 v41, 0xffff0000, v41
	v_and_b32_e32 v40, 0xffff0000, v40
	v_mov_b32_e32 v18, v17
	v_mov_b32_e32 v48, v16
	v_pk_fma_f32 v[16:17], v[30:31], v[40:41], v[18:19] op_sel_hi:[0,1,1]
	v_pk_fma_f32 v[46:47], v[30:31], v[46:47], v[48:49] op_sel_hi:[0,1,1]
	s_mov_b64 s[6:7], -1
	s_and_b64 vcc, exec, s[12:13]
	s_waitcnt vmcnt(0)
	v_lshlrev_b32_e32 v45, 16, v141
	v_lshlrev_b32_e32 v44, 16, v140
	v_and_b32_e32 v43, 0xffff0000, v141
	v_and_b32_e32 v42, 0xffff0000, v140
	v_pk_mul_f32 v[16:17], v[16:17], v[42:43]
	v_pk_mul_f32 v[44:45], v[46:47], v[44:45]
	v_and_b32_sdwa v31, v17, v177 dst_sel:DWORD dst_unused:UNUSED_PAD src0_sel:WORD_1 src1_sel:DWORD
	v_and_b32_sdwa v40, v16, v177 dst_sel:DWORD dst_unused:UNUSED_PAD src0_sel:WORD_1 src1_sel:DWORD
	v_and_b32_sdwa v18, v45, v177 dst_sel:DWORD dst_unused:UNUSED_PAD src0_sel:WORD_1 src1_sel:DWORD
	v_and_b32_sdwa v19, v44, v177 dst_sel:DWORD dst_unused:UNUSED_PAD src0_sel:WORD_1 src1_sel:DWORD
	v_add3_u32 v17, v17, v31, s60
	v_add3_u32 v16, v16, v40, s60
	v_add3_u32 v19, v44, v19, s60
	v_add3_u32 v18, v45, v18, s60
	v_and_b32_e32 v17, 0xffff0000, v17
	v_and_b32_e32 v16, 0xffff0000, v16
	v_or_b32_sdwa v17, v17, v18 dst_sel:DWORD dst_unused:UNUSED_PAD src0_sel:DWORD src1_sel:WORD_1
	v_or_b32_sdwa v16, v16, v19 dst_sel:DWORD dst_unused:UNUSED_PAD src0_sel:DWORD src1_sel:WORD_1
	s_cbranch_vccz .LBB0_1268
	flat_store_dwordx2 v[22:23], v[16:17]
	s_mov_b64 s[6:7], 0

.LBB0_1301:
	s_bitcmp1_b32 s33, 0
	s_cselect_b32 s78, 0x9800, 0
	s_cmp_lt_i32 s33, s92
	s_cselect_b64 s[6:7], -1, 0
	s_and_b64 s[76:77], s[72:73], s[6:7]
	s_cmp_eq_u64 s[76:77], 0
	s_cbranch_scc1 .Lnm0_entry
	s_setprio 1
	v_or_b32_e32 v68, s78, v94
	v_add_u32_e32 v88, v68, v163
	ds_read_b128 v[204:207], v88 offset:2304
	ds_read_b128 v[208:211], v88
	ds_read_b128 v[212:215], v88 offset:4608
	ds_read_b128 v[216:219], v88 offset:6912
	ds_read_b128 v[220:223], v88 offset:64
	ds_read_b128 v[224:227], v88 offset:2368
	ds_read_b128 v[228:231], v88 offset:4672
	ds_read_b128 v[232:235], v88 offset:6976
	s_waitcnt lgkmcnt(7)
	v_mfma_f32_16x16x32_bf16 v[82:85], v[204:207], v[4:7], v[0:3]
	v_mfma_f32_16x16x32_bf16 v[108:111], v[204:207], v[12:15], v[0:3]
	s_waitcnt lgkmcnt(5)
	v_mfma_f32_16x16x32_bf16 v[112:115], v[212:215], v[4:7], v[0:3]
	v_mfma_f32_16x16x32_bf16 v[116:119], v[212:215], v[12:15], v[0:3]
	s_waitcnt lgkmcnt(4)
	v_mfma_f32_16x16x32_bf16 v[120:123], v[216:219], v[4:7], v[0:3]
	v_mfma_f32_16x16x32_bf16 v[124:127], v[216:219], v[12:15], v[0:3]
	v_mfma_f32_16x16x32_bf16 v[74:77], v[208:211], v[4:7], v[0:3]
	v_mfma_f32_16x16x32_bf16 v[68:71], v[208:211], v[12:15], v[0:3]
	s_waitcnt lgkmcnt(3)
	v_mfma_f32_16x16x32_bf16 v[128:131], v[220:223], v[8:11], v[74:77]
	v_mfma_f32_16x16x32_bf16 v[76:79], v[220:223], v[16:19], v[68:71]
	s_waitcnt lgkmcnt(2)
	v_mfma_f32_16x16x32_bf16 v[132:135], v[224:227], v[8:11], v[82:85]
	v_mfma_f32_16x16x32_bf16 v[80:83], v[224:227], v[16:19], v[108:111]
	s_waitcnt lgkmcnt(1)
	v_mfma_f32_16x16x32_bf16 v[108:111], v[228:231], v[8:11], v[112:115]
	v_mfma_f32_16x16x32_bf16 v[84:87], v[228:231], v[16:19], v[116:119]
	s_waitcnt lgkmcnt(0)
	v_mfma_f32_16x16x32_bf16 v[112:115], v[232:235], v[8:11], v[120:123]
	v_mfma_f32_16x16x32_bf16 v[142:145], v[232:235], v[16:19], v[124:127]
	s_nop 1
	s_setprio 0
	v_add_u32_e32 v69, 0x73, v166
	v_cmp_gt_u32_e32 vcc, s83, v69
	v_add_u32_e32 v70, 0x72, v166
	s_and_b64 s[12:13], s[76:77], vcc
	v_cmp_gt_u32_e32 vcc, s83, v70
	v_add_u32_e32 v72, 0x71, v166
	s_and_b64 s[14:15], s[76:77], vcc
	v_cmp_gt_u32_e32 vcc, s83, v72
	v_add_u32_e32 v74, 0x70, v166
	s_and_b64 s[16:17], s[76:77], vcc
	v_cmp_gt_u32_e32 vcc, s83, v74
	v_add_u32_e32 v75, 0x63, v166
	s_and_b64 s[18:19], s[76:77], vcc
	v_cmp_gt_u32_e32 vcc, s83, v75
	v_add_u32_e32 v106, 0x62, v166
	s_and_b64 s[20:21], s[76:77], vcc
	v_cmp_gt_u32_e32 vcc, s83, v106
	v_add_u32_e32 v116, 0x61, v166
	s_and_b64 s[22:23], s[76:77], vcc
	v_cmp_gt_u32_e32 vcc, s83, v116
	v_add_u32_e32 v117, 0x60, v166
	s_and_b64 s[24:25], s[76:77], vcc
	v_cmp_gt_u32_e32 vcc, s83, v117
	v_add_u32_e32 v117, 0x53, v166
	s_and_b64 s[26:27], s[76:77], vcc
	v_cmp_gt_u32_e32 vcc, s83, v117
	v_add_u32_e32 v117, 0x52, v166
	v_mul_f32_e32 v68, 0x3e38aa3b, v128
	v_mul_f32_e32 v69, 0x3e38aa3b, v129
	s_and_b64 s[28:29], s[76:77], vcc
	v_cmp_gt_u32_e32 vcc, s83, v117
	v_add_u32_e32 v117, 0x51, v166
	v_cndmask_b32_e64 v68, v68, v182, s[12:13]
	v_cndmask_b32_e64 v69, v69, v182, s[14:15]
	v_mul_f32_e32 v71, 0x3e38aa3b, v130
	v_mul_f32_e32 v72, 0x3e38aa3b, v131
	s_and_b64 s[30:31], s[76:77], vcc
	v_cmp_gt_u32_e32 vcc, s83, v117
	v_add_u32_e32 v117, 0x50, v166
	v_max3_f32 v70, v68, s71, v69
	v_cndmask_b32_e64 v71, v71, v182, s[16:17]
	v_cndmask_b32_e64 v72, v72, v182, s[18:19]
	v_mul_f32_e32 v74, 0x3e38aa3b, v132
	v_mul_f32_e32 v75, 0x3e38aa3b, v133
	s_and_b64 s[34:35], s[76:77], vcc
	v_cmp_gt_u32_e32 vcc, s83, v117
	v_add_u32_e32 v117, 0x43, v166
	v_max3_f32 v70, v70, v71, v72
	v_cndmask_b32_e64 v74, v74, v182, s[20:21]
	v_cndmask_b32_e64 v75, v75, v182, s[22:23]
	v_mul_f32_e32 v106, 0x3e38aa3b, v134
	v_mul_f32_e32 v116, 0x3e38aa3b, v135
	s_and_b64 s[36:37], s[76:77], vcc
	v_cmp_gt_u32_e32 vcc, s83, v117
	v_add_u32_e32 v117, 0x42, v166
	v_max3_f32 v70, v70, v74, v75
	v_cndmask_b32_e64 v106, v106, v182, s[24:25]
	v_cndmask_b32_e64 v116, v116, v182, s[26:27]
	v_mul_f32_e32 v108, 0x3e38aa3b, v108
	v_mul_f32_e32 v109, 0x3e38aa3b, v109
	v_cmp_gt_u32_e64 s[6:7], s83, v117
	v_add_u32_e32 v117, 0x41, v166
	v_max3_f32 v70, v70, v106, v116
	v_cndmask_b32_e64 v108, v108, v182, s[28:29]
	v_cndmask_b32_e64 v109, v109, v182, s[30:31]
	v_mul_f32_e32 v110, 0x3e38aa3b, v110
	v_mul_f32_e32 v111, 0x3e38aa3b, v111
	v_cmp_gt_u32_e64 s[8:9], s83, v117
	v_add_u32_e32 v117, 64, v166
	v_max3_f32 v70, v70, v108, v109
	v_cndmask_b32_e64 v110, v110, v182, s[34:35]
	v_cndmask_b32_e64 v111, v111, v182, s[36:37]
	v_mul_f32_e32 v112, 0x3e38aa3b, v112
	s_and_b64 vcc, s[76:77], vcc
	v_mul_f32_e32 v113, 0x3e38aa3b, v113
	s_and_b64 s[6:7], s[76:77], s[6:7]
	v_cmp_gt_u32_e64 s[10:11], s83, v117
	v_max3_f32 v70, v70, v110, v111
	v_cndmask_b32_e32 v112, v112, v182, vcc
	v_cndmask_b32_e64 v113, v113, v182, s[6:7]
	v_mul_f32_e32 v114, 0x3e38aa3b, v114
	s_and_b64 s[8:9], s[76:77], s[8:9]
	v_mul_f32_e32 v115, 0x3e38aa3b, v115
	s_and_b64 s[10:11], s[76:77], s[10:11]
	v_max3_f32 v70, v70, v112, v113
	v_cndmask_b32_e64 v114, v114, v182, s[8:9]
	v_cndmask_b32_e64 v118, v115, v182, s[10:11]
	v_max3_f32 v70, v70, v114, v118
	v_mov_b32_e32 v115, v70
	s_nop 1
	v_permlane16_swap_b32_e32 v70, v115
	v_max_f32_e32 v70, v70, v115
	v_mov_b32_e32 v115, v70
	s_nop 1
	v_permlane32_swap_b32_e32 v70, v115
	v_max3_f32 v140, v73, v70, v115
	v_sub_f32_e32 v68, v68, v140
	v_exp_f32_e32 v139, v68
	v_sub_f32_e32 v68, v69, v140
	v_exp_f32_e32 v137, v68
	v_sub_f32_e32 v68, v71, v140
	v_exp_f32_e32 v135, v68
	v_sub_f32_e32 v68, v72, v140
	v_exp_f32_e32 v133, v68
	v_sub_f32_e32 v68, v74, v140
	v_exp_f32_e32 v131, v68
	v_sub_f32_e32 v68, v75, v140
	v_exp_f32_e32 v129, v68
	v_sub_f32_e32 v68, v106, v140
	v_exp_f32_e32 v127, v68
	v_sub_f32_e32 v68, v116, v140
	v_exp_f32_e32 v125, v68
	v_sub_f32_e32 v68, v108, v140
	v_add_u32_e32 v108, 0x83, v166
	v_cmp_gt_u32_e64 s[40:41], s83, v108
	v_mul_f32_e32 v76, 0x3e38aa3b, v76
	s_and_b64 s[40:41], s[76:77], s[40:41]
	v_add_u32_e32 v108, 0x82, v166
	v_exp_f32_e32 v123, v68
	v_sub_f32_e32 v68, v109, v140
	v_cndmask_b32_e64 v76, v76, v182, s[40:41]
	v_cmp_gt_u32_e64 s[40:41], s83, v108
	v_exp_f32_e32 v121, v68
	v_sub_f32_e32 v68, v110, v140
	v_mul_f32_e32 v77, 0x3e38aa3b, v77
	s_and_b64 s[40:41], s[76:77], s[40:41]
	v_add_u32_e32 v110, 0x81, v166
	v_cndmask_b32_e64 v77, v77, v182, s[40:41]
	v_cmp_gt_u32_e64 s[40:41], s83, v110
	v_mul_f32_e32 v78, 0x3e38aa3b, v78
	s_and_b64 s[40:41], s[76:77], s[40:41]
	v_cndmask_b32_e64 v110, v78, v182, s[40:41]
	v_mul_f32_e32 v78, 0x3e38aa3b, v79
	v_add_u32_e32 v79, 0x80, v166
	v_cmp_gt_u32_e64 s[40:41], s83, v79
	s_and_b64 s[40:41], s[76:77], s[40:41]
	v_max3_f32 v108, v76, s71, v77
	v_cndmask_b32_e64 v79, v78, v182, s[40:41]
	v_mul_f32_e32 v80, 0x3e38aa3b, v80
	v_mul_f32_e32 v81, 0x3e38aa3b, v81
	v_exp_f32_e32 v119, v68
	v_sub_f32_e32 v68, v111, v140
	v_max3_f32 v78, v108, v110, v79
	v_cndmask_b32_e64 v80, v80, v182, s[12:13]
	v_cndmask_b32_e64 v81, v81, v182, s[14:15]
	v_mul_f32_e32 v82, 0x3e38aa3b, v82
	v_mul_f32_e32 v83, 0x3e38aa3b, v83
	v_exp_f32_e32 v115, v68
	v_sub_f32_e32 v68, v112, v140
	v_max3_f32 v78, v78, v80, v81
	v_cndmask_b32_e64 v82, v82, v182, s[16:17]
	v_cndmask_b32_e64 v83, v83, v182, s[18:19]
	v_mul_f32_e32 v84, 0x3e38aa3b, v84
	v_mul_f32_e32 v85, 0x3e38aa3b, v85
	v_exp_f32_e32 v111, v68
	v_sub_f32_e32 v68, v113, v140
	v_max3_f32 v78, v78, v82, v83
	v_cndmask_b32_e64 v84, v84, v182, s[20:21]
	v_cndmask_b32_e64 v85, v85, v182, s[22:23]
	v_mul_f32_e32 v86, 0x3e38aa3b, v86
	v_mul_f32_e32 v87, 0x3e38aa3b, v87
	v_exp_f32_e32 v109, v68
	v_sub_f32_e32 v68, v114, v140
	v_max3_f32 v78, v78, v84, v85
	v_cndmask_b32_e64 v86, v86, v182, s[24:25]
	v_cndmask_b32_e64 v87, v87, v182, s[26:27]
	v_mul_f32_e32 v108, 0x3e38aa3b, v142
	v_mul_f32_e32 v112, 0x3e38aa3b, v143
	v_mul_f32_e32 v114, 0x3e38aa3b, v144
	v_max3_f32 v78, v78, v86, v87
	v_cndmask_b32_e64 v108, v108, v182, s[28:29]
	v_cndmask_b32_e64 v112, v112, v182, s[30:31]
	v_cndmask_b32_e64 v116, v114, v182, s[34:35]
	v_mul_f32_e32 v114, 0x3e38aa3b, v145
	v_max3_f32 v78, v78, v108, v112
	v_cndmask_b32_e64 v141, v114, v182, s[36:37]
	v_max3_f32 v78, v78, v116, v141
	v_mov_b32_e32 v114, v78
	s_nop 1
	v_permlane16_swap_b32_e32 v78, v114
	v_max_f32_e32 v78, v78, v114
	v_mov_b32_e32 v114, v78
	s_nop 1
	v_permlane32_swap_b32_e32 v78, v114
	v_max3_f32 v78, v167, v78, v114
	v_sub_f32_e32 v76, v76, v78
	v_exp_f32_e32 v138, v76
	v_sub_f32_e32 v76, v77, v78
	v_exp_f32_e32 v136, v76
	v_sub_f32_e32 v76, v110, v78
	v_exp_f32_e32 v134, v76
	v_sub_f32_e32 v76, v79, v78
	v_exp_f32_e32 v132, v76
	v_sub_f32_e32 v76, v80, v78
	v_exp_f32_e32 v130, v76
	v_sub_f32_e32 v76, v81, v78
	v_exp_f32_e32 v128, v76
	v_sub_f32_e32 v76, v82, v78
	v_exp_f32_e32 v126, v76
	v_sub_f32_e32 v76, v83, v78
	v_exp_f32_e32 v124, v76
	v_sub_f32_e32 v76, v84, v78
	v_exp_f32_e32 v122, v76
	v_sub_f32_e32 v76, v85, v78
	v_exp_f32_e32 v120, v76
	v_sub_f32_e32 v76, v86, v78
	v_exp_f32_e32 v117, v68
	v_sub_f32_e32 v68, v118, v140
	v_exp_f32_e32 v118, v76
	v_sub_f32_e32 v76, v87, v78
	v_exp_f32_e32 v114, v76
	v_sub_f32_e32 v76, v108, v78
	v_sub_f32_e32 v77, v116, v78
	v_sub_f32_e32 v70, v73, v140
	v_sub_f32_e32 v142, v167, v78
	v_exp_f32_e32 v110, v76
	v_sub_f32_e32 v76, v112, v78
	v_exp_f32_e32 v116, v77
	v_sub_f32_e32 v77, v141, v78
	v_exp_f32_e32 v106, v70
	v_exp_f32_e32 v113, v68
	v_exp_f32_e32 v108, v76
	v_exp_f32_e32 v76, v142
	v_exp_f32_e32 v112, v77
	v_pk_mul_f32 v[58:59], v[58:59], v[106:107] op_sel_hi:[1,0]
	v_pk_mul_f32 v[56:57], v[56:57], v[106:107] op_sel_hi:[1,0]
	v_pk_mul_f32 v[54:55], v[54:55], v[106:107] op_sel_hi:[1,0]
	v_pk_mul_f32 v[52:53], v[52:53], v[106:107] op_sel_hi:[1,0]
	v_pk_mul_f32 v[62:63], v[62:63], v[106:107] op_sel_hi:[1,0]
	v_pk_mul_f32 v[60:61], v[60:61], v[106:107] op_sel_hi:[1,0]
	v_pk_mul_f32 v[70:71], v[66:67], v[106:107] op_sel_hi:[1,0]
	v_pk_mul_f32 v[68:69], v[64:65], v[106:107] op_sel_hi:[1,0]
	v_cvt_pk_bf16_f32 v72, v139, v137
	v_cvt_pk_bf16_f32 v73, v135, v133
	v_cvt_pk_bf16_f32 v74, v131, v129
	v_cvt_pk_bf16_f32 v75, v127, v125
	v_cvt_pk_bf16_f32 v64, v123, v121
	v_cvt_pk_bf16_f32 v65, v119, v115
	v_cvt_pk_bf16_f32 v66, v111, v109
	v_cvt_pk_bf16_f32 v67, v117, v113
	v_pk_mul_f32 v[42:43], v[42:43], v[76:77] op_sel_hi:[1,0]
	v_pk_mul_f32 v[40:41], v[40:41], v[76:77] op_sel_hi:[1,0]
	v_pk_mul_f32 v[38:39], v[38:39], v[76:77] op_sel_hi:[1,0]
	v_pk_mul_f32 v[36:37], v[36:37], v[76:77] op_sel_hi:[1,0]
	v_pk_mul_f32 v[46:47], v[46:47], v[76:77] op_sel_hi:[1,0]
	v_pk_mul_f32 v[44:45], v[44:45], v[76:77] op_sel_hi:[1,0]
	v_pk_mul_f32 v[50:51], v[50:51], v[76:77] op_sel_hi:[1,0]
	v_pk_mul_f32 v[48:49], v[48:49], v[76:77] op_sel_hi:[1,0]
	v_cvt_pk_bf16_f32 v80, v138, v136
	v_cvt_pk_bf16_f32 v81, v134, v132
	v_cvt_pk_bf16_f32 v82, v130, v128
	v_cvt_pk_bf16_f32 v83, v126, v124
	v_cvt_pk_bf16_f32 v84, v122, v120
	v_cvt_pk_bf16_f32 v85, v118, v114
	v_cvt_pk_bf16_f32 v86, v110, v108
	v_cvt_pk_bf16_f32 v87, v116, v112
	s_setprio 1
	v_add3_u32 v77, s78, v164, v165
	ds_read_b64_tr_b16 v[206:207], v77 offset:20992
	ds_read_b64_tr_b16 v[204:205], v77 offset:18432
	ds_read_b64_tr_b16 v[208:209], v77 offset:18464
	ds_read_b64_tr_b16 v[210:211], v77 offset:21024
	ds_read_b64_tr_b16 v[212:213], v77 offset:23552
	ds_read_b64_tr_b16 v[214:215], v77 offset:26112
	ds_read_b64_tr_b16 v[216:217], v77 offset:23584
	ds_read_b64_tr_b16 v[218:219], v77 offset:26144
	ds_read_b64_tr_b16 v[220:221], v77 offset:18496
	ds_read_b64_tr_b16 v[222:223], v77 offset:21056
	ds_read_b64_tr_b16 v[224:225], v77 offset:23616
	ds_read_b64_tr_b16 v[226:227], v77 offset:26176
	ds_read_b64_tr_b16 v[228:229], v77 offset:18528
	ds_read_b64_tr_b16 v[230:231], v77 offset:21088
	ds_read_b64_tr_b16 v[232:233], v77 offset:23648
	ds_read_b64_tr_b16 v[234:235], v77 offset:26208
	s_waitcnt lgkmcnt(14)
	v_mfma_f32_16x16x32_bf16 v[56:59], v[204:207], v[72:75], v[56:59]
	v_mfma_f32_16x16x32_bf16 v[40:43], v[204:207], v[80:83], v[40:43]
	s_waitcnt lgkmcnt(10)
	v_mfma_f32_16x16x32_bf16 v[56:59], v[212:215], v[64:67], v[56:59]
	v_mfma_f32_16x16x32_bf16 v[40:43], v[212:215], v[84:87], v[40:43]
	v_mfma_f32_16x16x32_bf16 v[52:55], v[208:211], v[72:75], v[52:55]
	v_mfma_f32_16x16x32_bf16 v[36:39], v[208:211], v[80:83], v[36:39]
	s_waitcnt lgkmcnt(8)
	v_mfma_f32_16x16x32_bf16 v[52:55], v[216:219], v[64:67], v[52:55]
	v_mfma_f32_16x16x32_bf16 v[36:39], v[216:219], v[84:87], v[36:39]
	s_waitcnt lgkmcnt(6)
	v_mfma_f32_16x16x32_bf16 v[60:63], v[220:223], v[72:75], v[60:63]
	v_mfma_f32_16x16x32_bf16 v[44:47], v[220:223], v[80:83], v[44:47]
	s_waitcnt lgkmcnt(4)
	v_mfma_f32_16x16x32_bf16 v[60:63], v[224:227], v[64:67], v[60:63]
	v_mfma_f32_16x16x32_bf16 v[44:47], v[224:227], v[84:87], v[44:47]
	s_waitcnt lgkmcnt(2)
	v_mfma_f32_16x16x32_bf16 v[68:71], v[228:231], v[72:75], v[68:71]
	v_mfma_f32_16x16x32_bf16 v[48:51], v[228:231], v[80:83], v[48:51]
	s_waitcnt lgkmcnt(0)
	v_mfma_f32_16x16x32_bf16 v[64:67], v[232:235], v[64:67], v[68:71]
	v_mfma_f32_16x16x32_bf16 v[48:51], v[232:235], v[84:87], v[48:51]
	s_nop 3
	s_setprio 0
	s_setprio 1
	ds_read_b128 v[204:207], v88 offset:9216
	ds_read_b128 v[208:211], v88 offset:9280
	ds_read_b128 v[212:215], v88 offset:11520
	ds_read_b128 v[216:219], v88 offset:13824
	ds_read_b128 v[220:223], v88 offset:16128
	ds_read_b128 v[224:227], v88 offset:11584
	ds_read_b128 v[228:231], v88 offset:13888
	ds_read_b128 v[232:235], v88 offset:16192
	s_waitcnt lgkmcnt(7)
	v_mfma_f32_16x16x32_bf16 v[72:75], v[204:207], v[4:7], v[0:3]
	v_mfma_f32_16x16x32_bf16 v[68:71], v[204:207], v[12:15], v[0:3]
	s_waitcnt lgkmcnt(6)
	v_mfma_f32_16x16x32_bf16 v[168:171], v[208:211], v[16:19], v[68:71]
	v_mfma_f32_16x16x32_bf16 v[72:75], v[208:211], v[8:11], v[72:75]
	s_waitcnt lgkmcnt(5)
	v_mfma_f32_16x16x32_bf16 v[84:87], v[212:215], v[4:7], v[0:3]
	v_mfma_f32_16x16x32_bf16 v[80:83], v[212:215], v[12:15], v[0:3]
	s_waitcnt lgkmcnt(2)
	v_mfma_f32_16x16x32_bf16 v[84:87], v[224:227], v[8:11], v[84:87]
	v_mfma_f32_16x16x32_bf16 v[186:189], v[224:227], v[16:19], v[80:83]
	v_mfma_f32_16x16x32_bf16 v[146:149], v[216:219], v[4:7], v[0:3]
	v_mfma_f32_16x16x32_bf16 v[142:145], v[216:219], v[12:15], v[0:3]
	s_waitcnt lgkmcnt(1)
	v_mfma_f32_16x16x32_bf16 v[80:83], v[228:231], v[8:11], v[146:149]
	v_mfma_f32_16x16x32_bf16 v[190:193], v[228:231], v[16:19], v[142:145]
	v_mfma_f32_16x16x32_bf16 v[154:157], v[220:223], v[4:7], v[0:3]
	v_mfma_f32_16x16x32_bf16 v[150:153], v[220:223], v[12:15], v[0:3]
	s_waitcnt lgkmcnt(0)
	v_mfma_f32_16x16x32_bf16 v[142:145], v[232:235], v[8:11], v[154:157]
	v_mfma_f32_16x16x32_bf16 v[194:197], v[232:235], v[16:19], v[150:153]
	s_nop 0
	s_setprio 0
	v_mul_f32_e32 v68, 0x3e38aa3b, v72
	v_add_u32_e32 v69, 51, v166
	v_mul_f32_e32 v71, 0x3e38aa3b, v74
	v_add_u32_e32 v72, 49, v166
	v_add_u32_e32 v74, 35, v166
	v_cmp_gt_u32_e64 s[12:13], s83, v69
	v_mul_f32_e32 v69, 0x3e38aa3b, v73
	v_cmp_gt_u32_e64 s[16:17], s83, v72
	v_mul_f32_e32 v72, 0x3e38aa3b, v75
	v_add_u32_e32 v73, 48, v166
	v_cmp_gt_u32_e64 s[20:21], s83, v74
	v_add_u32_e32 v75, 34, v166
	v_cmp_gt_u32_e64 s[18:19], s83, v73
	v_mul_f32_e32 v73, 0x3e38aa3b, v84
	s_and_b64 s[20:21], s[76:77], s[20:21]
	v_cmp_gt_u32_e64 s[22:23], s83, v75
	v_add_u32_e32 v79, 33, v166
	v_cndmask_b32_e64 v74, v73, v182, s[20:21]
	v_mul_f32_e32 v73, 0x3e38aa3b, v85
	s_and_b64 s[22:23], s[76:77], s[22:23]
	v_cmp_gt_u32_e64 s[24:25], s83, v79
	v_add_u32_e32 v84, 32, v166
	v_cndmask_b32_e64 v75, v73, v182, s[22:23]
	v_mul_f32_e32 v73, 0x3e38aa3b, v86
	s_and_b64 s[24:25], s[76:77], s[24:25]
	v_cmp_gt_u32_e64 s[26:27], s83, v84
	v_cndmask_b32_e64 v79, v73, v182, s[24:25]
	v_mul_f32_e32 v73, 0x3e38aa3b, v87
	s_and_b64 s[26:27], s[76:77], s[26:27]
	v_cndmask_b32_e64 v84, v73, v182, s[26:27]
	v_mul_f32_e32 v73, 0x3e38aa3b, v80
	v_add_u32_e32 v80, 19, v166
	v_cmp_gt_u32_e64 s[28:29], s83, v80
	s_and_b64 s[28:29], s[76:77], s[28:29]
	v_add_u32_e32 v70, 50, v166
	v_cndmask_b32_e64 v80, v73, v182, s[28:29]
	v_mul_f32_e32 v73, 0x3e38aa3b, v81
	v_add_u32_e32 v81, 18, v166
	v_cmp_gt_u32_e64 s[30:31], s83, v81
	s_and_b64 s[30:31], s[76:77], s[30:31]
	v_cmp_gt_u32_e64 s[14:15], s83, v70
	v_cndmask_b32_e64 v81, v73, v182, s[30:31]
	v_mul_f32_e32 v73, 0x3e38aa3b, v82
	v_add_u32_e32 v82, 17, v166
	v_cmp_gt_u32_e64 s[34:35], s83, v82
	s_and_b64 s[34:35], s[76:77], s[34:35]
	v_add_u32_e32 v85, 3, v166
	v_cndmask_b32_e64 v82, v73, v182, s[34:35]
	v_mul_f32_e32 v73, 0x3e38aa3b, v83
	v_add_u32_e32 v83, 16, v166
	v_cmp_gt_u32_e64 s[36:37], s83, v83
	s_and_b64 s[12:13], s[76:77], s[12:13]
	s_and_b64 s[14:15], s[76:77], s[14:15]
	s_and_b64 s[36:37], s[76:77], s[36:37]
	v_cmp_gt_u32_e64 s[40:41], s83, v85
	v_cndmask_b32_e64 v68, v68, v182, s[12:13]
	v_cndmask_b32_e64 v69, v69, v182, s[14:15]
	s_and_b64 s[16:17], s[76:77], s[16:17]
	s_and_b64 s[18:19], s[76:77], s[18:19]
	v_cndmask_b32_e64 v83, v73, v182, s[36:37]
	v_mul_f32_e32 v73, 0x3e38aa3b, v142
	s_and_b64 s[40:41], s[76:77], s[40:41]
	v_add_u32_e32 v86, 2, v166
	v_max3_f32 v70, v68, s71, v69
	v_cndmask_b32_e64 v71, v71, v182, s[16:17]
	v_cndmask_b32_e64 v72, v72, v182, s[18:19]
	v_cndmask_b32_e64 v85, v73, v182, s[40:41]
	v_cmp_gt_u32_e64 s[40:41], s83, v86
	v_max3_f32 v70, v70, v71, v72
	v_mul_f32_e32 v73, 0x3e38aa3b, v143
	s_and_b64 s[40:41], s[76:77], s[40:41]
	v_add_u32_e32 v87, 1, v166
	v_max3_f32 v70, v70, v74, v75
	v_cndmask_b32_e64 v86, v73, v182, s[40:41]
	v_cmp_gt_u32_e64 s[40:41], s83, v87
	v_max3_f32 v70, v70, v79, v84
	v_mul_f32_e32 v73, 0x3e38aa3b, v144
	s_and_b64 s[40:41], s[76:77], s[40:41]
	v_max3_f32 v70, v70, v80, v81
	v_cndmask_b32_e64 v88, v73, v182, s[40:41]
	v_cmp_gt_u32_e64 s[40:41], s83, v166
	v_max3_f32 v70, v70, v82, v83
	v_mul_f32_e32 v73, 0x3e38aa3b, v145
	s_and_b64 s[40:41], s[76:77], s[40:41]
	v_max3_f32 v70, v70, v85, v86
	v_cndmask_b32_e64 v142, v73, v182, s[40:41]
	v_max3_f32 v70, v70, v88, v142
	v_mov_b32_e32 v73, v70
	s_nop 1
	v_permlane16_swap_b32_e32 v70, v73
	v_max_f32_e32 v70, v70, v73
	v_mov_b32_e32 v73, v70
	s_nop 1
	v_permlane32_swap_b32_e32 v70, v73
	v_max3_f32 v73, v140, v70, v73
	v_sub_f32_e32 v68, v68, v73
	v_exp_f32_e32 v159, v68
	v_sub_f32_e32 v68, v69, v73
	v_exp_f32_e32 v157, v68
	v_sub_f32_e32 v68, v71, v73
	v_exp_f32_e32 v155, v68
	v_sub_f32_e32 v68, v72, v73
	v_exp_f32_e32 v153, v68
	v_sub_f32_e32 v68, v74, v73
	v_exp_f32_e32 v151, v68
	v_sub_f32_e32 v68, v75, v73
	v_exp_f32_e32 v149, v68
	v_sub_f32_e32 v68, v79, v73
	v_exp_f32_e32 v147, v68
	v_sub_f32_e32 v68, v84, v73
	v_exp_f32_e32 v145, v68
	v_sub_f32_e32 v68, v80, v73
	v_exp_f32_e32 v143, v68
	v_sub_f32_e32 v68, v81, v73
	v_exp_f32_e32 v141, v68
	v_sub_f32_e32 v68, v82, v73
	v_sub_f32_e32 v70, v140, v73
	v_exp_f32_e32 v87, v68
	v_sub_f32_e32 v68, v83, v73
	v_exp_f32_e32 v83, v68
	v_sub_f32_e32 v68, v85, v73
	v_exp_f32_e32 v72, v70
	v_exp_f32_e32 v79, v68
	v_sub_f32_e32 v68, v86, v73
	v_exp_f32_e32 v75, v68
	v_sub_f32_e32 v68, v88, v73
	v_exp_f32_e32 v85, v68
	v_sub_f32_e32 v68, v142, v73
	v_exp_f32_e32 v81, v68
	v_pk_mul_f32 v[68:69], v[64:65], v[72:73] op_sel_hi:[1,0]
	v_mul_f32_e32 v64, 0x3e38aa3b, v168
	v_cndmask_b32_e32 v74, v64, v182, vcc
	v_mul_f32_e32 v64, 0x3e38aa3b, v169
	v_cndmask_b32_e64 v80, v64, v182, s[6:7]
	v_mul_f32_e32 v64, 0x3e38aa3b, v170
	v_cndmask_b32_e64 v82, v64, v182, s[8:9]
	v_mul_f32_e32 v64, 0x3e38aa3b, v171
	v_cndmask_b32_e64 v84, v64, v182, s[10:11]
	v_mul_f32_e32 v64, 0x3e38aa3b, v186
	v_cndmask_b32_e64 v86, v64, v182, s[12:13]
	v_mul_f32_e32 v64, 0x3e38aa3b, v187
	v_cndmask_b32_e64 v88, v64, v182, s[14:15]
	v_mul_f32_e32 v64, 0x3e38aa3b, v188
	v_cndmask_b32_e64 v140, v64, v182, s[16:17]
	v_mul_f32_e32 v64, 0x3e38aa3b, v189
	v_cndmask_b32_e64 v142, v64, v182, s[18:19]
	v_mul_f32_e32 v64, 0x3e38aa3b, v190
	v_cndmask_b32_e64 v160, v64, v182, s[20:21]
	v_mul_f32_e32 v64, 0x3e38aa3b, v191
	v_cndmask_b32_e64 v161, v64, v182, s[22:23]
	v_mul_f32_e32 v64, 0x3e38aa3b, v192
	v_cndmask_b32_e64 v172, v64, v182, s[24:25]
	v_mul_f32_e32 v64, 0x3e38aa3b, v193
	v_cndmask_b32_e64 v173, v64, v182, s[26:27]
	v_mul_f32_e32 v64, 0x3e38aa3b, v194
	v_cndmask_b32_e64 v185, v64, v182, s[28:29]
	v_mul_f32_e32 v64, 0x3e38aa3b, v195
	v_cndmask_b32_e64 v186, v64, v182, s[30:31]
	v_mul_f32_e32 v64, 0x3e38aa3b, v196
	v_cndmask_b32_e64 v187, v64, v182, s[34:35]
	v_mul_f32_e32 v64, 0x3e38aa3b, v197
	v_cndmask_b32_e64 v188, v64, v182, s[36:37]
	v_max3_f32 v64, v74, s71, v80
	v_max3_f32 v64, v64, v82, v84
	v_max3_f32 v64, v64, v86, v88
	v_max3_f32 v64, v64, v140, v142
	v_max3_f32 v64, v64, v160, v161
	v_max3_f32 v64, v64, v172, v173
	v_max3_f32 v144, v64, v185, v186
	v_max3_f32 v144, v144, v187, v188
	v_mov_b32_e32 v146, v144
	s_nop 1
	v_permlane16_swap_b32_e32 v144, v146
	v_max_f32_e32 v144, v144, v146
	v_mov_b32_e32 v146, v144
	s_nop 1
	v_permlane32_swap_b32_e32 v144, v146
	v_max3_f32 v167, v78, v144, v146
	v_sub_f32_e32 v74, v74, v167
	v_exp_f32_e32 v158, v74
	v_sub_f32_e32 v74, v80, v167
	v_exp_f32_e32 v156, v74
	v_sub_f32_e32 v74, v82, v167
	v_exp_f32_e32 v154, v74
	v_sub_f32_e32 v74, v84, v167
	v_exp_f32_e32 v152, v74
	v_sub_f32_e32 v74, v86, v167
	v_exp_f32_e32 v150, v74
	v_sub_f32_e32 v74, v88, v167
	v_exp_f32_e32 v148, v74
	v_sub_f32_e32 v74, v140, v167
	v_exp_f32_e32 v146, v74
	v_sub_f32_e32 v74, v142, v167
	v_exp_f32_e32 v144, v74
	v_sub_f32_e32 v74, v160, v167
	v_exp_f32_e32 v142, v74
	v_sub_f32_e32 v74, v161, v167
	v_exp_f32_e32 v140, v74
	v_sub_f32_e32 v74, v172, v167
	v_exp_f32_e32 v86, v74
	v_sub_f32_e32 v74, v173, v167
	v_sub_f32_e32 v189, v78, v167
	v_exp_f32_e32 v82, v74
	v_sub_f32_e32 v74, v185, v167
	v_sub_f32_e32 v80, v187, v167
	v_exp_f32_e32 v78, v74
	v_sub_f32_e32 v74, v186, v167
	v_exp_f32_e32 v160, v189
	v_exp_f32_e32 v84, v80
	v_sub_f32_e32 v80, v188, v167
	v_exp_f32_e32 v74, v74
	v_exp_f32_e32 v80, v80
	v_pk_mul_f32 v[58:59], v[58:59], v[72:73] op_sel_hi:[1,0]
	v_pk_mul_f32 v[56:57], v[56:57], v[72:73] op_sel_hi:[1,0]
	v_pk_mul_f32 v[54:55], v[54:55], v[72:73] op_sel_hi:[1,0]
	v_pk_mul_f32 v[52:53], v[52:53], v[72:73] op_sel_hi:[1,0]
	v_pk_mul_f32 v[62:63], v[62:63], v[72:73] op_sel_hi:[1,0]
	v_pk_mul_f32 v[60:61], v[60:61], v[72:73] op_sel_hi:[1,0]
	v_pk_mul_f32 v[70:71], v[66:67], v[72:73] op_sel_hi:[1,0]
	v_cvt_pk_bf16_f32 v64, v143, v141
	v_cvt_pk_bf16_f32 v65, v87, v83
	v_cvt_pk_bf16_f32 v66, v79, v75
	v_cvt_pk_bf16_f32 v67, v85, v81
	v_pk_mul_f32 v[42:43], v[42:43], v[160:161] op_sel_hi:[1,0]
	v_pk_mul_f32 v[40:41], v[40:41], v[160:161] op_sel_hi:[1,0]
	v_pk_mul_f32 v[38:39], v[38:39], v[160:161] op_sel_hi:[1,0]
	v_pk_mul_f32 v[36:37], v[36:37], v[160:161] op_sel_hi:[1,0]
	v_pk_mul_f32 v[46:47], v[46:47], v[160:161] op_sel_hi:[1,0]
	v_pk_mul_f32 v[44:45], v[44:45], v[160:161] op_sel_hi:[1,0]
	v_pk_mul_f32 v[50:51], v[50:51], v[160:161] op_sel_hi:[1,0]
	v_pk_mul_f32 v[48:49], v[48:49], v[160:161] op_sel_hi:[1,0]
	v_cvt_pk_bf16_f32 v168, v159, v157
	v_cvt_pk_bf16_f32 v169, v155, v153
	v_cvt_pk_bf16_f32 v170, v151, v149
	v_cvt_pk_bf16_f32 v171, v147, v145
	v_cvt_pk_bf16_f32 v186, v158, v156
	v_cvt_pk_bf16_f32 v187, v154, v152
	v_cvt_pk_bf16_f32 v188, v150, v148
	v_cvt_pk_bf16_f32 v189, v146, v144
	v_cvt_pk_bf16_f32 v190, v142, v140
	v_cvt_pk_bf16_f32 v191, v86, v82
	v_cvt_pk_bf16_f32 v192, v78, v74
	v_cvt_pk_bf16_f32 v193, v84, v80
	s_setprio 1
	ds_read_b64_tr_b16 v[206:207], v77 offset:31232
	ds_read_b64_tr_b16 v[204:205], v77 offset:28672
	ds_read_b64_tr_b16 v[208:209], v77 offset:28704
	ds_read_b64_tr_b16 v[210:211], v77 offset:31264
	ds_read_b64_tr_b16 v[212:213], v77 offset:33792
	ds_read_b64_tr_b16 v[214:215], v77 offset:36352
	ds_read_b64_tr_b16 v[216:217], v77 offset:33824
	ds_read_b64_tr_b16 v[218:219], v77 offset:36384
	ds_read_b64_tr_b16 v[220:221], v77 offset:28736
	ds_read_b64_tr_b16 v[222:223], v77 offset:31296
	ds_read_b64_tr_b16 v[224:225], v77 offset:33856
	ds_read_b64_tr_b16 v[226:227], v77 offset:36416
	ds_read_b64_tr_b16 v[228:229], v77 offset:28768
	ds_read_b64_tr_b16 v[230:231], v77 offset:31328
	ds_read_b64_tr_b16 v[232:233], v77 offset:33888
	ds_read_b64_tr_b16 v[234:235], v77 offset:36448
	s_waitcnt lgkmcnt(14)
	v_mfma_f32_16x16x32_bf16 v[56:59], v[204:207], v[168:171], v[56:59]
	v_mfma_f32_16x16x32_bf16 v[40:43], v[204:207], v[186:189], v[40:43]
	s_waitcnt lgkmcnt(10)
	v_mfma_f32_16x16x32_bf16 v[56:59], v[212:215], v[64:67], v[56:59]
	v_mfma_f32_16x16x32_bf16 v[40:43], v[212:215], v[190:193], v[40:43]
	v_mfma_f32_16x16x32_bf16 v[52:55], v[208:211], v[168:171], v[52:55]
	v_mfma_f32_16x16x32_bf16 v[36:39], v[208:211], v[186:189], v[36:39]
	s_waitcnt lgkmcnt(8)
	v_mfma_f32_16x16x32_bf16 v[52:55], v[216:219], v[64:67], v[52:55]
	v_mfma_f32_16x16x32_bf16 v[36:39], v[216:219], v[190:193], v[36:39]
	s_waitcnt lgkmcnt(6)
	v_mfma_f32_16x16x32_bf16 v[60:63], v[220:223], v[168:171], v[60:63]
	v_mfma_f32_16x16x32_bf16 v[44:47], v[220:223], v[186:189], v[44:47]
	s_waitcnt lgkmcnt(4)
	v_mfma_f32_16x16x32_bf16 v[60:63], v[224:227], v[64:67], v[60:63]
	v_mfma_f32_16x16x32_bf16 v[44:47], v[224:227], v[190:193], v[44:47]
	s_waitcnt lgkmcnt(2)
	v_mfma_f32_16x16x32_bf16 v[68:71], v[228:231], v[168:171], v[68:71]
	v_mfma_f32_16x16x32_bf16 v[48:51], v[228:231], v[186:189], v[48:51]
	s_waitcnt lgkmcnt(0)
	v_mfma_f32_16x16x32_bf16 v[64:67], v[232:235], v[64:67], v[68:71]
	v_mfma_f32_16x16x32_bf16 v[48:51], v[232:235], v[190:193], v[48:51]
	s_nop 3
	s_setprio 0
	s_add_i32 s12, s33, 1
	s_cmp_ge_i32 s12, s44
	s_cbranch_scc1 .LBB0_1303
	s_bitcmp1_b32 s12, 0
	s_cselect_b32 s6, 0x9800, 0
	v_add3_u32 v71, s6, v99, v98
	v_add3_u32 v68, s6, v162, v98
	v_add3_u32 v69, s6, v107, v98
	v_add3_u32 v70, s6, v103, v98
	s_waitcnt vmcnt(0)
	ds_write_b128 v71, v[20:23]
	ds_write_b128 v70, v[24:27]
	ds_write_b128 v69, v[28:31] offset:18432
	ds_write_b128 v68, v[32:35] offset:18432

.Lnm0_entry:
	s_setprio 1
	v_or_b32_e32 v68, s78, v94
	v_add_u32_e32 v88, v68, v163
	ds_read_b128 v[204:207], v88 offset:2304
	ds_read_b128 v[208:211], v88
	ds_read_b128 v[212:215], v88 offset:4608
	ds_read_b128 v[216:219], v88 offset:6912
	ds_read_b128 v[220:223], v88 offset:64
	ds_read_b128 v[224:227], v88 offset:2368
	ds_read_b128 v[228:231], v88 offset:4672
	ds_read_b128 v[232:235], v88 offset:6976
	s_waitcnt lgkmcnt(7)
	v_mfma_f32_16x16x32_bf16 v[82:85], v[204:207], v[4:7], v[0:3]
	v_mfma_f32_16x16x32_bf16 v[108:111], v[204:207], v[12:15], v[0:3]
	s_waitcnt lgkmcnt(5)
	v_mfma_f32_16x16x32_bf16 v[112:115], v[212:215], v[4:7], v[0:3]
	v_mfma_f32_16x16x32_bf16 v[116:119], v[212:215], v[12:15], v[0:3]
	s_waitcnt lgkmcnt(4)
	v_mfma_f32_16x16x32_bf16 v[120:123], v[216:219], v[4:7], v[0:3]
	v_mfma_f32_16x16x32_bf16 v[124:127], v[216:219], v[12:15], v[0:3]
	v_mfma_f32_16x16x32_bf16 v[74:77], v[208:211], v[4:7], v[0:3]
	v_mfma_f32_16x16x32_bf16 v[68:71], v[208:211], v[12:15], v[0:3]
	s_waitcnt lgkmcnt(3)
	v_mfma_f32_16x16x32_bf16 v[128:131], v[220:223], v[8:11], v[74:77]
	v_mfma_f32_16x16x32_bf16 v[76:79], v[220:223], v[16:19], v[68:71]
	s_waitcnt lgkmcnt(2)
	v_mfma_f32_16x16x32_bf16 v[132:135], v[224:227], v[8:11], v[82:85]
	v_mfma_f32_16x16x32_bf16 v[80:83], v[224:227], v[16:19], v[108:111]
	s_waitcnt lgkmcnt(1)
	v_mfma_f32_16x16x32_bf16 v[108:111], v[228:231], v[8:11], v[112:115]
	v_mfma_f32_16x16x32_bf16 v[84:87], v[228:231], v[16:19], v[116:119]
	s_waitcnt lgkmcnt(0)
	v_mfma_f32_16x16x32_bf16 v[112:115], v[232:235], v[8:11], v[120:123]
	v_mfma_f32_16x16x32_bf16 v[142:145], v[232:235], v[16:19], v[124:127]
	s_nop 1
	s_setprio 0
	v_mul_f32_e32 v68, 0x3e38aa3b, v128
	v_mul_f32_e32 v69, 0x3e38aa3b, v129
	v_mul_f32_e32 v71, 0x3e38aa3b, v130
	v_mul_f32_e32 v72, 0x3e38aa3b, v131
	v_max3_f32 v70, v68, s71, v69
	v_mul_f32_e32 v74, 0x3e38aa3b, v132
	v_mul_f32_e32 v75, 0x3e38aa3b, v133
	v_max3_f32 v70, v70, v71, v72
	v_mul_f32_e32 v106, 0x3e38aa3b, v134
	v_mul_f32_e32 v116, 0x3e38aa3b, v135
	v_max3_f32 v70, v70, v74, v75
	v_mul_f32_e32 v108, 0x3e38aa3b, v108
	v_mul_f32_e32 v109, 0x3e38aa3b, v109
	v_max3_f32 v70, v70, v106, v116
	v_mul_f32_e32 v110, 0x3e38aa3b, v110
	v_mul_f32_e32 v111, 0x3e38aa3b, v111
	v_max3_f32 v70, v70, v108, v109
	v_mul_f32_e32 v112, 0x3e38aa3b, v112
	v_mul_f32_e32 v113, 0x3e38aa3b, v113
	v_max3_f32 v70, v70, v110, v111
	v_mul_f32_e32 v114, 0x3e38aa3b, v114
	v_mul_f32_e32 v115, 0x3e38aa3b, v115
	v_max3_f32 v70, v70, v112, v113
	v_mov_b32_e32 v118, v115
	v_max3_f32 v70, v70, v114, v118
	v_mov_b32_e32 v115, v70
	s_nop 1
	v_permlane16_swap_b32_e32 v70, v115
	v_max_f32_e32 v70, v70, v115
	v_mov_b32_e32 v115, v70
	s_nop 1
	v_permlane32_swap_b32_e32 v70, v115
	v_max3_f32 v140, v73, v70, v115
	v_sub_f32_e32 v68, v68, v140
	v_exp_f32_e32 v139, v68
	v_sub_f32_e32 v68, v69, v140
	v_exp_f32_e32 v137, v68
	v_sub_f32_e32 v68, v71, v140
	v_exp_f32_e32 v135, v68
	v_sub_f32_e32 v68, v72, v140
	v_exp_f32_e32 v133, v68
	v_sub_f32_e32 v68, v74, v140
	v_exp_f32_e32 v131, v68
	v_sub_f32_e32 v68, v75, v140
	v_exp_f32_e32 v129, v68
	v_sub_f32_e32 v68, v106, v140
	v_exp_f32_e32 v127, v68
	v_sub_f32_e32 v68, v116, v140
	v_exp_f32_e32 v125, v68
	v_sub_f32_e32 v68, v108, v140
	v_mul_f32_e32 v76, 0x3e38aa3b, v76
	v_exp_f32_e32 v123, v68
	v_sub_f32_e32 v68, v109, v140
	v_exp_f32_e32 v121, v68
	v_sub_f32_e32 v68, v110, v140
	v_mul_f32_e32 v77, 0x3e38aa3b, v77
	v_mul_f32_e32 v78, 0x3e38aa3b, v78
	v_mov_b32_e32 v110, v78
	v_mul_f32_e32 v78, 0x3e38aa3b, v79
	v_max3_f32 v108, v76, s71, v77
	v_mov_b32_e32 v79, v78
	v_mul_f32_e32 v80, 0x3e38aa3b, v80
	v_mul_f32_e32 v81, 0x3e38aa3b, v81
	v_exp_f32_e32 v119, v68
	v_sub_f32_e32 v68, v111, v140
	v_max3_f32 v78, v108, v110, v79
	v_mul_f32_e32 v82, 0x3e38aa3b, v82
	v_mul_f32_e32 v83, 0x3e38aa3b, v83
	v_exp_f32_e32 v115, v68
	v_sub_f32_e32 v68, v112, v140
	v_max3_f32 v78, v78, v80, v81
	v_mul_f32_e32 v84, 0x3e38aa3b, v84
	v_mul_f32_e32 v85, 0x3e38aa3b, v85
	v_exp_f32_e32 v111, v68
	v_sub_f32_e32 v68, v113, v140
	v_max3_f32 v78, v78, v82, v83
	v_mul_f32_e32 v86, 0x3e38aa3b, v86
	v_mul_f32_e32 v87, 0x3e38aa3b, v87
	v_exp_f32_e32 v109, v68
	v_sub_f32_e32 v68, v114, v140
	v_max3_f32 v78, v78, v84, v85
	v_mul_f32_e32 v108, 0x3e38aa3b, v142
	v_mul_f32_e32 v112, 0x3e38aa3b, v143
	v_mul_f32_e32 v114, 0x3e38aa3b, v144
	v_max3_f32 v78, v78, v86, v87
	v_mov_b32_e32 v116, v114
	v_mul_f32_e32 v114, 0x3e38aa3b, v145
	v_max3_f32 v78, v78, v108, v112
	v_mov_b32_e32 v141, v114
	v_max3_f32 v78, v78, v116, v141
	v_mov_b32_e32 v114, v78
	s_nop 1
	v_permlane16_swap_b32_e32 v78, v114
	v_max_f32_e32 v78, v78, v114
	v_mov_b32_e32 v114, v78
	s_nop 1
	v_permlane32_swap_b32_e32 v78, v114
	v_max3_f32 v78, v167, v78, v114
	v_sub_f32_e32 v76, v76, v78
	v_exp_f32_e32 v138, v76
	v_sub_f32_e32 v76, v77, v78
	v_exp_f32_e32 v136, v76
	v_sub_f32_e32 v76, v110, v78
	v_exp_f32_e32 v134, v76
	v_sub_f32_e32 v76, v79, v78
	v_exp_f32_e32 v132, v76
	v_sub_f32_e32 v76, v80, v78
	v_exp_f32_e32 v130, v76
	v_sub_f32_e32 v76, v81, v78
	v_exp_f32_e32 v128, v76
	v_sub_f32_e32 v76, v82, v78
	v_exp_f32_e32 v126, v76
	v_sub_f32_e32 v76, v83, v78
	v_exp_f32_e32 v124, v76
	v_sub_f32_e32 v76, v84, v78
	v_exp_f32_e32 v122, v76
	v_sub_f32_e32 v76, v85, v78
	v_exp_f32_e32 v120, v76
	v_sub_f32_e32 v76, v86, v78
	v_exp_f32_e32 v117, v68
	v_sub_f32_e32 v68, v118, v140
	v_exp_f32_e32 v118, v76
	v_sub_f32_e32 v76, v87, v78
	v_exp_f32_e32 v114, v76
	v_sub_f32_e32 v76, v108, v78
	v_sub_f32_e32 v77, v116, v78
	v_sub_f32_e32 v70, v73, v140
	v_sub_f32_e32 v142, v167, v78
	v_exp_f32_e32 v110, v76
	v_sub_f32_e32 v76, v112, v78
	v_exp_f32_e32 v116, v77
	v_sub_f32_e32 v77, v141, v78
	v_exp_f32_e32 v106, v70
	v_exp_f32_e32 v113, v68
	v_exp_f32_e32 v108, v76
	v_exp_f32_e32 v76, v142
	v_exp_f32_e32 v112, v77
	v_pk_mul_f32 v[58:59], v[58:59], v[106:107] op_sel_hi:[1,0]
	v_pk_mul_f32 v[56:57], v[56:57], v[106:107] op_sel_hi:[1,0]
	v_pk_mul_f32 v[54:55], v[54:55], v[106:107] op_sel_hi:[1,0]
	v_pk_mul_f32 v[52:53], v[52:53], v[106:107] op_sel_hi:[1,0]
	v_pk_mul_f32 v[62:63], v[62:63], v[106:107] op_sel_hi:[1,0]
	v_pk_mul_f32 v[60:61], v[60:61], v[106:107] op_sel_hi:[1,0]
	v_pk_mul_f32 v[70:71], v[66:67], v[106:107] op_sel_hi:[1,0]
	v_pk_mul_f32 v[68:69], v[64:65], v[106:107] op_sel_hi:[1,0]
	v_cvt_pk_bf16_f32 v72, v139, v137
	v_cvt_pk_bf16_f32 v73, v135, v133
	v_cvt_pk_bf16_f32 v74, v131, v129
	v_cvt_pk_bf16_f32 v75, v127, v125
	v_cvt_pk_bf16_f32 v64, v123, v121
	v_cvt_pk_bf16_f32 v65, v119, v115
	v_cvt_pk_bf16_f32 v66, v111, v109
	v_cvt_pk_bf16_f32 v67, v117, v113
	v_pk_mul_f32 v[42:43], v[42:43], v[76:77] op_sel_hi:[1,0]
	v_pk_mul_f32 v[40:41], v[40:41], v[76:77] op_sel_hi:[1,0]
	v_pk_mul_f32 v[38:39], v[38:39], v[76:77] op_sel_hi:[1,0]
	v_pk_mul_f32 v[36:37], v[36:37], v[76:77] op_sel_hi:[1,0]
	v_pk_mul_f32 v[46:47], v[46:47], v[76:77] op_sel_hi:[1,0]
	v_pk_mul_f32 v[44:45], v[44:45], v[76:77] op_sel_hi:[1,0]
	v_pk_mul_f32 v[50:51], v[50:51], v[76:77] op_sel_hi:[1,0]
	v_pk_mul_f32 v[48:49], v[48:49], v[76:77] op_sel_hi:[1,0]
	v_cvt_pk_bf16_f32 v80, v138, v136
	v_cvt_pk_bf16_f32 v81, v134, v132
	v_cvt_pk_bf16_f32 v82, v130, v128
	v_cvt_pk_bf16_f32 v83, v126, v124
	v_cvt_pk_bf16_f32 v84, v122, v120
	v_cvt_pk_bf16_f32 v85, v118, v114
	v_cvt_pk_bf16_f32 v86, v110, v108
	v_cvt_pk_bf16_f32 v87, v116, v112
	s_setprio 1
	v_add3_u32 v77, s78, v164, v165
	ds_read_b64_tr_b16 v[206:207], v77 offset:20992
	ds_read_b64_tr_b16 v[204:205], v77 offset:18432
	ds_read_b64_tr_b16 v[208:209], v77 offset:18464
	ds_read_b64_tr_b16 v[210:211], v77 offset:21024
	ds_read_b64_tr_b16 v[212:213], v77 offset:23552
	ds_read_b64_tr_b16 v[214:215], v77 offset:26112
	ds_read_b64_tr_b16 v[216:217], v77 offset:23584
	ds_read_b64_tr_b16 v[218:219], v77 offset:26144
	ds_read_b64_tr_b16 v[220:221], v77 offset:18496
	ds_read_b64_tr_b16 v[222:223], v77 offset:21056
	ds_read_b64_tr_b16 v[224:225], v77 offset:23616
	ds_read_b64_tr_b16 v[226:227], v77 offset:26176
	ds_read_b64_tr_b16 v[228:229], v77 offset:18528
	ds_read_b64_tr_b16 v[230:231], v77 offset:21088
	ds_read_b64_tr_b16 v[232:233], v77 offset:23648
	ds_read_b64_tr_b16 v[234:235], v77 offset:26208
	s_waitcnt lgkmcnt(14)
	v_mfma_f32_16x16x32_bf16 v[56:59], v[204:207], v[72:75], v[56:59]
	v_mfma_f32_16x16x32_bf16 v[40:43], v[204:207], v[80:83], v[40:43]
	s_waitcnt lgkmcnt(10)
	v_mfma_f32_16x16x32_bf16 v[56:59], v[212:215], v[64:67], v[56:59]
	v_mfma_f32_16x16x32_bf16 v[40:43], v[212:215], v[84:87], v[40:43]
	v_mfma_f32_16x16x32_bf16 v[52:55], v[208:211], v[72:75], v[52:55]
	v_mfma_f32_16x16x32_bf16 v[36:39], v[208:211], v[80:83], v[36:39]
	s_waitcnt lgkmcnt(8)
	v_mfma_f32_16x16x32_bf16 v[52:55], v[216:219], v[64:67], v[52:55]
	v_mfma_f32_16x16x32_bf16 v[36:39], v[216:219], v[84:87], v[36:39]
	s_waitcnt lgkmcnt(6)
	v_mfma_f32_16x16x32_bf16 v[60:63], v[220:223], v[72:75], v[60:63]
	v_mfma_f32_16x16x32_bf16 v[44:47], v[220:223], v[80:83], v[44:47]
	s_waitcnt lgkmcnt(4)
	v_mfma_f32_16x16x32_bf16 v[60:63], v[224:227], v[64:67], v[60:63]
	v_mfma_f32_16x16x32_bf16 v[44:47], v[224:227], v[84:87], v[44:47]
	s_waitcnt lgkmcnt(2)
	v_mfma_f32_16x16x32_bf16 v[68:71], v[228:231], v[72:75], v[68:71]
	v_mfma_f32_16x16x32_bf16 v[48:51], v[228:231], v[80:83], v[48:51]
	s_waitcnt lgkmcnt(0)
	v_mfma_f32_16x16x32_bf16 v[64:67], v[232:235], v[64:67], v[68:71]
	v_mfma_f32_16x16x32_bf16 v[48:51], v[232:235], v[84:87], v[48:51]
	s_nop 3
	s_setprio 0
	s_setprio 1
	ds_read_b128 v[204:207], v88 offset:9216
	ds_read_b128 v[208:211], v88 offset:9280
	ds_read_b128 v[212:215], v88 offset:11520
	ds_read_b128 v[216:219], v88 offset:13824
	ds_read_b128 v[220:223], v88 offset:16128
	ds_read_b128 v[224:227], v88 offset:11584
	ds_read_b128 v[228:231], v88 offset:13888
	ds_read_b128 v[232:235], v88 offset:16192
	s_waitcnt lgkmcnt(7)
	v_mfma_f32_16x16x32_bf16 v[72:75], v[204:207], v[4:7], v[0:3]
	v_mfma_f32_16x16x32_bf16 v[68:71], v[204:207], v[12:15], v[0:3]
	s_waitcnt lgkmcnt(6)
	v_mfma_f32_16x16x32_bf16 v[168:171], v[208:211], v[16:19], v[68:71]
	v_mfma_f32_16x16x32_bf16 v[72:75], v[208:211], v[8:11], v[72:75]
	s_waitcnt lgkmcnt(5)
	v_mfma_f32_16x16x32_bf16 v[84:87], v[212:215], v[4:7], v[0:3]
	v_mfma_f32_16x16x32_bf16 v[80:83], v[212:215], v[12:15], v[0:3]
	s_waitcnt lgkmcnt(2)
	v_mfma_f32_16x16x32_bf16 v[84:87], v[224:227], v[8:11], v[84:87]
	v_mfma_f32_16x16x32_bf16 v[186:189], v[224:227], v[16:19], v[80:83]
	v_mfma_f32_16x16x32_bf16 v[146:149], v[216:219], v[4:7], v[0:3]
	v_mfma_f32_16x16x32_bf16 v[142:145], v[216:219], v[12:15], v[0:3]
	s_waitcnt lgkmcnt(1)
	v_mfma_f32_16x16x32_bf16 v[80:83], v[228:231], v[8:11], v[146:149]
	v_mfma_f32_16x16x32_bf16 v[190:193], v[228:231], v[16:19], v[142:145]
	v_mfma_f32_16x16x32_bf16 v[154:157], v[220:223], v[4:7], v[0:3]
	v_mfma_f32_16x16x32_bf16 v[150:153], v[220:223], v[12:15], v[0:3]
	s_waitcnt lgkmcnt(0)
	v_mfma_f32_16x16x32_bf16 v[142:145], v[232:235], v[8:11], v[154:157]
	v_mfma_f32_16x16x32_bf16 v[194:197], v[232:235], v[16:19], v[150:153]
	s_nop 0
	s_setprio 0
	v_mul_f32_e32 v68, 0x3e38aa3b, v72
	v_mul_f32_e32 v71, 0x3e38aa3b, v74
	v_mul_f32_e32 v69, 0x3e38aa3b, v73
	v_mul_f32_e32 v72, 0x3e38aa3b, v75
	v_mul_f32_e32 v73, 0x3e38aa3b, v84
	v_mov_b32_e32 v74, v73
	v_mul_f32_e32 v73, 0x3e38aa3b, v85
	v_mov_b32_e32 v75, v73
	v_mul_f32_e32 v73, 0x3e38aa3b, v86
	v_mov_b32_e32 v79, v73
	v_mul_f32_e32 v73, 0x3e38aa3b, v87
	v_mov_b32_e32 v84, v73
	v_mul_f32_e32 v73, 0x3e38aa3b, v80
	v_mov_b32_e32 v80, v73
	v_mul_f32_e32 v73, 0x3e38aa3b, v81
	v_mov_b32_e32 v81, v73
	v_mul_f32_e32 v73, 0x3e38aa3b, v82
	v_mov_b32_e32 v82, v73
	v_mul_f32_e32 v73, 0x3e38aa3b, v83
	v_mov_b32_e32 v83, v73
	v_mul_f32_e32 v73, 0x3e38aa3b, v142
	v_max3_f32 v70, v68, s71, v69
	v_mov_b32_e32 v85, v73
	v_max3_f32 v70, v70, v71, v72
	v_mul_f32_e32 v73, 0x3e38aa3b, v143
	v_max3_f32 v70, v70, v74, v75
	v_mov_b32_e32 v86, v73
	v_max3_f32 v70, v70, v79, v84
	v_mul_f32_e32 v73, 0x3e38aa3b, v144
	v_max3_f32 v70, v70, v80, v81
	v_mov_b32_e32 v88, v73
	v_max3_f32 v70, v70, v82, v83
	v_mul_f32_e32 v73, 0x3e38aa3b, v145
	v_max3_f32 v70, v70, v85, v86
	v_mov_b32_e32 v142, v73
	v_max3_f32 v70, v70, v88, v142
	v_mov_b32_e32 v73, v70
	s_nop 1
	v_permlane16_swap_b32_e32 v70, v73
	v_max_f32_e32 v70, v70, v73
	v_mov_b32_e32 v73, v70
	s_nop 1
	v_permlane32_swap_b32_e32 v70, v73
	v_max3_f32 v73, v140, v70, v73
	v_sub_f32_e32 v68, v68, v73
	v_exp_f32_e32 v159, v68
	v_sub_f32_e32 v68, v69, v73
	v_exp_f32_e32 v157, v68
	v_sub_f32_e32 v68, v71, v73
	v_exp_f32_e32 v155, v68
	v_sub_f32_e32 v68, v72, v73
	v_exp_f32_e32 v153, v68
	v_sub_f32_e32 v68, v74, v73
	v_exp_f32_e32 v151, v68
	v_sub_f32_e32 v68, v75, v73
	v_exp_f32_e32 v149, v68
	v_sub_f32_e32 v68, v79, v73
	v_exp_f32_e32 v147, v68
	v_sub_f32_e32 v68, v84, v73
	v_exp_f32_e32 v145, v68
	v_sub_f32_e32 v68, v80, v73
	v_exp_f32_e32 v143, v68
	v_sub_f32_e32 v68, v81, v73
	v_exp_f32_e32 v141, v68
	v_sub_f32_e32 v68, v82, v73
	v_sub_f32_e32 v70, v140, v73
	v_exp_f32_e32 v87, v68
	v_sub_f32_e32 v68, v83, v73
	v_exp_f32_e32 v83, v68
	v_sub_f32_e32 v68, v85, v73
	v_exp_f32_e32 v72, v70
	v_exp_f32_e32 v79, v68
	v_sub_f32_e32 v68, v86, v73
	v_exp_f32_e32 v75, v68
	v_sub_f32_e32 v68, v88, v73
	v_exp_f32_e32 v85, v68
	v_sub_f32_e32 v68, v142, v73
	v_exp_f32_e32 v81, v68
	v_pk_mul_f32 v[68:69], v[64:65], v[72:73] op_sel_hi:[1,0]
	v_mul_f32_e32 v64, 0x3e38aa3b, v168
	v_mov_b32_e32 v74, v64
	v_mul_f32_e32 v64, 0x3e38aa3b, v169
	v_mov_b32_e32 v80, v64
	v_mul_f32_e32 v64, 0x3e38aa3b, v170
	v_mov_b32_e32 v82, v64
	v_mul_f32_e32 v64, 0x3e38aa3b, v171
	v_mov_b32_e32 v84, v64
	v_mul_f32_e32 v64, 0x3e38aa3b, v186
	v_mov_b32_e32 v86, v64
	v_mul_f32_e32 v64, 0x3e38aa3b, v187
	v_mov_b32_e32 v88, v64
	v_mul_f32_e32 v64, 0x3e38aa3b, v188
	v_mov_b32_e32 v140, v64
	v_mul_f32_e32 v64, 0x3e38aa3b, v189
	v_mov_b32_e32 v142, v64
	v_mul_f32_e32 v64, 0x3e38aa3b, v190
	v_mov_b32_e32 v160, v64
	v_mul_f32_e32 v64, 0x3e38aa3b, v191
	v_mov_b32_e32 v161, v64
	v_mul_f32_e32 v64, 0x3e38aa3b, v192
	v_mov_b32_e32 v172, v64
	v_mul_f32_e32 v64, 0x3e38aa3b, v193
	v_mov_b32_e32 v173, v64
	v_mul_f32_e32 v64, 0x3e38aa3b, v194
	v_mov_b32_e32 v185, v64
	v_mul_f32_e32 v64, 0x3e38aa3b, v195
	v_mov_b32_e32 v186, v64
	v_mul_f32_e32 v64, 0x3e38aa3b, v196
	v_mov_b32_e32 v187, v64
	v_mul_f32_e32 v64, 0x3e38aa3b, v197
	v_mov_b32_e32 v188, v64
	v_max3_f32 v64, v74, s71, v80
	v_max3_f32 v64, v64, v82, v84
	v_max3_f32 v64, v64, v86, v88
	v_max3_f32 v64, v64, v140, v142
	v_max3_f32 v64, v64, v160, v161
	v_max3_f32 v64, v64, v172, v173
	v_max3_f32 v144, v64, v185, v186
	v_max3_f32 v144, v144, v187, v188
	v_mov_b32_e32 v146, v144
	s_nop 1
	v_permlane16_swap_b32_e32 v144, v146
	v_max_f32_e32 v144, v144, v146
	v_mov_b32_e32 v146, v144
	s_nop 1
	v_permlane32_swap_b32_e32 v144, v146
	v_max3_f32 v167, v78, v144, v146
	v_sub_f32_e32 v74, v74, v167
	v_exp_f32_e32 v158, v74
	v_sub_f32_e32 v74, v80, v167
	v_exp_f32_e32 v156, v74
	v_sub_f32_e32 v74, v82, v167
	v_exp_f32_e32 v154, v74
	v_sub_f32_e32 v74, v84, v167
	v_exp_f32_e32 v152, v74
	v_sub_f32_e32 v74, v86, v167
	v_exp_f32_e32 v150, v74
	v_sub_f32_e32 v74, v88, v167
	v_exp_f32_e32 v148, v74
	v_sub_f32_e32 v74, v140, v167
	v_exp_f32_e32 v146, v74
	v_sub_f32_e32 v74, v142, v167
	v_exp_f32_e32 v144, v74
	v_sub_f32_e32 v74, v160, v167
	v_exp_f32_e32 v142, v74
	v_sub_f32_e32 v74, v161, v167
	v_exp_f32_e32 v140, v74
	v_sub_f32_e32 v74, v172, v167
	v_exp_f32_e32 v86, v74
	v_sub_f32_e32 v74, v173, v167
	v_sub_f32_e32 v189, v78, v167
	v_exp_f32_e32 v82, v74
	v_sub_f32_e32 v74, v185, v167
	v_sub_f32_e32 v80, v187, v167
	v_exp_f32_e32 v78, v74
	v_sub_f32_e32 v74, v186, v167
	v_exp_f32_e32 v160, v189
	v_exp_f32_e32 v84, v80
	v_sub_f32_e32 v80, v188, v167
	v_exp_f32_e32 v74, v74
	v_exp_f32_e32 v80, v80
	v_pk_mul_f32 v[58:59], v[58:59], v[72:73] op_sel_hi:[1,0]
	v_pk_mul_f32 v[56:57], v[56:57], v[72:73] op_sel_hi:[1,0]
	v_pk_mul_f32 v[54:55], v[54:55], v[72:73] op_sel_hi:[1,0]
	v_pk_mul_f32 v[52:53], v[52:53], v[72:73] op_sel_hi:[1,0]
	v_pk_mul_f32 v[62:63], v[62:63], v[72:73] op_sel_hi:[1,0]
	v_pk_mul_f32 v[60:61], v[60:61], v[72:73] op_sel_hi:[1,0]
	v_pk_mul_f32 v[70:71], v[66:67], v[72:73] op_sel_hi:[1,0]
	v_cvt_pk_bf16_f32 v64, v143, v141
	v_cvt_pk_bf16_f32 v65, v87, v83
	v_cvt_pk_bf16_f32 v66, v79, v75
	v_cvt_pk_bf16_f32 v67, v85, v81
	v_pk_mul_f32 v[42:43], v[42:43], v[160:161] op_sel_hi:[1,0]
	v_pk_mul_f32 v[40:41], v[40:41], v[160:161] op_sel_hi:[1,0]
	v_pk_mul_f32 v[38:39], v[38:39], v[160:161] op_sel_hi:[1,0]
	v_pk_mul_f32 v[36:37], v[36:37], v[160:161] op_sel_hi:[1,0]
	v_pk_mul_f32 v[46:47], v[46:47], v[160:161] op_sel_hi:[1,0]
	v_pk_mul_f32 v[44:45], v[44:45], v[160:161] op_sel_hi:[1,0]
	v_pk_mul_f32 v[50:51], v[50:51], v[160:161] op_sel_hi:[1,0]
	v_pk_mul_f32 v[48:49], v[48:49], v[160:161] op_sel_hi:[1,0]
	v_cvt_pk_bf16_f32 v168, v159, v157
	v_cvt_pk_bf16_f32 v169, v155, v153
	v_cvt_pk_bf16_f32 v170, v151, v149
	v_cvt_pk_bf16_f32 v171, v147, v145
	v_cvt_pk_bf16_f32 v186, v158, v156
	v_cvt_pk_bf16_f32 v187, v154, v152
	v_cvt_pk_bf16_f32 v188, v150, v148
	v_cvt_pk_bf16_f32 v189, v146, v144
	v_cvt_pk_bf16_f32 v190, v142, v140
	v_cvt_pk_bf16_f32 v191, v86, v82
	v_cvt_pk_bf16_f32 v192, v78, v74
	v_cvt_pk_bf16_f32 v193, v84, v80
	s_setprio 1
	ds_read_b64_tr_b16 v[206:207], v77 offset:31232
	ds_read_b64_tr_b16 v[204:205], v77 offset:28672
	ds_read_b64_tr_b16 v[208:209], v77 offset:28704
	ds_read_b64_tr_b16 v[210:211], v77 offset:31264
	ds_read_b64_tr_b16 v[212:213], v77 offset:33792
	ds_read_b64_tr_b16 v[214:215], v77 offset:36352
	ds_read_b64_tr_b16 v[216:217], v77 offset:33824
	ds_read_b64_tr_b16 v[218:219], v77 offset:36384
	ds_read_b64_tr_b16 v[220:221], v77 offset:28736
	ds_read_b64_tr_b16 v[222:223], v77 offset:31296
	ds_read_b64_tr_b16 v[224:225], v77 offset:33856
	ds_read_b64_tr_b16 v[226:227], v77 offset:36416
	ds_read_b64_tr_b16 v[228:229], v77 offset:28768
	ds_read_b64_tr_b16 v[230:231], v77 offset:31328
	ds_read_b64_tr_b16 v[232:233], v77 offset:33888
	ds_read_b64_tr_b16 v[234:235], v77 offset:36448
	s_waitcnt lgkmcnt(14)
	v_mfma_f32_16x16x32_bf16 v[56:59], v[204:207], v[168:171], v[56:59]
	v_mfma_f32_16x16x32_bf16 v[40:43], v[204:207], v[186:189], v[40:43]
	s_waitcnt lgkmcnt(10)
	v_mfma_f32_16x16x32_bf16 v[56:59], v[212:215], v[64:67], v[56:59]
	v_mfma_f32_16x16x32_bf16 v[40:43], v[212:215], v[190:193], v[40:43]
	v_mfma_f32_16x16x32_bf16 v[52:55], v[208:211], v[168:171], v[52:55]
	v_mfma_f32_16x16x32_bf16 v[36:39], v[208:211], v[186:189], v[36:39]
	s_waitcnt lgkmcnt(8)
	v_mfma_f32_16x16x32_bf16 v[52:55], v[216:219], v[64:67], v[52:55]
	v_mfma_f32_16x16x32_bf16 v[36:39], v[216:219], v[190:193], v[36:39]
	s_waitcnt lgkmcnt(6)
	v_mfma_f32_16x16x32_bf16 v[60:63], v[220:223], v[168:171], v[60:63]
	v_mfma_f32_16x16x32_bf16 v[44:47], v[220:223], v[186:189], v[44:47]
	s_waitcnt lgkmcnt(4)
	v_mfma_f32_16x16x32_bf16 v[60:63], v[224:227], v[64:67], v[60:63]
	v_mfma_f32_16x16x32_bf16 v[44:47], v[224:227], v[190:193], v[44:47]
	s_waitcnt lgkmcnt(2)
	v_mfma_f32_16x16x32_bf16 v[68:71], v[228:231], v[168:171], v[68:71]
	v_mfma_f32_16x16x32_bf16 v[48:51], v[228:231], v[186:189], v[48:51]
	s_waitcnt lgkmcnt(0)
	v_mfma_f32_16x16x32_bf16 v[64:67], v[232:235], v[64:67], v[68:71]
	v_mfma_f32_16x16x32_bf16 v[48:51], v[232:235], v[190:193], v[48:51]
	s_nop 3
	s_setprio 0
	s_add_i32 s12, s33, 1
	s_cmp_ge_i32 s12, s44
	s_cbranch_scc1 .Lnm0_b1303
	s_bitcmp1_b32 s12, 0
	s_cselect_b32 s6, 0x9800, 0
	v_add3_u32 v71, s6, v99, v98
	v_add3_u32 v68, s6, v162, v98
	v_add3_u32 v69, s6, v107, v98
	v_add3_u32 v70, s6, v103, v98
	s_waitcnt vmcnt(0)
	ds_write_b128 v71, v[20:23]
	ds_write_b128 v70, v[24:27]
	ds_write_b128 v69, v[28:31] offset:18432
	ds_write_b128 v68, v[32:35] offset:18432

.Lnm0_b1308:
	v_pk_add_f32 v[68:69], v[138:139], 0 op_sel_hi:[1,0]
	v_pk_add_f32 v[70:71], v[158:159], 0 op_sel_hi:[1,0]
	v_pk_add_f32 v[68:69], v[136:137], v[68:69]
	v_pk_add_f32 v[70:71], v[156:157], v[70:71]
	v_pk_add_f32 v[68:69], v[134:135], v[68:69]
	v_pk_add_f32 v[70:71], v[154:155], v[70:71]
	v_pk_add_f32 v[68:69], v[132:133], v[68:69]
	v_pk_add_f32 v[70:71], v[152:153], v[70:71]
	v_pk_add_f32 v[68:69], v[130:131], v[68:69]
	v_pk_add_f32 v[70:71], v[150:151], v[70:71]
	v_pk_add_f32 v[68:69], v[128:129], v[68:69]
	v_pk_add_f32 v[70:71], v[148:149], v[70:71]
	v_pk_add_f32 v[68:69], v[126:127], v[68:69]
	v_pk_add_f32 v[70:71], v[146:147], v[70:71]
	v_pk_add_f32 v[68:69], v[124:125], v[68:69]
	v_pk_add_f32 v[70:71], v[144:145], v[70:71]
	v_pk_add_f32 v[68:69], v[122:123], v[68:69]
	v_pk_add_f32 v[70:71], v[142:143], v[70:71]
	v_pk_add_f32 v[68:69], v[120:121], v[68:69]
	v_pk_add_f32 v[70:71], v[140:141], v[70:71]
	v_pk_add_f32 v[68:69], v[118:119], v[68:69]
	v_pk_add_f32 v[70:71], v[86:87], v[70:71]
	v_pk_add_f32 v[68:69], v[114:115], v[68:69]
	v_pk_add_f32 v[70:71], v[82:83], v[70:71]
	v_pk_add_f32 v[68:69], v[110:111], v[68:69]
	v_pk_add_f32 v[70:71], v[78:79], v[70:71]
	v_pk_add_f32 v[68:69], v[108:109], v[68:69]
	v_pk_add_f32 v[70:71], v[74:75], v[70:71]
	v_pk_add_f32 v[68:69], v[116:117], v[68:69]
	s_addk_i32 s97, 0x80
	v_pk_add_f32 v[68:69], v[112:113], v[68:69]
	v_mov_b32_e32 v77, v106
	v_pk_add_f32 v[70:71], v[84:85], v[70:71]
	s_add_u32 s74, s74, 0x80
	v_pk_fma_f32 v[68:69], v[96:97], v[76:77], v[68:69]
	v_pk_add_f32 v[70:71], v[80:81], v[70:71]
	v_mov_b32_e32 v161, v72
	s_addc_u32 s75, s75, 0
	v_pk_fma_f32 v[96:97], v[68:69], v[160:161], v[70:71]
	s_cmp_lg_u32 s44, s12
	s_waitcnt lgkmcnt(0)
	s_barrier
	s_cbranch_scc0 .LBB0_1311
	s_mov_b32 s33, s12
	s_branch .LBB0_1301

.LBB0_1749:
	v_lshl_add_u32 v146, s44, 8, v151
	v_ashrrev_i32_e32 v147, 31, v146
	v_lshl_or_b32 v144, s42, 8, v153
	v_lshlrev_b64 v[148:149], 13, v[146:147]
	v_ashrrev_i32_e32 v145, 31, v144
	v_lshl_add_u64 v[148:149], s[14:15], 0, v[148:149]
	v_lshl_add_u64 v[148:149], v[144:145], 1, v[148:149]
	v_cmp_gt_i32_e32 vcc, s81, v144
	s_and_saveexec_b64 s[10:11], vcc
	s_cbranch_execz .LBB0_1751
	v_max_f32_e32 v124, 0, v124
	v_max_f32_e32 v125, 0, v125
	v_max_f32_e32 v126, 0, v126
	v_max_f32_e32 v127, 0, v127
	v_max_f32_e32 v120, 0, v120
	v_max_f32_e32 v121, 0, v121
	v_max_f32_e32 v122, 0, v122
	v_max_f32_e32 v123, 0, v123
	v_pk_mul_f32 v[124:125], v[124:125], v[124:125]
	v_pk_mul_f32 v[126:127], v[126:127], v[126:127]
	v_pk_mul_f32 v[120:121], v[120:121], v[120:121]
	v_pk_mul_f32 v[122:123], v[122:123], v[122:123]
	v_cvt_pk_bf16_f32 v120, v120, v121
	v_cvt_pk_bf16_f32 v121, v122, v123
	v_cvt_pk_bf16_f32 v122, v124, v125
	v_cvt_pk_bf16_f32 v123, v126, v127
	flat_store_dwordx4 v[148:149], v[120:123]
.LBB0_1751:
	s_or_b64 exec, exec, s[10:11]
	s_nop 0
	v_or_b32_e32 v120, 0x80, v144
	v_cmp_gt_i32_e64 s[10:11], s81, v120
	s_and_saveexec_b64 s[42:43], s[10:11]
	s_load_dwordx2 s[84:85], s[90:91], 0x120
	s_cbranch_execz .LBB0_1753
	v_max_f32_e32 v116, 0, v116
	v_max_f32_e32 v117, 0, v117
	v_max_f32_e32 v118, 0, v118
	v_max_f32_e32 v119, 0, v119
	v_max_f32_e32 v112, 0, v112
	v_max_f32_e32 v113, 0, v113
	v_max_f32_e32 v114, 0, v114
	v_max_f32_e32 v115, 0, v115
	v_pk_mul_f32 v[116:117], v[116:117], v[116:117]
	v_pk_mul_f32 v[118:119], v[118:119], v[118:119]
	v_pk_mul_f32 v[112:113], v[112:113], v[112:113]
	v_pk_mul_f32 v[114:115], v[114:115], v[114:115]
	v_cvt_pk_bf16_f32 v112, v112, v113
	v_cvt_pk_bf16_f32 v113, v114, v115
	v_cvt_pk_bf16_f32 v114, v116, v117
	v_cvt_pk_bf16_f32 v115, v118, v119
	flat_store_dwordx4 v[148:149], v[112:115] offset:256
.LBB0_1753:
	s_or_b64 exec, exec, s[42:43]
	s_nop 0
	v_or_b32_e32 v112, 16, v146
	v_ashrrev_i32_e32 v113, 31, v112
	v_lshlrev_b64 v[112:113], 13, v[112:113]
	v_lshl_add_u64 v[112:113], s[14:15], 0, v[112:113]
	v_lshl_add_u64 v[112:113], v[144:145], 1, v[112:113]
	s_and_saveexec_b64 s[42:43], vcc
	s_cbranch_execz .LBB0_1755
	v_max_f32_e32 v108, 0, v108
	v_max_f32_e32 v109, 0, v109
	v_max_f32_e32 v110, 0, v110
	v_max_f32_e32 v111, 0, v111
	v_max_f32_e32 v104, 0, v104
	v_max_f32_e32 v105, 0, v105
	v_max_f32_e32 v106, 0, v106
	v_max_f32_e32 v107, 0, v107
	v_pk_mul_f32 v[108:109], v[108:109], v[108:109]
	v_pk_mul_f32 v[110:111], v[110:111], v[110:111]
	v_pk_mul_f32 v[104:105], v[104:105], v[104:105]
	v_pk_mul_f32 v[106:107], v[106:107], v[106:107]
	v_cvt_pk_bf16_f32 v104, v104, v105
	v_cvt_pk_bf16_f32 v105, v106, v107
	v_cvt_pk_bf16_f32 v106, v108, v109
	v_cvt_pk_bf16_f32 v107, v110, v111
	flat_store_dwordx4 v[112:113], v[104:107]
.LBB0_1755:
	s_or_b64 exec, exec, s[42:43]
	s_and_saveexec_b64 s[42:43], s[10:11]
	s_cbranch_execz .LBB0_1757
	v_max_f32_e32 v100, 0, v100
	v_max_f32_e32 v101, 0, v101
	v_max_f32_e32 v102, 0, v102
	v_max_f32_e32 v103, 0, v103
	v_max_f32_e32 v96, 0, v96
	v_max_f32_e32 v97, 0, v97
	v_max_f32_e32 v98, 0, v98
	v_max_f32_e32 v99, 0, v99
	v_pk_mul_f32 v[100:101], v[100:101], v[100:101]
	v_pk_mul_f32 v[102:103], v[102:103], v[102:103]
	v_pk_mul_f32 v[96:97], v[96:97], v[96:97]
	v_pk_mul_f32 v[98:99], v[98:99], v[98:99]
	v_cvt_pk_bf16_f32 v96, v96, v97
	v_cvt_pk_bf16_f32 v97, v98, v99
	v_cvt_pk_bf16_f32 v98, v100, v101
	v_cvt_pk_bf16_f32 v99, v102, v103
	flat_store_dwordx4 v[112:113], v[96:99] offset:256
.LBB0_1757:
	s_or_b64 exec, exec, s[42:43]
	s_nop 0
	v_or_b32_e32 v96, 32, v146
	v_ashrrev_i32_e32 v97, 31, v96
	v_lshlrev_b64 v[96:97], 13, v[96:97]
	v_lshl_add_u64 v[96:97], s[14:15], 0, v[96:97]
	v_lshl_add_u64 v[96:97], v[144:145], 1, v[96:97]
	s_and_saveexec_b64 s[42:43], vcc
	s_cbranch_execz .LBB0_1759
	v_max_f32_e32 v92, 0, v92
	v_max_f32_e32 v93, 0, v93
	v_max_f32_e32 v94, 0, v94
	v_max_f32_e32 v95, 0, v95
	v_max_f32_e32 v88, 0, v88
	v_max_f32_e32 v89, 0, v89
	v_max_f32_e32 v90, 0, v90
	v_max_f32_e32 v91, 0, v91
	v_pk_mul_f32 v[92:93], v[92:93], v[92:93]
	v_pk_mul_f32 v[94:95], v[94:95], v[94:95]
	v_pk_mul_f32 v[88:89], v[88:89], v[88:89]
	v_pk_mul_f32 v[90:91], v[90:91], v[90:91]
	v_cvt_pk_bf16_f32 v88, v88, v89
	v_cvt_pk_bf16_f32 v89, v90, v91
	v_cvt_pk_bf16_f32 v90, v92, v93
	v_cvt_pk_bf16_f32 v91, v94, v95
	flat_store_dwordx4 v[96:97], v[88:91]
.LBB0_1759:
	s_or_b64 exec, exec, s[42:43]
	s_and_saveexec_b64 s[42:43], s[10:11]
	s_cbranch_execz .LBB0_1761
	v_max_f32_e32 v84, 0, v84
	v_max_f32_e32 v85, 0, v85
	v_max_f32_e32 v86, 0, v86
	v_max_f32_e32 v87, 0, v87
	v_max_f32_e32 v80, 0, v80
	v_max_f32_e32 v81, 0, v81
	v_max_f32_e32 v82, 0, v82
	v_max_f32_e32 v83, 0, v83
	v_pk_mul_f32 v[84:85], v[84:85], v[84:85]
	v_pk_mul_f32 v[86:87], v[86:87], v[86:87]
	v_pk_mul_f32 v[80:81], v[80:81], v[80:81]
	v_pk_mul_f32 v[82:83], v[82:83], v[82:83]
	v_cvt_pk_bf16_f32 v80, v80, v81
	v_cvt_pk_bf16_f32 v81, v82, v83
	v_cvt_pk_bf16_f32 v82, v84, v85
	v_cvt_pk_bf16_f32 v83, v86, v87
	flat_store_dwordx4 v[96:97], v[80:83] offset:256
.LBB0_1761:
	s_or_b64 exec, exec, s[42:43]
	s_nop 0
	v_or_b32_e32 v80, 48, v146
	v_ashrrev_i32_e32 v81, 31, v80
	v_lshlrev_b64 v[80:81], 13, v[80:81]
	v_lshl_add_u64 v[80:81], s[14:15], 0, v[80:81]
	v_lshl_add_u64 v[80:81], v[144:145], 1, v[80:81]
	s_and_saveexec_b64 s[42:43], vcc
	s_cbranch_execz .LBB0_1763
	v_max_f32_e32 v76, 0, v76
	v_max_f32_e32 v77, 0, v77
	v_max_f32_e32 v78, 0, v78
	v_max_f32_e32 v79, 0, v79
	v_max_f32_e32 v72, 0, v72
	v_max_f32_e32 v73, 0, v73
	v_max_f32_e32 v74, 0, v74
	v_max_f32_e32 v75, 0, v75
	v_pk_mul_f32 v[76:77], v[76:77], v[76:77]
	v_pk_mul_f32 v[78:79], v[78:79], v[78:79]
	v_pk_mul_f32 v[72:73], v[72:73], v[72:73]
	v_pk_mul_f32 v[74:75], v[74:75], v[74:75]
	v_cvt_pk_bf16_f32 v72, v72, v73
	v_cvt_pk_bf16_f32 v73, v74, v75
	v_cvt_pk_bf16_f32 v74, v76, v77
	v_cvt_pk_bf16_f32 v75, v78, v79
	flat_store_dwordx4 v[80:81], v[72:75]
.LBB0_1763:
	s_or_b64 exec, exec, s[42:43]
	s_and_saveexec_b64 s[42:43], s[10:11]
	s_cbranch_execz .LBB0_1765
	v_max_f32_e32 v68, 0, v68
	v_max_f32_e32 v69, 0, v69
	v_max_f32_e32 v70, 0, v70
	v_max_f32_e32 v71, 0, v71
	v_max_f32_e32 v64, 0, v64
	v_max_f32_e32 v65, 0, v65
	v_max_f32_e32 v66, 0, v66
	v_max_f32_e32 v67, 0, v67
	v_pk_mul_f32 v[68:69], v[68:69], v[68:69]
	v_pk_mul_f32 v[70:71], v[70:71], v[70:71]
	v_pk_mul_f32 v[64:65], v[64:65], v[64:65]
	v_pk_mul_f32 v[66:67], v[66:67], v[66:67]
	v_cvt_pk_bf16_f32 v64, v64, v65
	v_cvt_pk_bf16_f32 v65, v66, v67
	v_cvt_pk_bf16_f32 v66, v68, v69
	v_cvt_pk_bf16_f32 v67, v70, v71
	flat_store_dwordx4 v[80:81], v[64:67] offset:256
.LBB0_1765:
	s_or_b64 exec, exec, s[42:43]
	s_nop 0
	v_lshlrev_b64 v[64:65], 13, v[146:147]
	v_lshl_add_u64 v[64:65], s[14:15], 0, v[64:65]
	v_lshl_add_u64 v[64:65], v[144:145], 1, v[64:65]
	v_lshl_add_u64 v[64:65], v[64:65], 0, s[22:23]
	s_and_saveexec_b64 s[42:43], vcc
	s_cbranch_execz .LBB0_1767
	v_max_f32_e32 v60, 0, v60
	v_max_f32_e32 v61, 0, v61
	v_max_f32_e32 v62, 0, v62
	v_max_f32_e32 v63, 0, v63
	v_max_f32_e32 v56, 0, v56
	v_max_f32_e32 v57, 0, v57
	v_max_f32_e32 v58, 0, v58
	v_max_f32_e32 v59, 0, v59
	v_pk_mul_f32 v[60:61], v[60:61], v[60:61]
	v_pk_mul_f32 v[62:63], v[62:63], v[62:63]
	v_pk_mul_f32 v[56:57], v[56:57], v[56:57]
	v_pk_mul_f32 v[58:59], v[58:59], v[58:59]
	v_cvt_pk_bf16_f32 v56, v56, v57
	v_cvt_pk_bf16_f32 v57, v58, v59
	v_cvt_pk_bf16_f32 v58, v60, v61
	v_cvt_pk_bf16_f32 v59, v62, v63
	flat_store_dwordx4 v[64:65], v[56:59]
.LBB0_1767:
	s_or_b64 exec, exec, s[42:43]
	s_and_saveexec_b64 s[42:43], s[10:11]
	s_cbranch_execz .LBB0_1769
	v_max_f32_e32 v52, 0, v52
	v_max_f32_e32 v53, 0, v53
	v_max_f32_e32 v54, 0, v54
	v_max_f32_e32 v55, 0, v55
	v_max_f32_e32 v48, 0, v48
	v_max_f32_e32 v49, 0, v49
	v_max_f32_e32 v50, 0, v50
	v_max_f32_e32 v51, 0, v51
	v_pk_mul_f32 v[52:53], v[52:53], v[52:53]
	v_pk_mul_f32 v[54:55], v[54:55], v[54:55]
	v_pk_mul_f32 v[48:49], v[48:49], v[48:49]
	v_pk_mul_f32 v[50:51], v[50:51], v[50:51]
	v_cvt_pk_bf16_f32 v48, v48, v49
	v_cvt_pk_bf16_f32 v49, v50, v51
	v_cvt_pk_bf16_f32 v50, v52, v53
	v_cvt_pk_bf16_f32 v51, v54, v55
	flat_store_dwordx4 v[64:65], v[48:51] offset:256
.LBB0_1769:
	s_or_b64 exec, exec, s[42:43]
	s_nop 0
	v_lshlrev_b64 v[48:49], 13, v[146:147]
	v_lshl_add_u64 v[48:49], s[14:15], 0, v[48:49]
	v_lshl_add_u64 v[48:49], v[144:145], 1, v[48:49]
	v_lshl_add_u64 v[48:49], v[48:49], 0, s[24:25]
	s_and_saveexec_b64 s[42:43], vcc
	s_cbranch_execz .LBB0_1771
	v_max_f32_e32 v44, 0, v44
	v_max_f32_e32 v45, 0, v45
	v_max_f32_e32 v46, 0, v46
	v_max_f32_e32 v47, 0, v47
	v_max_f32_e32 v40, 0, v40
	v_max_f32_e32 v41, 0, v41
	v_max_f32_e32 v42, 0, v42
	v_max_f32_e32 v43, 0, v43
	v_pk_mul_f32 v[44:45], v[44:45], v[44:45]
	v_pk_mul_f32 v[46:47], v[46:47], v[46:47]
	v_pk_mul_f32 v[40:41], v[40:41], v[40:41]
	v_pk_mul_f32 v[42:43], v[42:43], v[42:43]
	v_cvt_pk_bf16_f32 v40, v40, v41
	v_cvt_pk_bf16_f32 v41, v42, v43
	v_cvt_pk_bf16_f32 v42, v44, v45
	v_cvt_pk_bf16_f32 v43, v46, v47
	flat_store_dwordx4 v[48:49], v[40:43]
.LBB0_1771:
	s_or_b64 exec, exec, s[42:43]
	s_and_saveexec_b64 s[42:43], s[10:11]
	s_cbranch_execz .LBB0_1773
	v_max_f32_e32 v36, 0, v36
	v_max_f32_e32 v37, 0, v37
	v_max_f32_e32 v38, 0, v38
	v_max_f32_e32 v39, 0, v39
	v_max_f32_e32 v32, 0, v32
	v_max_f32_e32 v33, 0, v33
	v_max_f32_e32 v34, 0, v34
	v_max_f32_e32 v35, 0, v35
	v_pk_mul_f32 v[36:37], v[36:37], v[36:37]
	v_pk_mul_f32 v[38:39], v[38:39], v[38:39]
	v_pk_mul_f32 v[32:33], v[32:33], v[32:33]
	v_pk_mul_f32 v[34:35], v[34:35], v[34:35]
	v_cvt_pk_bf16_f32 v32, v32, v33
	v_cvt_pk_bf16_f32 v33, v34, v35
	v_cvt_pk_bf16_f32 v34, v36, v37
	v_cvt_pk_bf16_f32 v35, v38, v39
	flat_store_dwordx4 v[48:49], v[32:35] offset:256
.LBB0_1773:
	s_or_b64 exec, exec, s[42:43]
	s_nop 0
	v_lshlrev_b64 v[32:33], 13, v[146:147]
	v_lshl_add_u64 v[32:33], s[14:15], 0, v[32:33]
	v_lshl_add_u64 v[32:33], v[144:145], 1, v[32:33]
	v_lshl_add_u64 v[32:33], v[32:33], 0, s[26:27]
	s_and_saveexec_b64 s[42:43], vcc
	s_cbranch_execz .LBB0_1775
	v_max_f32_e32 v28, 0, v28
	v_max_f32_e32 v29, 0, v29
	v_max_f32_e32 v30, 0, v30
	v_max_f32_e32 v31, 0, v31
	v_max_f32_e32 v24, 0, v24
	v_max_f32_e32 v25, 0, v25
	v_max_f32_e32 v26, 0, v26
	v_max_f32_e32 v27, 0, v27
	v_pk_mul_f32 v[28:29], v[28:29], v[28:29]
	v_pk_mul_f32 v[30:31], v[30:31], v[30:31]
	v_pk_mul_f32 v[24:25], v[24:25], v[24:25]
	v_pk_mul_f32 v[26:27], v[26:27], v[26:27]
	v_cvt_pk_bf16_f32 v24, v24, v25
	v_cvt_pk_bf16_f32 v25, v26, v27
	v_cvt_pk_bf16_f32 v26, v28, v29
	v_cvt_pk_bf16_f32 v27, v30, v31
	flat_store_dwordx4 v[32:33], v[24:27]
.LBB0_1775:
	s_or_b64 exec, exec, s[42:43]
	s_and_saveexec_b64 s[42:43], s[10:11]
	s_cbranch_execz .LBB0_1777
	v_max_f32_e32 v20, 0, v20
	v_max_f32_e32 v21, 0, v21
	v_max_f32_e32 v22, 0, v22
	v_max_f32_e32 v23, 0, v23
	v_max_f32_e32 v16, 0, v16
	v_max_f32_e32 v17, 0, v17
	v_max_f32_e32 v18, 0, v18
	v_max_f32_e32 v19, 0, v19
	v_pk_mul_f32 v[20:21], v[20:21], v[20:21]
	v_pk_mul_f32 v[22:23], v[22:23], v[22:23]
	v_pk_mul_f32 v[16:17], v[16:17], v[16:17]
	v_pk_mul_f32 v[18:19], v[18:19], v[18:19]
	v_cvt_pk_bf16_f32 v16, v16, v17
	v_cvt_pk_bf16_f32 v17, v18, v19
	v_cvt_pk_bf16_f32 v18, v20, v21
	v_cvt_pk_bf16_f32 v19, v22, v23
	flat_store_dwordx4 v[32:33], v[16:19] offset:256
.LBB0_1777:
	s_or_b64 exec, exec, s[42:43]
	s_nop 0
	v_lshlrev_b64 v[16:17], 13, v[146:147]
	v_lshl_add_u64 v[16:17], s[14:15], 0, v[16:17]
	v_lshl_add_u64 v[16:17], v[144:145], 1, v[16:17]
	v_lshl_add_u64 v[16:17], v[16:17], 0, s[28:29]
	s_and_saveexec_b64 s[42:43], vcc
	s_cbranch_execz .LBB0_1779
	v_max_f32_e32 v12, 0, v12
	v_max_f32_e32 v13, 0, v13
	v_max_f32_e32 v14, 0, v14
	v_max_f32_e32 v15, 0, v15
	v_max_f32_e32 v8, 0, v8
	v_max_f32_e32 v9, 0, v9
	v_max_f32_e32 v10, 0, v10
	v_max_f32_e32 v11, 0, v11
	v_pk_mul_f32 v[12:13], v[12:13], v[12:13]
	v_pk_mul_f32 v[14:15], v[14:15], v[14:15]
	v_pk_mul_f32 v[8:9], v[8:9], v[8:9]
	v_pk_mul_f32 v[10:11], v[10:11], v[10:11]
	v_cvt_pk_bf16_f32 v8, v8, v9
	v_cvt_pk_bf16_f32 v9, v10, v11
	v_cvt_pk_bf16_f32 v10, v12, v13
	v_cvt_pk_bf16_f32 v11, v14, v15
	flat_store_dwordx4 v[16:17], v[8:11]
.LBB0_1779:
	s_or_b64 exec, exec, s[42:43]
	s_and_saveexec_b64 s[42:43], s[10:11]
	s_cbranch_execz .LBB0_1725
	v_max_f32_e32 v4, 0, v4
	v_max_f32_e32 v5, 0, v5
	v_max_f32_e32 v6, 0, v6
	v_max_f32_e32 v7, 0, v7
	v_max_f32_e32 v0, 0, v0
	v_max_f32_e32 v1, 0, v1
	v_max_f32_e32 v2, 0, v2
	v_max_f32_e32 v3, 0, v3
	v_pk_mul_f32 v[4:5], v[4:5], v[4:5]
	v_pk_mul_f32 v[6:7], v[6:7], v[6:7]
	v_pk_mul_f32 v[0:1], v[0:1], v[0:1]
	v_pk_mul_f32 v[2:3], v[2:3], v[2:3]
	v_cvt_pk_bf16_f32 v0, v0, v1
	v_cvt_pk_bf16_f32 v1, v2, v3
	v_cvt_pk_bf16_f32 v2, v4, v5
	v_cvt_pk_bf16_f32 v3, v6, v7
	flat_store_dwordx4 v[16:17], v[0:3] offset:256
	s_branch .LBB0_1725

.LBB0_2968:
	s_bitcmp1_b32 s10, 0
	s_cselect_b32 s11, 0xb800, 0
	s_setprio 1
	v_or_b32_e32 v80, s11, v94
	v_add_u32_e32 v109, v80, v186
	ds_read_b128 v[220:223], v109
	ds_read_b128 v[224:227], v109 offset:64
	ds_read_b128 v[228:231], v109 offset:3328
	ds_read_b128 v[232:235], v109 offset:6656
	ds_read_b128 v[236:239], v109 offset:9984
	ds_read_b128 v[240:243], v109 offset:3392
	ds_read_b128 v[244:247], v109 offset:6720
	ds_read_b128 v[248:251], v109 offset:10048
	s_waitcnt lgkmcnt(7)
	v_mfma_f32_16x16x32_bf16 v[112:115], v[220:223], v[4:7], v[0:3]
	v_mfma_f32_16x16x32_bf16 v[82:85], v[220:223], v[16:19], v[0:3]
	ds_read_b128 v[220:223], v109 offset:128
	s_waitcnt lgkmcnt(7)
	v_mfma_f32_16x16x32_bf16 v[112:115], v[224:227], v[8:11], v[112:115]
	v_mfma_f32_16x16x32_bf16 v[82:85], v[224:227], v[20:23], v[82:85]
	ds_read_b128 v[224:227], v109 offset:3456
	s_waitcnt lgkmcnt(7)
	v_mfma_f32_16x16x32_bf16 v[120:123], v[228:231], v[4:7], v[0:3]
	v_mfma_f32_16x16x32_bf16 v[116:119], v[228:231], v[16:19], v[0:3]
	ds_read_b128 v[228:231], v109 offset:6784
	s_waitcnt lgkmcnt(5)
	v_mfma_f32_16x16x32_bf16 v[120:123], v[240:243], v[8:11], v[120:123]
	v_mfma_f32_16x16x32_bf16 v[116:119], v[240:243], v[20:23], v[116:119]
	ds_read_b128 v[240:243], v109 offset:10112
	v_mfma_f32_16x16x32_bf16 v[128:131], v[232:235], v[4:7], v[0:3]
	v_mfma_f32_16x16x32_bf16 v[124:127], v[232:235], v[16:19], v[0:3]
	s_waitcnt lgkmcnt(5)
	v_mfma_f32_16x16x32_bf16 v[128:131], v[244:247], v[8:11], v[128:131]
	v_mfma_f32_16x16x32_bf16 v[124:127], v[244:247], v[20:23], v[124:127]
	v_mfma_f32_16x16x32_bf16 v[136:139], v[236:239], v[4:7], v[0:3]
	v_mfma_f32_16x16x32_bf16 v[132:135], v[236:239], v[16:19], v[0:3]
	s_waitcnt lgkmcnt(4)
	v_mfma_f32_16x16x32_bf16 v[136:139], v[248:251], v[8:11], v[136:139]
	v_mfma_f32_16x16x32_bf16 v[132:135], v[248:251], v[20:23], v[132:135]
	s_waitcnt lgkmcnt(3)
	v_mfma_f32_16x16x32_bf16 v[148:151], v[220:223], v[24:27], v[82:85]
	s_waitcnt lgkmcnt(2)
	v_mfma_f32_16x16x32_bf16 v[120:123], v[224:227], v[12:15], v[120:123]
	v_mfma_f32_16x16x32_bf16 v[84:87], v[224:227], v[24:27], v[116:119]
	s_waitcnt lgkmcnt(1)
	v_mfma_f32_16x16x32_bf16 v[152:155], v[228:231], v[12:15], v[128:131]
	v_mfma_f32_16x16x32_bf16 v[156:159], v[228:231], v[24:27], v[124:127]
	v_mfma_f32_16x16x32_bf16 v[112:115], v[220:223], v[12:15], v[112:115]
	s_waitcnt lgkmcnt(0)
	v_mfma_f32_16x16x32_bf16 v[160:163], v[240:243], v[12:15], v[136:139]
	v_mfma_f32_16x16x32_bf16 v[164:167], v[240:243], v[24:27], v[132:135]
	s_nop 2
	s_setprio 0
	s_nop 3
	v_max3_f32 v80, v112, v113, v114
	v_max3_f32 v80, v80, v115, v120
	v_max3_f32 v80, v80, v121, v122
	v_max3_f32 v80, v80, v123, v152
	v_max3_f32 v80, v80, v153, v154
	v_max3_f32 v80, v80, v155, v160
	v_max3_f32 v80, v80, v161, v162
	v_max_f32_e32 v80, v80, v163
	v_mul_f32_e32 v80, 0x3e16c740, v80
	v_max_f32_e32 v80, s68, v80
	v_mov_b32_e32 v82, v80
	s_nop 1
	v_permlane16_swap_b32_e32 v80, v82
	v_max_f32_e32 v80, v80, v82
	v_mov_b32_e32 v82, v80
	s_nop 1
	v_permlane32_swap_b32_e32 v80, v82
	v_max3_f32 v144, v81, v80, v82
	v_sub_f32_e32 v80, v81, v144
	v_fma_f32 v81, v112, s38, -v144
	v_exp_f32_e32 v143, v81
	v_fma_f32 v81, v113, s38, -v144
	v_exp_f32_e32 v141, v81
	v_fma_f32 v81, v114, s38, -v144
	v_max3_f32 v112, v148, v149, v150
	v_max3_f32 v112, v112, v151, v84
	v_max3_f32 v112, v112, v85, v86
	v_max3_f32 v112, v112, v87, v156
	v_max3_f32 v112, v112, v157, v158
	v_max3_f32 v112, v112, v159, v164
	v_max3_f32 v112, v112, v165, v166
	v_max_f32_e32 v112, v112, v167
	v_mul_f32_e32 v112, 0x3e16c740, v112
	v_max_f32_e32 v112, s68, v112
	v_mov_b32_e32 v114, v112
	s_nop 1
	v_permlane16_swap_b32_e32 v112, v114
	v_max_f32_e32 v112, v112, v114
	v_mov_b32_e32 v114, v112
	v_exp_f32_e32 v139, v81
	v_fma_f32 v81, v115, s38, -v144
	v_permlane32_swap_b32_e32 v112, v114
	v_exp_f32_e32 v137, v81
	v_fma_f32 v81, v120, s38, -v144
	v_max3_f32 v146, v189, v112, v114
	v_exp_f32_e32 v135, v81
	v_fma_f32 v81, v121, s38, -v144
	v_fma_f32 v84, v84, s38, -v146
	v_exp_f32_e32 v133, v81
	v_fma_f32 v81, v122, s38, -v144
	v_exp_f32_e32 v134, v84
	v_fma_f32 v84, v85, s38, -v146
	v_exp_f32_e32 v131, v81
	v_fma_f32 v81, v123, s38, -v144
	v_exp_f32_e32 v132, v84
	v_fma_f32 v84, v86, s38, -v146
	v_exp_f32_e32 v129, v81
	v_fma_f32 v81, v152, s38, -v144
	v_exp_f32_e32 v130, v84
	v_fma_f32 v84, v87, s38, -v146
	v_exp_f32_e32 v127, v81
	v_fma_f32 v81, v153, s38, -v144
	v_exp_f32_e32 v128, v84
	v_fma_f32 v84, v156, s38, -v146
	v_exp_f32_e32 v125, v81
	v_fma_f32 v81, v154, s38, -v144
	v_exp_f32_e32 v126, v84
	v_fma_f32 v84, v157, s38, -v146
	v_exp_f32_e32 v123, v81
	v_fma_f32 v81, v155, s38, -v144
	v_fma_f32 v112, v148, s38, -v146
	v_exp_f32_e32 v124, v84
	v_fma_f32 v84, v158, s38, -v146
	v_exp_f32_e32 v119, v81
	v_fma_f32 v81, v160, s38, -v144
	v_exp_f32_e32 v142, v112
	v_fma_f32 v112, v149, s38, -v146
	v_exp_f32_e32 v122, v84
	v_fma_f32 v84, v159, s38, -v146
	v_exp_f32_e32 v115, v81
	v_fma_f32 v81, v161, s38, -v144
	v_exp_f32_e32 v140, v112
	v_fma_f32 v112, v150, s38, -v146
	v_exp_f32_e32 v118, v84
	v_fma_f32 v84, v164, s38, -v146
	v_fma_f32 v85, v166, s38, -v146
	v_exp_f32_e32 v113, v81
	v_fma_f32 v81, v162, s38, -v144
	v_exp_f32_e32 v110, v80
	v_fma_f32 v80, v163, s38, -v144
	v_sub_f32_e32 v116, v189, v146
	v_exp_f32_e32 v138, v112
	v_fma_f32 v112, v151, s38, -v146
	v_exp_f32_e32 v114, v84
	v_fma_f32 v84, v165, s38, -v146
	v_exp_f32_e32 v120, v85
	v_fma_f32 v85, v167, s38, -v146
	v_exp_f32_e32 v121, v81
	v_exp_f32_e32 v117, v80
	v_exp_f32_e32 v136, v112
	v_exp_f32_e32 v112, v84
	v_exp_f32_e32 v84, v116
	v_exp_f32_e32 v116, v85
	v_pk_mul_f32 v[70:71], v[70:71], v[110:111] op_sel_hi:[1,0]
	v_pk_mul_f32 v[68:69], v[68:69], v[110:111] op_sel_hi:[1,0]
	v_pk_mul_f32 v[66:67], v[66:67], v[110:111] op_sel_hi:[1,0]
	v_pk_mul_f32 v[64:65], v[64:65], v[110:111] op_sel_hi:[1,0]
	v_pk_mul_f32 v[74:75], v[74:75], v[110:111] op_sel_hi:[1,0]
	v_pk_mul_f32 v[72:73], v[72:73], v[110:111] op_sel_hi:[1,0]
	v_pk_mul_f32 v[82:83], v[78:79], v[110:111] op_sel_hi:[1,0]
	v_pk_mul_f32 v[80:81], v[76:77], v[110:111] op_sel_hi:[1,0]
	v_cvt_pk_bf16_f32 v152, v143, v141
	v_cvt_pk_bf16_f32 v153, v139, v137
	v_cvt_pk_bf16_f32 v154, v135, v133
	v_cvt_pk_bf16_f32 v155, v131, v129
	v_cvt_pk_bf16_f32 v76, v127, v125
	v_cvt_pk_bf16_f32 v77, v123, v119
	v_cvt_pk_bf16_f32 v78, v115, v113
	v_cvt_pk_bf16_f32 v79, v121, v117
	v_pk_mul_f32 v[54:55], v[54:55], v[84:85] op_sel_hi:[1,0]
	v_pk_mul_f32 v[52:53], v[52:53], v[84:85] op_sel_hi:[1,0]
	v_pk_mul_f32 v[50:51], v[50:51], v[84:85] op_sel_hi:[1,0]
	v_pk_mul_f32 v[48:49], v[48:49], v[84:85] op_sel_hi:[1,0]
	v_pk_mul_f32 v[58:59], v[58:59], v[84:85] op_sel_hi:[1,0]
	v_pk_mul_f32 v[56:57], v[56:57], v[84:85] op_sel_hi:[1,0]
	v_pk_mul_f32 v[62:63], v[62:63], v[84:85] op_sel_hi:[1,0]
	v_pk_mul_f32 v[60:61], v[60:61], v[84:85] op_sel_hi:[1,0]
	v_cvt_pk_bf16_f32 v148, v142, v140
	v_cvt_pk_bf16_f32 v149, v138, v136
	v_cvt_pk_bf16_f32 v150, v134, v132
	v_cvt_pk_bf16_f32 v151, v130, v128
	v_cvt_pk_bf16_f32 v156, v126, v124
	v_cvt_pk_bf16_f32 v157, v122, v118
	v_cvt_pk_bf16_f32 v158, v114, v112
	v_cvt_pk_bf16_f32 v159, v120, v116
	s_setprio 1
	v_add3_u32 v85, s11, v187, v188
	ds_read_b64_tr_b16 v[222:223], v85 offset:29184
	ds_read_b64_tr_b16 v[220:221], v85 offset:26624
	ds_read_b64_tr_b16 v[224:225], v85 offset:26656
	ds_read_b64_tr_b16 v[226:227], v85 offset:29216
	ds_read_b64_tr_b16 v[228:229], v85 offset:31744
	ds_read_b64_tr_b16 v[230:231], v85 offset:34304
	ds_read_b64_tr_b16 v[232:233], v85 offset:31776
	ds_read_b64_tr_b16 v[234:235], v85 offset:34336
	ds_read_b64_tr_b16 v[236:237], v85 offset:26688
	ds_read_b64_tr_b16 v[238:239], v85 offset:29248
	ds_read_b64_tr_b16 v[240:241], v85 offset:31808
	ds_read_b64_tr_b16 v[242:243], v85 offset:34368
	ds_read_b64_tr_b16 v[244:245], v85 offset:26720
	ds_read_b64_tr_b16 v[246:247], v85 offset:29280
	ds_read_b64_tr_b16 v[248:249], v85 offset:31840
	ds_read_b64_tr_b16 v[250:251], v85 offset:34400
	s_waitcnt lgkmcnt(14)
	v_mfma_f32_16x16x32_bf16 v[68:71], v[220:223], v[152:155], v[68:71]
	v_mfma_f32_16x16x32_bf16 v[52:55], v[220:223], v[148:151], v[52:55]
	s_waitcnt lgkmcnt(10)
	v_mfma_f32_16x16x32_bf16 v[68:71], v[228:231], v[76:79], v[68:71]
	v_mfma_f32_16x16x32_bf16 v[52:55], v[228:231], v[156:159], v[52:55]
	v_mfma_f32_16x16x32_bf16 v[64:67], v[224:227], v[152:155], v[64:67]
	v_mfma_f32_16x16x32_bf16 v[48:51], v[224:227], v[148:151], v[48:51]
	s_waitcnt lgkmcnt(8)
	v_mfma_f32_16x16x32_bf16 v[64:67], v[232:235], v[76:79], v[64:67]
	v_mfma_f32_16x16x32_bf16 v[48:51], v[232:235], v[156:159], v[48:51]
	s_waitcnt lgkmcnt(6)
	v_mfma_f32_16x16x32_bf16 v[72:75], v[236:239], v[152:155], v[72:75]
	v_mfma_f32_16x16x32_bf16 v[56:59], v[236:239], v[148:151], v[56:59]
	s_waitcnt lgkmcnt(4)
	v_mfma_f32_16x16x32_bf16 v[72:75], v[240:243], v[76:79], v[72:75]
	v_mfma_f32_16x16x32_bf16 v[56:59], v[240:243], v[156:159], v[56:59]
	s_waitcnt lgkmcnt(2)
	v_mfma_f32_16x16x32_bf16 v[60:63], v[244:247], v[148:151], v[60:63]
	v_mfma_f32_16x16x32_bf16 v[80:83], v[244:247], v[152:155], v[80:83]
	s_waitcnt lgkmcnt(0)
	v_mfma_f32_16x16x32_bf16 v[76:79], v[248:251], v[76:79], v[80:83]
	v_mfma_f32_16x16x32_bf16 v[60:63], v[248:251], v[156:159], v[60:63]
	s_nop 3
	s_setprio 0
	s_setprio 1
	ds_read_b128 v[220:223], v109 offset:13312
	ds_read_b128 v[224:227], v109 offset:13376
	ds_read_b128 v[228:231], v109 offset:16640
	ds_read_b128 v[232:235], v109 offset:19968
	ds_read_b128 v[236:239], v109 offset:23296
	ds_read_b128 v[240:243], v109 offset:16704
	ds_read_b128 v[244:247], v109 offset:20032
	ds_read_b128 v[248:251], v109 offset:23360
	s_waitcnt lgkmcnt(7)
	v_mfma_f32_16x16x32_bf16 v[148:151], v[220:223], v[4:7], v[0:3]
	v_mfma_f32_16x16x32_bf16 v[80:83], v[220:223], v[16:19], v[0:3]
	ds_read_b128 v[220:223], v109 offset:13440
	s_waitcnt lgkmcnt(7)
	v_mfma_f32_16x16x32_bf16 v[148:151], v[224:227], v[8:11], v[148:151]
	v_mfma_f32_16x16x32_bf16 v[80:83], v[224:227], v[20:23], v[80:83]
	ds_read_b128 v[224:227], v109 offset:16768
	s_waitcnt lgkmcnt(7)
	v_mfma_f32_16x16x32_bf16 v[156:159], v[228:231], v[4:7], v[0:3]
	v_mfma_f32_16x16x32_bf16 v[152:155], v[228:231], v[16:19], v[0:3]
	ds_read_b128 v[228:231], v109 offset:20096
	s_waitcnt lgkmcnt(5)
	v_mfma_f32_16x16x32_bf16 v[156:159], v[240:243], v[8:11], v[156:159]
	v_mfma_f32_16x16x32_bf16 v[152:155], v[240:243], v[20:23], v[152:155]
	ds_read_b128 v[240:243], v109 offset:23424
	v_mfma_f32_16x16x32_bf16 v[164:167], v[232:235], v[4:7], v[0:3]
	v_mfma_f32_16x16x32_bf16 v[160:163], v[232:235], v[16:19], v[0:3]
	s_waitcnt lgkmcnt(5)
	v_mfma_f32_16x16x32_bf16 v[164:167], v[244:247], v[8:11], v[164:167]
	v_mfma_f32_16x16x32_bf16 v[160:163], v[244:247], v[20:23], v[160:163]
	v_mfma_f32_16x16x32_bf16 v[190:193], v[236:239], v[4:7], v[0:3]
	v_mfma_f32_16x16x32_bf16 v[168:171], v[236:239], v[16:19], v[0:3]
	s_waitcnt lgkmcnt(4)
	v_mfma_f32_16x16x32_bf16 v[190:193], v[248:251], v[8:11], v[190:193]
	v_mfma_f32_16x16x32_bf16 v[168:171], v[248:251], v[20:23], v[168:171]
	s_waitcnt lgkmcnt(3)
	v_mfma_f32_16x16x32_bf16 v[148:151], v[220:223], v[12:15], v[148:151]
	v_mfma_f32_16x16x32_bf16 v[194:197], v[220:223], v[24:27], v[80:83]
	s_waitcnt lgkmcnt(2)
	v_mfma_f32_16x16x32_bf16 v[198:201], v[224:227], v[12:15], v[156:159]
	v_mfma_f32_16x16x32_bf16 v[202:205], v[224:227], v[24:27], v[152:155]
	s_waitcnt lgkmcnt(1)
	v_mfma_f32_16x16x32_bf16 v[206:209], v[228:231], v[12:15], v[164:167]
	v_mfma_f32_16x16x32_bf16 v[210:213], v[228:231], v[24:27], v[160:163]
	s_waitcnt lgkmcnt(0)
	v_mfma_f32_16x16x32_bf16 v[190:193], v[240:243], v[12:15], v[190:193]
	v_mfma_f32_16x16x32_bf16 v[214:217], v[240:243], v[24:27], v[168:171]
	s_nop 1
	s_setprio 0
	v_max3_f32 v80, v148, v149, v150
	v_max3_f32 v80, v80, v151, v198
	v_max3_f32 v80, v80, v199, v200
	v_max3_f32 v80, v80, v201, v206
	v_max3_f32 v80, v80, v207, v208
	v_max3_f32 v80, v80, v209, v190
	v_max3_f32 v80, v80, v191, v192
	v_max_f32_e32 v80, v80, v193
	v_mul_f32_e32 v80, 0x3e16c740, v80
	v_max_f32_e32 v80, s68, v80
	v_mov_b32_e32 v81, v80
	s_nop 1
	v_permlane16_swap_b32_e32 v80, v81
	v_max_f32_e32 v80, v80, v81
	v_mov_b32_e32 v81, v80
	s_nop 1
	v_permlane32_swap_b32_e32 v80, v81
	v_max3_f32 v81, v144, v80, v81
	v_fma_f32 v82, v148, s38, -v81
	v_exp_f32_e32 v171, v82
	v_fma_f32 v82, v149, s38, -v81
	v_exp_f32_e32 v169, v82
	v_fma_f32 v82, v150, s38, -v81
	v_exp_f32_e32 v167, v82
	v_fma_f32 v82, v151, s38, -v81
	v_exp_f32_e32 v165, v82
	v_fma_f32 v82, v198, s38, -v81
	v_exp_f32_e32 v163, v82
	v_fma_f32 v82, v199, s38, -v81
	v_exp_f32_e32 v161, v82
	v_fma_f32 v82, v200, s38, -v81
	v_exp_f32_e32 v159, v82
	v_fma_f32 v82, v201, s38, -v81
	v_exp_f32_e32 v157, v82
	v_fma_f32 v82, v206, s38, -v81
	v_exp_f32_e32 v155, v82
	v_fma_f32 v82, v207, s38, -v81
	v_exp_f32_e32 v153, v82
	v_fma_f32 v82, v208, s38, -v81
	v_exp_f32_e32 v151, v82
	v_fma_f32 v82, v209, s38, -v81
	v_exp_f32_e32 v147, v82
	v_fma_f32 v82, v190, s38, -v81
	v_exp_f32_e32 v87, v82
	v_fma_f32 v82, v191, s38, -v81
	v_exp_f32_e32 v83, v82
	v_fma_f32 v82, v192, s38, -v81
	v_exp_f32_e32 v149, v82
	v_fma_f32 v82, v193, s38, -v81
	v_exp_f32_e32 v145, v82
	v_max3_f32 v82, v194, v195, v196
	v_max3_f32 v82, v82, v197, v202
	v_max3_f32 v82, v82, v203, v204
	v_max3_f32 v82, v82, v205, v210
	v_max3_f32 v82, v82, v211, v212
	v_max3_f32 v82, v82, v213, v214
	v_max3_f32 v82, v82, v215, v216
	v_max_f32_e32 v82, v82, v217
	v_mul_f32_e32 v82, 0x3e16c740, v82
	v_max_f32_e32 v82, s68, v82
	v_mov_b32_e32 v86, v82
	s_nop 1
	v_permlane16_swap_b32_e32 v82, v86
	v_max_f32_e32 v82, v82, v86
	v_mov_b32_e32 v86, v82
	s_nop 1
	v_permlane32_swap_b32_e32 v82, v86
	v_max3_f32 v189, v146, v82, v86
	v_fma_f32 v82, v194, s38, -v189
	v_exp_f32_e32 v170, v82
	v_fma_f32 v82, v195, s38, -v189
	v_exp_f32_e32 v168, v82
	v_fma_f32 v82, v196, s38, -v189
	v_exp_f32_e32 v166, v82
	v_fma_f32 v82, v197, s38, -v189
	v_exp_f32_e32 v164, v82
	v_fma_f32 v82, v202, s38, -v189
	v_exp_f32_e32 v162, v82
	v_fma_f32 v82, v203, s38, -v189
	v_exp_f32_e32 v160, v82
	v_fma_f32 v82, v204, s38, -v189
	v_exp_f32_e32 v158, v82
	v_fma_f32 v82, v205, s38, -v189
	v_exp_f32_e32 v156, v82
	v_fma_f32 v82, v210, s38, -v189
	v_exp_f32_e32 v154, v82
	v_fma_f32 v82, v211, s38, -v189
	v_exp_f32_e32 v152, v82
	v_fma_f32 v82, v212, s38, -v189
	v_exp_f32_e32 v150, v82
	v_fma_f32 v82, v213, s38, -v189
	v_sub_f32_e32 v80, v144, v81
	v_sub_f32_e32 v109, v146, v189
	v_exp_f32_e32 v146, v82
	v_fma_f32 v82, v214, s38, -v189
	v_exp_f32_e32 v80, v80
	v_exp_f32_e32 v86, v82
	v_fma_f32 v82, v215, s38, -v189
	v_fma_f32 v144, v216, s38, -v189
	v_exp_f32_e32 v172, v109
	v_fma_f32 v109, v217, s38, -v189
	v_exp_f32_e32 v82, v82
	v_exp_f32_e32 v148, v144
	v_exp_f32_e32 v144, v109
	v_pk_mul_f32 v[70:71], v[70:71], v[80:81] op_sel_hi:[1,0]
	v_pk_mul_f32 v[68:69], v[68:69], v[80:81] op_sel_hi:[1,0]
	v_pk_mul_f32 v[66:67], v[66:67], v[80:81] op_sel_hi:[1,0]
	v_pk_mul_f32 v[64:65], v[64:65], v[80:81] op_sel_hi:[1,0]
	v_pk_mul_f32 v[74:75], v[74:75], v[80:81] op_sel_hi:[1,0]
	v_pk_mul_f32 v[72:73], v[72:73], v[80:81] op_sel_hi:[1,0]
	v_pk_mul_f32 v[192:193], v[78:79], v[80:81] op_sel_hi:[1,0]
	v_pk_mul_f32 v[190:191], v[76:77], v[80:81] op_sel_hi:[1,0]
	v_cvt_pk_bf16_f32 v76, v155, v153
	v_cvt_pk_bf16_f32 v77, v151, v147
	v_cvt_pk_bf16_f32 v78, v87, v83
	v_cvt_pk_bf16_f32 v79, v149, v145
	v_pk_mul_f32 v[54:55], v[54:55], v[172:173] op_sel_hi:[1,0]
	v_pk_mul_f32 v[52:53], v[52:53], v[172:173] op_sel_hi:[1,0]
	v_pk_mul_f32 v[50:51], v[50:51], v[172:173] op_sel_hi:[1,0]
	v_pk_mul_f32 v[48:49], v[48:49], v[172:173] op_sel_hi:[1,0]
	v_pk_mul_f32 v[58:59], v[58:59], v[172:173] op_sel_hi:[1,0]
	v_pk_mul_f32 v[56:57], v[56:57], v[172:173] op_sel_hi:[1,0]
	v_pk_mul_f32 v[62:63], v[62:63], v[172:173] op_sel_hi:[1,0]
	v_pk_mul_f32 v[60:61], v[60:61], v[172:173] op_sel_hi:[1,0]
	v_cvt_pk_bf16_f32 v198, v171, v169
	v_cvt_pk_bf16_f32 v199, v167, v165
	v_cvt_pk_bf16_f32 v200, v163, v161
	v_cvt_pk_bf16_f32 v201, v159, v157
	v_cvt_pk_bf16_f32 v194, v170, v168
	v_cvt_pk_bf16_f32 v195, v166, v164
	v_cvt_pk_bf16_f32 v196, v162, v160
	v_cvt_pk_bf16_f32 v197, v158, v156
	v_cvt_pk_bf16_f32 v202, v154, v152
	v_cvt_pk_bf16_f32 v203, v150, v146
	v_cvt_pk_bf16_f32 v204, v86, v82
	v_cvt_pk_bf16_f32 v205, v148, v144
	s_setprio 1
	ds_read_b64_tr_b16 v[222:223], v85 offset:39424
	ds_read_b64_tr_b16 v[220:221], v85 offset:36864
	ds_read_b64_tr_b16 v[224:225], v85 offset:36896
	ds_read_b64_tr_b16 v[226:227], v85 offset:39456
	ds_read_b64_tr_b16 v[228:229], v85 offset:41984
	ds_read_b64_tr_b16 v[230:231], v85 offset:44544
	ds_read_b64_tr_b16 v[232:233], v85 offset:42016
	ds_read_b64_tr_b16 v[234:235], v85 offset:44576
	ds_read_b64_tr_b16 v[236:237], v85 offset:36928
	ds_read_b64_tr_b16 v[238:239], v85 offset:39488
	ds_read_b64_tr_b16 v[240:241], v85 offset:42048
	ds_read_b64_tr_b16 v[242:243], v85 offset:44608
	ds_read_b64_tr_b16 v[244:245], v85 offset:36960
	ds_read_b64_tr_b16 v[246:247], v85 offset:39520
	ds_read_b64_tr_b16 v[248:249], v85 offset:42080
	ds_read_b64_tr_b16 v[250:251], v85 offset:44640
	s_waitcnt lgkmcnt(14)
	v_mfma_f32_16x16x32_bf16 v[68:71], v[220:223], v[198:201], v[68:71]
	v_mfma_f32_16x16x32_bf16 v[52:55], v[220:223], v[194:197], v[52:55]
	s_waitcnt lgkmcnt(10)
	v_mfma_f32_16x16x32_bf16 v[68:71], v[228:231], v[76:79], v[68:71]
	v_mfma_f32_16x16x32_bf16 v[52:55], v[228:231], v[202:205], v[52:55]
	v_mfma_f32_16x16x32_bf16 v[64:67], v[224:227], v[198:201], v[64:67]
	v_mfma_f32_16x16x32_bf16 v[48:51], v[224:227], v[194:197], v[48:51]
	s_waitcnt lgkmcnt(8)
	v_mfma_f32_16x16x32_bf16 v[64:67], v[232:235], v[76:79], v[64:67]
	v_mfma_f32_16x16x32_bf16 v[48:51], v[232:235], v[202:205], v[48:51]
	s_waitcnt lgkmcnt(6)
	v_mfma_f32_16x16x32_bf16 v[72:75], v[236:239], v[198:201], v[72:75]
	v_mfma_f32_16x16x32_bf16 v[56:59], v[236:239], v[194:197], v[56:59]
	s_waitcnt lgkmcnt(4)
	v_mfma_f32_16x16x32_bf16 v[72:75], v[240:243], v[76:79], v[72:75]
	v_mfma_f32_16x16x32_bf16 v[56:59], v[240:243], v[202:205], v[56:59]
	s_waitcnt lgkmcnt(2)
	v_mfma_f32_16x16x32_bf16 v[60:63], v[244:247], v[194:197], v[60:63]
	v_mfma_f32_16x16x32_bf16 v[190:193], v[244:247], v[198:201], v[190:193]
	s_waitcnt lgkmcnt(0)
	v_mfma_f32_16x16x32_bf16 v[76:79], v[248:251], v[76:79], v[190:193]
	v_mfma_f32_16x16x32_bf16 v[60:63], v[248:251], v[202:205], v[60:63]
	s_nop 3
	s_setprio 0
	s_add_i32 s22, s10, 1
	s_cmp_ge_u32 s22, s19
	s_cbranch_scc1 .LBB0_2970
	s_bitcmp1_b32 s22, 0
	s_cselect_b32 s11, 0xb800, 0
	v_add3_u32 v85, s11, v95, v96
	s_waitcnt vmcnt(0)
	ds_write_b128 v85, v[28:31]
	v_add3_u32 v85, s11, v99, v96
	ds_write_b128 v85, v[36:39]
	v_add3_u32 v85, s11, v184, v96
	ds_write_b128 v85, v[32:35] offset:26624
	v_add3_u32 v85, s11, v185, v96
	ds_write_b128 v85, v[40:43] offset:26624
	v_add3_u32 v85, s11, v111, v98
	ds_write_b128 v85, v[44:47] offset:128

.LBB0_3018:
	s_or_b64 exec, exec, s[6:7]
	s_ashr_i32 s12, s24, 2
	s_and_b32 s6, s12, -16
	s_max_i32 s13, s6, 64
	s_or_b32 s6, s12, 15
	s_add_i32 s16, s13, 0xffffff80
	s_min_i32 s17, s6, 64
	s_mov_b64 s[6:7], s[0:1]
	s_add_u32 s6, s6, s3
	s_addc_u32 s7, s7, s63
	s_waitcnt lgkmcnt(0)
	s_barrier
	s_load_dwordx2 s[6:7], s[6:7], 0x100
	s_ashr_i32 s11, s10, 31
	s_lshl_b64 s[10:11], s[10:11], 2
	v_bfe_u32 v4, v8, 4, 2
	v_bfi_b32 v5, -16, s12, v8
	s_waitcnt lgkmcnt(0)
	s_add_u32 s6, s6, s10
	s_addc_u32 s7, s7, s11
	global_load_dword v34, v89, s[6:7] offset:1920
	global_load_dword v35, v89, s[6:7] offset:2944
	v_lshlrev_b32_e32 v4, 2, v4
	v_lshl_or_b32 v20, v5, 4, v4
	v_ashrrev_i32_e32 v21, 31, v20
	v_lshl_add_u64 v[4:5], v[20:21], 1, s[8:9]
	s_mov_b64 s[6:7], 0x7554000
	v_lshl_add_u64 v[22:23], v[4:5], 0, s[6:7]
	s_mov_b64 s[6:7], 0x7555000
	v_lshl_add_u64 v[24:25], v[4:5], 0, s[6:7]
	s_mov_b64 s[6:7], 0x7556000
	v_lshrrev_b32_e32 v7, 4, v8
	v_lshl_add_u64 v[26:27], v[4:5], 0, s[6:7]
	s_mov_b64 s[6:7], 0x7557000
	v_bfe_u32 v7, v7, 1, 1
	v_lshl_add_u64 v[28:29], v[4:5], 0, s[6:7]
	v_bfi_b32 v5, v8, 15, 1
	v_and_b32_e32 v4, 16, v8
	v_lshlrev_b32_e32 v5, 1, v5
	v_or_b32_e32 v7, s13, v7
	s_cmp_le_i32 s16, s17
	v_sub_u32_e32 v5, v4, v5
	v_lshlrev_b32_e32 v7, 5, v7
	v_and_b32_e32 v6, 15, v8
	s_cselect_b64 s[10:11], -1, 0
	v_sub_u32_e32 v5, v5, v7
	s_lshl_b32 s6, s12, 5
	v_add_u32_e32 v38, 0x183e, v5
	s_and_b32 s6, s6, 0xfffffe00
	v_lshlrev_b32_e32 v5, 5, v6
	v_or3_b32 v4, s6, v5, v4
	v_bitop3_b32 v36, v8, 1, v8 bitop3:0xc
	v_lshlrev_b32_e32 v37, 1, v20
	v_sub_u32_e32 v39, v4, v7
	s_mov_b32 s12, 0
	s_mov_b64 s[6:7], -1
	s_branch .LBB0_3020

.Lhy_lat1_done:
.LBB0_3023:
	s_waitcnt vmcnt(0)
	s_xor_b64 s[12:13], s[6:7], -1
	s_and_b64 s[18:19], s[6:7], exec
	s_cselect_b32 s18, s2, 0xddf2000
	s_add_u32 s18, s8, s18
	s_addc_u32 s19, s9, 0
	v_cndmask_b32_e64 v30, v35, v34, s[6:7]
	s_and_b64 s[6:7], s[6:7], exec
	s_mov_b32 s6, 0x9380
	s_cselect_b32 s6, 0x4380, s6
	v_lshl_add_u64 v[32:33], v[20:21], 1, s[18:19]
	v_lshl_add_u32 v31, v20, 1, s6
	s_movk_i32 s6, 0x2000
	v_add_co_u32_e32 v42, vcc, s6, v32
	ds_read_b64 v[40:41], v31
	s_nop 0
	v_addc_co_u32_e32 v43, vcc, 0, v33, vcc
	v_mov_b32_e32 v49, v18
	s_waitcnt lgkmcnt(0)
	v_lshlrev_b32_e32 v47, 16, v41
	v_lshlrev_b32_e32 v46, 16, v40
	v_and_b32_e32 v41, 0xffff0000, v41
	v_and_b32_e32 v40, 0xffff0000, v40
	v_mov_b32_e32 v18, v17
	v_mov_b32_e32 v48, v16
	v_pk_fma_f32 v[16:17], v[30:31], v[40:41], v[18:19] op_sel_hi:[0,1,1]
	v_pk_fma_f32 v[46:47], v[30:31], v[46:47], v[48:49] op_sel_hi:[0,1,1]
	s_mov_b64 s[6:7], -1
	s_and_b64 vcc, exec, s[12:13]
	s_waitcnt vmcnt(0)
	v_lshlrev_b32_e32 v45, 16, v141
	v_lshlrev_b32_e32 v44, 16, v140
	v_and_b32_e32 v43, 0xffff0000, v141
	v_and_b32_e32 v42, 0xffff0000, v140
	v_pk_mul_f32 v[16:17], v[16:17], v[42:43]
	v_pk_mul_f32 v[44:45], v[46:47], v[44:45]
	v_and_b32_sdwa v31, v17, v176 dst_sel:DWORD dst_unused:UNUSED_PAD src0_sel:WORD_1 src1_sel:DWORD
	v_and_b32_sdwa v40, v16, v176 dst_sel:DWORD dst_unused:UNUSED_PAD src0_sel:WORD_1 src1_sel:DWORD
	v_and_b32_sdwa v18, v45, v176 dst_sel:DWORD dst_unused:UNUSED_PAD src0_sel:WORD_1 src1_sel:DWORD
	v_and_b32_sdwa v19, v44, v176 dst_sel:DWORD dst_unused:UNUSED_PAD src0_sel:WORD_1 src1_sel:DWORD
	v_add3_u32 v17, v17, v31, s93
	v_add3_u32 v16, v16, v40, s93
	v_add3_u32 v19, v44, v19, s93
	v_add3_u32 v18, v45, v18, s93
	v_and_b32_e32 v17, 0xffff0000, v17
	v_and_b32_e32 v16, 0xffff0000, v16
	v_or_b32_sdwa v17, v17, v18 dst_sel:DWORD dst_unused:UNUSED_PAD src0_sel:DWORD src1_sel:WORD_1
	v_or_b32_sdwa v16, v16, v19 dst_sel:DWORD dst_unused:UNUSED_PAD src0_sel:DWORD src1_sel:WORD_1
	s_cbranch_vccz .LBB0_3025
	flat_store_dwordx2 v[22:23], v[16:17]
	s_mov_b64 s[6:7], 0

.LBB0_3058:
	s_bitcmp1_b32 s82, 0
	s_cselect_b32 s83, 0x9800, 0
	s_cmp_lt_i32 s82, s76
	s_cselect_b64 s[6:7], -1, 0
	s_and_b64 s[74:75], s[70:71], s[6:7]
	s_cmp_eq_u64 s[74:75], 0
	s_cbranch_scc1 .Lnm1_entry
	s_setprio 1
	v_or_b32_e32 v68, s83, v94
	v_add_u32_e32 v88, v68, v163
	ds_read_b128 v[204:207], v88 offset:2304
	ds_read_b128 v[208:211], v88
	ds_read_b128 v[212:215], v88 offset:4608
	ds_read_b128 v[216:219], v88 offset:6912
	ds_read_b128 v[220:223], v88 offset:64
	ds_read_b128 v[224:227], v88 offset:2368
	ds_read_b128 v[228:231], v88 offset:4672
	ds_read_b128 v[232:235], v88 offset:6976
	s_waitcnt lgkmcnt(7)
	v_mfma_f32_16x16x32_bf16 v[82:85], v[204:207], v[4:7], v[0:3]
	v_mfma_f32_16x16x32_bf16 v[108:111], v[204:207], v[12:15], v[0:3]
	s_waitcnt lgkmcnt(5)
	v_mfma_f32_16x16x32_bf16 v[112:115], v[212:215], v[4:7], v[0:3]
	v_mfma_f32_16x16x32_bf16 v[116:119], v[212:215], v[12:15], v[0:3]
	s_waitcnt lgkmcnt(4)
	v_mfma_f32_16x16x32_bf16 v[120:123], v[216:219], v[4:7], v[0:3]
	v_mfma_f32_16x16x32_bf16 v[124:127], v[216:219], v[12:15], v[0:3]
	v_mfma_f32_16x16x32_bf16 v[74:77], v[208:211], v[4:7], v[0:3]
	v_mfma_f32_16x16x32_bf16 v[68:71], v[208:211], v[12:15], v[0:3]
	s_waitcnt lgkmcnt(3)
	v_mfma_f32_16x16x32_bf16 v[128:131], v[220:223], v[8:11], v[74:77]
	v_mfma_f32_16x16x32_bf16 v[76:79], v[220:223], v[16:19], v[68:71]
	s_waitcnt lgkmcnt(2)
	v_mfma_f32_16x16x32_bf16 v[132:135], v[224:227], v[8:11], v[82:85]
	v_mfma_f32_16x16x32_bf16 v[80:83], v[224:227], v[16:19], v[108:111]
	s_waitcnt lgkmcnt(1)
	v_mfma_f32_16x16x32_bf16 v[108:111], v[228:231], v[8:11], v[112:115]
	v_mfma_f32_16x16x32_bf16 v[84:87], v[228:231], v[16:19], v[116:119]
	s_waitcnt lgkmcnt(0)
	v_mfma_f32_16x16x32_bf16 v[112:115], v[232:235], v[8:11], v[120:123]
	v_mfma_f32_16x16x32_bf16 v[142:145], v[232:235], v[16:19], v[124:127]
	s_nop 1
	s_setprio 0
	v_add_u32_e32 v69, 0x73, v166
	v_cmp_gt_u32_e32 vcc, s39, v69
	v_add_u32_e32 v70, 0x72, v166
	s_and_b64 s[12:13], s[74:75], vcc
	v_cmp_gt_u32_e32 vcc, s39, v70
	v_add_u32_e32 v72, 0x71, v166
	s_and_b64 s[14:15], s[74:75], vcc
	v_cmp_gt_u32_e32 vcc, s39, v72
	v_add_u32_e32 v74, 0x70, v166
	s_and_b64 s[16:17], s[74:75], vcc
	v_cmp_gt_u32_e32 vcc, s39, v74
	v_add_u32_e32 v75, 0x63, v166
	s_and_b64 s[18:19], s[74:75], vcc
	v_cmp_gt_u32_e32 vcc, s39, v75
	v_add_u32_e32 v106, 0x62, v166
	s_and_b64 s[20:21], s[74:75], vcc
	v_cmp_gt_u32_e32 vcc, s39, v106
	v_add_u32_e32 v116, 0x61, v166
	s_and_b64 s[22:23], s[74:75], vcc
	v_cmp_gt_u32_e32 vcc, s39, v116
	v_add_u32_e32 v117, 0x60, v166
	s_and_b64 s[24:25], s[74:75], vcc
	v_cmp_gt_u32_e32 vcc, s39, v117
	v_add_u32_e32 v117, 0x53, v166
	s_and_b64 s[26:27], s[74:75], vcc
	v_cmp_gt_u32_e32 vcc, s39, v117
	v_add_u32_e32 v117, 0x52, v166
	v_mul_f32_e32 v68, 0x3e38aa3b, v128
	v_mul_f32_e32 v69, 0x3e38aa3b, v129
	s_and_b64 s[28:29], s[74:75], vcc
	v_cmp_gt_u32_e32 vcc, s39, v117
	v_add_u32_e32 v117, 0x51, v166
	v_cndmask_b32_e64 v68, v68, v181, s[12:13]
	v_cndmask_b32_e64 v69, v69, v181, s[14:15]
	v_mul_f32_e32 v71, 0x3e38aa3b, v130
	v_mul_f32_e32 v72, 0x3e38aa3b, v131
	s_and_b64 s[30:31], s[74:75], vcc
	v_cmp_gt_u32_e32 vcc, s39, v117
	v_add_u32_e32 v117, 0x50, v166
	v_max3_f32 v70, v68, s68, v69
	v_cndmask_b32_e64 v71, v71, v181, s[16:17]
	v_cndmask_b32_e64 v72, v72, v181, s[18:19]
	v_mul_f32_e32 v74, 0x3e38aa3b, v132
	v_mul_f32_e32 v75, 0x3e38aa3b, v133
	s_and_b64 s[34:35], s[74:75], vcc
	v_cmp_gt_u32_e32 vcc, s39, v117
	v_add_u32_e32 v117, 0x43, v166
	v_max3_f32 v70, v70, v71, v72
	v_cndmask_b32_e64 v74, v74, v181, s[20:21]
	v_cndmask_b32_e64 v75, v75, v181, s[22:23]
	v_mul_f32_e32 v106, 0x3e38aa3b, v134
	v_mul_f32_e32 v116, 0x3e38aa3b, v135
	s_and_b64 s[36:37], s[74:75], vcc
	v_cmp_gt_u32_e32 vcc, s39, v117
	v_add_u32_e32 v117, 0x42, v166
	v_max3_f32 v70, v70, v74, v75
	v_cndmask_b32_e64 v106, v106, v181, s[24:25]
	v_cndmask_b32_e64 v116, v116, v181, s[26:27]
	v_mul_f32_e32 v108, 0x3e38aa3b, v108
	v_mul_f32_e32 v109, 0x3e38aa3b, v109
	v_cmp_gt_u32_e64 s[6:7], s39, v117
	v_add_u32_e32 v117, 0x41, v166
	v_max3_f32 v70, v70, v106, v116
	v_cndmask_b32_e64 v108, v108, v181, s[28:29]
	v_cndmask_b32_e64 v109, v109, v181, s[30:31]
	v_mul_f32_e32 v110, 0x3e38aa3b, v110
	v_mul_f32_e32 v111, 0x3e38aa3b, v111
	v_cmp_gt_u32_e64 s[8:9], s39, v117
	v_add_u32_e32 v117, 64, v166
	v_max3_f32 v70, v70, v108, v109
	v_cndmask_b32_e64 v110, v110, v181, s[34:35]
	v_cndmask_b32_e64 v111, v111, v181, s[36:37]
	v_mul_f32_e32 v112, 0x3e38aa3b, v112
	s_and_b64 vcc, s[74:75], vcc
	v_mul_f32_e32 v113, 0x3e38aa3b, v113
	s_and_b64 s[6:7], s[74:75], s[6:7]
	v_cmp_gt_u32_e64 s[10:11], s39, v117
	v_max3_f32 v70, v70, v110, v111
	v_cndmask_b32_e32 v112, v112, v181, vcc
	v_cndmask_b32_e64 v113, v113, v181, s[6:7]
	v_mul_f32_e32 v114, 0x3e38aa3b, v114
	s_and_b64 s[8:9], s[74:75], s[8:9]
	v_mul_f32_e32 v115, 0x3e38aa3b, v115
	s_and_b64 s[10:11], s[74:75], s[10:11]
	v_max3_f32 v70, v70, v112, v113
	v_cndmask_b32_e64 v114, v114, v181, s[8:9]
	v_cndmask_b32_e64 v118, v115, v181, s[10:11]
	v_max3_f32 v70, v70, v114, v118
	v_mov_b32_e32 v115, v70
	s_nop 1
	v_permlane16_swap_b32_e32 v70, v115
	v_max_f32_e32 v70, v70, v115
	v_mov_b32_e32 v115, v70
	s_nop 1
	v_permlane32_swap_b32_e32 v70, v115
	v_max3_f32 v140, v73, v70, v115
	v_sub_f32_e32 v68, v68, v140
	v_exp_f32_e32 v139, v68
	v_sub_f32_e32 v68, v69, v140
	v_exp_f32_e32 v137, v68
	v_sub_f32_e32 v68, v71, v140
	v_exp_f32_e32 v135, v68
	v_sub_f32_e32 v68, v72, v140
	v_exp_f32_e32 v133, v68
	v_sub_f32_e32 v68, v74, v140
	v_exp_f32_e32 v131, v68
	v_sub_f32_e32 v68, v75, v140
	v_exp_f32_e32 v129, v68
	v_sub_f32_e32 v68, v106, v140
	v_exp_f32_e32 v127, v68
	v_sub_f32_e32 v68, v116, v140
	v_exp_f32_e32 v125, v68
	v_sub_f32_e32 v68, v108, v140
	v_add_u32_e32 v108, 0x83, v166
	v_cmp_gt_u32_e64 s[40:41], s39, v108
	v_mul_f32_e32 v76, 0x3e38aa3b, v76
	s_and_b64 s[40:41], s[74:75], s[40:41]
	v_add_u32_e32 v108, 0x82, v166
	v_exp_f32_e32 v123, v68
	v_sub_f32_e32 v68, v109, v140
	v_cndmask_b32_e64 v76, v76, v181, s[40:41]
	v_cmp_gt_u32_e64 s[40:41], s39, v108
	v_exp_f32_e32 v121, v68
	v_sub_f32_e32 v68, v110, v140
	v_mul_f32_e32 v77, 0x3e38aa3b, v77
	s_and_b64 s[40:41], s[74:75], s[40:41]
	v_add_u32_e32 v110, 0x81, v166
	v_cndmask_b32_e64 v77, v77, v181, s[40:41]
	v_cmp_gt_u32_e64 s[40:41], s39, v110
	v_mul_f32_e32 v78, 0x3e38aa3b, v78
	s_and_b64 s[40:41], s[74:75], s[40:41]
	v_cndmask_b32_e64 v110, v78, v181, s[40:41]
	v_mul_f32_e32 v78, 0x3e38aa3b, v79
	v_add_u32_e32 v79, 0x80, v166
	v_cmp_gt_u32_e64 s[40:41], s39, v79
	s_and_b64 s[40:41], s[74:75], s[40:41]
	v_max3_f32 v108, v76, s68, v77
	v_cndmask_b32_e64 v79, v78, v181, s[40:41]
	v_mul_f32_e32 v80, 0x3e38aa3b, v80
	v_mul_f32_e32 v81, 0x3e38aa3b, v81
	v_exp_f32_e32 v119, v68
	v_sub_f32_e32 v68, v111, v140
	v_max3_f32 v78, v108, v110, v79
	v_cndmask_b32_e64 v80, v80, v181, s[12:13]
	v_cndmask_b32_e64 v81, v81, v181, s[14:15]
	v_mul_f32_e32 v82, 0x3e38aa3b, v82
	v_mul_f32_e32 v83, 0x3e38aa3b, v83
	v_exp_f32_e32 v115, v68
	v_sub_f32_e32 v68, v112, v140
	v_max3_f32 v78, v78, v80, v81
	v_cndmask_b32_e64 v82, v82, v181, s[16:17]
	v_cndmask_b32_e64 v83, v83, v181, s[18:19]
	v_mul_f32_e32 v84, 0x3e38aa3b, v84
	v_mul_f32_e32 v85, 0x3e38aa3b, v85
	v_exp_f32_e32 v111, v68
	v_sub_f32_e32 v68, v113, v140
	v_max3_f32 v78, v78, v82, v83
	v_cndmask_b32_e64 v84, v84, v181, s[20:21]
	v_cndmask_b32_e64 v85, v85, v181, s[22:23]
	v_mul_f32_e32 v86, 0x3e38aa3b, v86
	v_mul_f32_e32 v87, 0x3e38aa3b, v87
	v_exp_f32_e32 v109, v68
	v_sub_f32_e32 v68, v114, v140
	v_max3_f32 v78, v78, v84, v85
	v_cndmask_b32_e64 v86, v86, v181, s[24:25]
	v_cndmask_b32_e64 v87, v87, v181, s[26:27]
	v_mul_f32_e32 v108, 0x3e38aa3b, v142
	v_mul_f32_e32 v112, 0x3e38aa3b, v143
	v_mul_f32_e32 v114, 0x3e38aa3b, v144
	v_max3_f32 v78, v78, v86, v87
	v_cndmask_b32_e64 v108, v108, v181, s[28:29]
	v_cndmask_b32_e64 v112, v112, v181, s[30:31]
	v_cndmask_b32_e64 v116, v114, v181, s[34:35]
	v_mul_f32_e32 v114, 0x3e38aa3b, v145
	v_max3_f32 v78, v78, v108, v112
	v_cndmask_b32_e64 v141, v114, v181, s[36:37]
	v_max3_f32 v78, v78, v116, v141
	v_mov_b32_e32 v114, v78
	s_nop 1
	v_permlane16_swap_b32_e32 v78, v114
	v_max_f32_e32 v78, v78, v114
	v_mov_b32_e32 v114, v78
	s_nop 1
	v_permlane32_swap_b32_e32 v78, v114
	v_max3_f32 v78, v167, v78, v114
	v_sub_f32_e32 v76, v76, v78
	v_exp_f32_e32 v138, v76
	v_sub_f32_e32 v76, v77, v78
	v_exp_f32_e32 v136, v76
	v_sub_f32_e32 v76, v110, v78
	v_exp_f32_e32 v134, v76
	v_sub_f32_e32 v76, v79, v78
	v_exp_f32_e32 v132, v76
	v_sub_f32_e32 v76, v80, v78
	v_exp_f32_e32 v130, v76
	v_sub_f32_e32 v76, v81, v78
	v_exp_f32_e32 v128, v76
	v_sub_f32_e32 v76, v82, v78
	v_exp_f32_e32 v126, v76
	v_sub_f32_e32 v76, v83, v78
	v_exp_f32_e32 v124, v76
	v_sub_f32_e32 v76, v84, v78
	v_exp_f32_e32 v122, v76
	v_sub_f32_e32 v76, v85, v78
	v_exp_f32_e32 v120, v76
	v_sub_f32_e32 v76, v86, v78
	v_exp_f32_e32 v117, v68
	v_sub_f32_e32 v68, v118, v140
	v_exp_f32_e32 v118, v76
	v_sub_f32_e32 v76, v87, v78
	v_exp_f32_e32 v114, v76
	v_sub_f32_e32 v76, v108, v78
	v_sub_f32_e32 v77, v116, v78
	v_sub_f32_e32 v70, v73, v140
	v_sub_f32_e32 v142, v167, v78
	v_exp_f32_e32 v110, v76
	v_sub_f32_e32 v76, v112, v78
	v_exp_f32_e32 v116, v77
	v_sub_f32_e32 v77, v141, v78
	v_exp_f32_e32 v106, v70
	v_exp_f32_e32 v113, v68
	v_exp_f32_e32 v108, v76
	v_exp_f32_e32 v76, v142
	v_exp_f32_e32 v112, v77
	v_pk_mul_f32 v[58:59], v[58:59], v[106:107] op_sel_hi:[1,0]
	v_pk_mul_f32 v[56:57], v[56:57], v[106:107] op_sel_hi:[1,0]
	v_pk_mul_f32 v[54:55], v[54:55], v[106:107] op_sel_hi:[1,0]
	v_pk_mul_f32 v[52:53], v[52:53], v[106:107] op_sel_hi:[1,0]
	v_pk_mul_f32 v[62:63], v[62:63], v[106:107] op_sel_hi:[1,0]
	v_pk_mul_f32 v[60:61], v[60:61], v[106:107] op_sel_hi:[1,0]
	v_pk_mul_f32 v[70:71], v[66:67], v[106:107] op_sel_hi:[1,0]
	v_pk_mul_f32 v[68:69], v[64:65], v[106:107] op_sel_hi:[1,0]
	v_cvt_pk_bf16_f32 v72, v139, v137
	v_cvt_pk_bf16_f32 v73, v135, v133
	v_cvt_pk_bf16_f32 v74, v131, v129
	v_cvt_pk_bf16_f32 v75, v127, v125
	v_cvt_pk_bf16_f32 v64, v123, v121
	v_cvt_pk_bf16_f32 v65, v119, v115
	v_cvt_pk_bf16_f32 v66, v111, v109
	v_cvt_pk_bf16_f32 v67, v117, v113
	v_pk_mul_f32 v[42:43], v[42:43], v[76:77] op_sel_hi:[1,0]
	v_pk_mul_f32 v[40:41], v[40:41], v[76:77] op_sel_hi:[1,0]
	v_pk_mul_f32 v[38:39], v[38:39], v[76:77] op_sel_hi:[1,0]
	v_pk_mul_f32 v[36:37], v[36:37], v[76:77] op_sel_hi:[1,0]
	v_pk_mul_f32 v[46:47], v[46:47], v[76:77] op_sel_hi:[1,0]
	v_pk_mul_f32 v[44:45], v[44:45], v[76:77] op_sel_hi:[1,0]
	v_pk_mul_f32 v[50:51], v[50:51], v[76:77] op_sel_hi:[1,0]
	v_pk_mul_f32 v[48:49], v[48:49], v[76:77] op_sel_hi:[1,0]
	v_cvt_pk_bf16_f32 v80, v138, v136
	v_cvt_pk_bf16_f32 v81, v134, v132
	v_cvt_pk_bf16_f32 v82, v130, v128
	v_cvt_pk_bf16_f32 v83, v126, v124
	v_cvt_pk_bf16_f32 v84, v122, v120
	v_cvt_pk_bf16_f32 v85, v118, v114
	v_cvt_pk_bf16_f32 v86, v110, v108
	v_cvt_pk_bf16_f32 v87, v116, v112
	s_setprio 1
	v_add3_u32 v77, s83, v164, v165
	ds_read_b64_tr_b16 v[206:207], v77 offset:20992
	ds_read_b64_tr_b16 v[204:205], v77 offset:18432
	ds_read_b64_tr_b16 v[208:209], v77 offset:18464
	ds_read_b64_tr_b16 v[210:211], v77 offset:21024
	ds_read_b64_tr_b16 v[212:213], v77 offset:23552
	ds_read_b64_tr_b16 v[214:215], v77 offset:26112
	ds_read_b64_tr_b16 v[216:217], v77 offset:23584
	ds_read_b64_tr_b16 v[218:219], v77 offset:26144
	ds_read_b64_tr_b16 v[220:221], v77 offset:18496
	ds_read_b64_tr_b16 v[222:223], v77 offset:21056
	ds_read_b64_tr_b16 v[224:225], v77 offset:23616
	ds_read_b64_tr_b16 v[226:227], v77 offset:26176
	ds_read_b64_tr_b16 v[228:229], v77 offset:18528
	ds_read_b64_tr_b16 v[230:231], v77 offset:21088
	ds_read_b64_tr_b16 v[232:233], v77 offset:23648
	ds_read_b64_tr_b16 v[234:235], v77 offset:26208
	s_waitcnt lgkmcnt(14)
	v_mfma_f32_16x16x32_bf16 v[56:59], v[204:207], v[72:75], v[56:59]
	v_mfma_f32_16x16x32_bf16 v[40:43], v[204:207], v[80:83], v[40:43]
	s_waitcnt lgkmcnt(10)
	v_mfma_f32_16x16x32_bf16 v[56:59], v[212:215], v[64:67], v[56:59]
	v_mfma_f32_16x16x32_bf16 v[40:43], v[212:215], v[84:87], v[40:43]
	v_mfma_f32_16x16x32_bf16 v[52:55], v[208:211], v[72:75], v[52:55]
	v_mfma_f32_16x16x32_bf16 v[36:39], v[208:211], v[80:83], v[36:39]
	s_waitcnt lgkmcnt(8)
	v_mfma_f32_16x16x32_bf16 v[52:55], v[216:219], v[64:67], v[52:55]
	v_mfma_f32_16x16x32_bf16 v[36:39], v[216:219], v[84:87], v[36:39]
	s_waitcnt lgkmcnt(6)
	v_mfma_f32_16x16x32_bf16 v[60:63], v[220:223], v[72:75], v[60:63]
	v_mfma_f32_16x16x32_bf16 v[44:47], v[220:223], v[80:83], v[44:47]
	s_waitcnt lgkmcnt(4)
	v_mfma_f32_16x16x32_bf16 v[60:63], v[224:227], v[64:67], v[60:63]
	v_mfma_f32_16x16x32_bf16 v[44:47], v[224:227], v[84:87], v[44:47]
	s_waitcnt lgkmcnt(2)
	v_mfma_f32_16x16x32_bf16 v[68:71], v[228:231], v[72:75], v[68:71]
	v_mfma_f32_16x16x32_bf16 v[48:51], v[228:231], v[80:83], v[48:51]
	s_waitcnt lgkmcnt(0)
	v_mfma_f32_16x16x32_bf16 v[64:67], v[232:235], v[64:67], v[68:71]
	v_mfma_f32_16x16x32_bf16 v[48:51], v[232:235], v[84:87], v[48:51]
	s_nop 3
	s_setprio 0
	s_setprio 1
	ds_read_b128 v[204:207], v88 offset:9216
	ds_read_b128 v[208:211], v88 offset:9280
	ds_read_b128 v[212:215], v88 offset:11520
	ds_read_b128 v[216:219], v88 offset:13824
	ds_read_b128 v[220:223], v88 offset:16128
	ds_read_b128 v[224:227], v88 offset:11584
	ds_read_b128 v[228:231], v88 offset:13888
	ds_read_b128 v[232:235], v88 offset:16192
	s_waitcnt lgkmcnt(7)
	v_mfma_f32_16x16x32_bf16 v[72:75], v[204:207], v[4:7], v[0:3]
	v_mfma_f32_16x16x32_bf16 v[68:71], v[204:207], v[12:15], v[0:3]
	s_waitcnt lgkmcnt(6)
	v_mfma_f32_16x16x32_bf16 v[168:171], v[208:211], v[16:19], v[68:71]
	v_mfma_f32_16x16x32_bf16 v[72:75], v[208:211], v[8:11], v[72:75]
	s_waitcnt lgkmcnt(5)
	v_mfma_f32_16x16x32_bf16 v[84:87], v[212:215], v[4:7], v[0:3]
	v_mfma_f32_16x16x32_bf16 v[80:83], v[212:215], v[12:15], v[0:3]
	s_waitcnt lgkmcnt(2)
	v_mfma_f32_16x16x32_bf16 v[84:87], v[224:227], v[8:11], v[84:87]
	v_mfma_f32_16x16x32_bf16 v[184:187], v[224:227], v[16:19], v[80:83]
	v_mfma_f32_16x16x32_bf16 v[146:149], v[216:219], v[4:7], v[0:3]
	v_mfma_f32_16x16x32_bf16 v[142:145], v[216:219], v[12:15], v[0:3]
	s_waitcnt lgkmcnt(1)
	v_mfma_f32_16x16x32_bf16 v[80:83], v[228:231], v[8:11], v[146:149]
	v_mfma_f32_16x16x32_bf16 v[188:191], v[228:231], v[16:19], v[142:145]
	v_mfma_f32_16x16x32_bf16 v[154:157], v[220:223], v[4:7], v[0:3]
	v_mfma_f32_16x16x32_bf16 v[150:153], v[220:223], v[12:15], v[0:3]
	s_waitcnt lgkmcnt(0)
	v_mfma_f32_16x16x32_bf16 v[142:145], v[232:235], v[8:11], v[154:157]
	v_mfma_f32_16x16x32_bf16 v[192:195], v[232:235], v[16:19], v[150:153]
	s_nop 0
	s_setprio 0
	v_mul_f32_e32 v68, 0x3e38aa3b, v72
	v_add_u32_e32 v69, 51, v166
	v_mul_f32_e32 v71, 0x3e38aa3b, v74
	v_add_u32_e32 v72, 49, v166
	v_add_u32_e32 v74, 35, v166
	v_cmp_gt_u32_e64 s[12:13], s39, v69
	v_mul_f32_e32 v69, 0x3e38aa3b, v73
	v_cmp_gt_u32_e64 s[16:17], s39, v72
	v_mul_f32_e32 v72, 0x3e38aa3b, v75
	v_add_u32_e32 v73, 48, v166
	v_cmp_gt_u32_e64 s[20:21], s39, v74
	v_add_u32_e32 v75, 34, v166
	v_cmp_gt_u32_e64 s[18:19], s39, v73
	v_mul_f32_e32 v73, 0x3e38aa3b, v84
	s_and_b64 s[20:21], s[74:75], s[20:21]
	v_cmp_gt_u32_e64 s[22:23], s39, v75
	v_add_u32_e32 v79, 33, v166
	v_cndmask_b32_e64 v74, v73, v181, s[20:21]
	v_mul_f32_e32 v73, 0x3e38aa3b, v85
	s_and_b64 s[22:23], s[74:75], s[22:23]
	v_cmp_gt_u32_e64 s[24:25], s39, v79
	v_add_u32_e32 v84, 32, v166
	v_cndmask_b32_e64 v75, v73, v181, s[22:23]
	v_mul_f32_e32 v73, 0x3e38aa3b, v86
	s_and_b64 s[24:25], s[74:75], s[24:25]
	v_cmp_gt_u32_e64 s[26:27], s39, v84
	v_cndmask_b32_e64 v79, v73, v181, s[24:25]
	v_mul_f32_e32 v73, 0x3e38aa3b, v87
	s_and_b64 s[26:27], s[74:75], s[26:27]
	v_cndmask_b32_e64 v84, v73, v181, s[26:27]
	v_mul_f32_e32 v73, 0x3e38aa3b, v80
	v_add_u32_e32 v80, 19, v166
	v_cmp_gt_u32_e64 s[28:29], s39, v80
	s_and_b64 s[28:29], s[74:75], s[28:29]
	v_add_u32_e32 v70, 50, v166
	v_cndmask_b32_e64 v80, v73, v181, s[28:29]
	v_mul_f32_e32 v73, 0x3e38aa3b, v81
	v_add_u32_e32 v81, 18, v166
	v_cmp_gt_u32_e64 s[30:31], s39, v81
	s_and_b64 s[30:31], s[74:75], s[30:31]
	v_cmp_gt_u32_e64 s[14:15], s39, v70
	v_cndmask_b32_e64 v81, v73, v181, s[30:31]
	v_mul_f32_e32 v73, 0x3e38aa3b, v82
	v_add_u32_e32 v82, 17, v166
	v_cmp_gt_u32_e64 s[34:35], s39, v82
	s_and_b64 s[34:35], s[74:75], s[34:35]
	v_add_u32_e32 v85, 3, v166
	v_cndmask_b32_e64 v82, v73, v181, s[34:35]
	v_mul_f32_e32 v73, 0x3e38aa3b, v83
	v_add_u32_e32 v83, 16, v166
	v_cmp_gt_u32_e64 s[36:37], s39, v83
	s_and_b64 s[12:13], s[74:75], s[12:13]
	s_and_b64 s[14:15], s[74:75], s[14:15]
	s_and_b64 s[36:37], s[74:75], s[36:37]
	v_cmp_gt_u32_e64 s[40:41], s39, v85
	v_cndmask_b32_e64 v68, v68, v181, s[12:13]
	v_cndmask_b32_e64 v69, v69, v181, s[14:15]
	s_and_b64 s[16:17], s[74:75], s[16:17]
	s_and_b64 s[18:19], s[74:75], s[18:19]
	v_cndmask_b32_e64 v83, v73, v181, s[36:37]
	v_mul_f32_e32 v73, 0x3e38aa3b, v142
	s_and_b64 s[40:41], s[74:75], s[40:41]
	v_add_u32_e32 v86, 2, v166
	v_max3_f32 v70, v68, s68, v69
	v_cndmask_b32_e64 v71, v71, v181, s[16:17]
	v_cndmask_b32_e64 v72, v72, v181, s[18:19]
	v_cndmask_b32_e64 v85, v73, v181, s[40:41]
	v_cmp_gt_u32_e64 s[40:41], s39, v86
	v_max3_f32 v70, v70, v71, v72
	v_mul_f32_e32 v73, 0x3e38aa3b, v143
	s_and_b64 s[40:41], s[74:75], s[40:41]
	v_add_u32_e32 v87, 1, v166
	v_max3_f32 v70, v70, v74, v75
	v_cndmask_b32_e64 v86, v73, v181, s[40:41]
	v_cmp_gt_u32_e64 s[40:41], s39, v87
	v_max3_f32 v70, v70, v79, v84
	v_mul_f32_e32 v73, 0x3e38aa3b, v144
	s_and_b64 s[40:41], s[74:75], s[40:41]
	v_max3_f32 v70, v70, v80, v81
	v_cndmask_b32_e64 v88, v73, v181, s[40:41]
	v_cmp_gt_u32_e64 s[40:41], s39, v166
	v_max3_f32 v70, v70, v82, v83
	v_mul_f32_e32 v73, 0x3e38aa3b, v145
	s_and_b64 s[40:41], s[74:75], s[40:41]
	v_max3_f32 v70, v70, v85, v86
	v_cndmask_b32_e64 v142, v73, v181, s[40:41]
	v_max3_f32 v70, v70, v88, v142
	v_mov_b32_e32 v73, v70
	s_nop 1
	v_permlane16_swap_b32_e32 v70, v73
	v_max_f32_e32 v70, v70, v73
	v_mov_b32_e32 v73, v70
	s_nop 1
	v_permlane32_swap_b32_e32 v70, v73
	v_max3_f32 v73, v140, v70, v73
	v_sub_f32_e32 v68, v68, v73
	v_exp_f32_e32 v159, v68
	v_sub_f32_e32 v68, v69, v73
	v_exp_f32_e32 v157, v68
	v_sub_f32_e32 v68, v71, v73
	v_exp_f32_e32 v155, v68
	v_sub_f32_e32 v68, v72, v73
	v_exp_f32_e32 v153, v68
	v_sub_f32_e32 v68, v74, v73
	v_exp_f32_e32 v151, v68
	v_sub_f32_e32 v68, v75, v73
	v_exp_f32_e32 v149, v68
	v_sub_f32_e32 v68, v79, v73
	v_exp_f32_e32 v147, v68
	v_sub_f32_e32 v68, v84, v73
	v_exp_f32_e32 v145, v68
	v_sub_f32_e32 v68, v80, v73
	v_exp_f32_e32 v143, v68
	v_sub_f32_e32 v68, v81, v73
	v_exp_f32_e32 v141, v68
	v_sub_f32_e32 v68, v82, v73
	v_sub_f32_e32 v70, v140, v73
	v_exp_f32_e32 v87, v68
	v_sub_f32_e32 v68, v83, v73
	v_exp_f32_e32 v83, v68
	v_sub_f32_e32 v68, v85, v73
	v_exp_f32_e32 v72, v70
	v_exp_f32_e32 v79, v68
	v_sub_f32_e32 v68, v86, v73
	v_exp_f32_e32 v75, v68
	v_sub_f32_e32 v68, v88, v73
	v_exp_f32_e32 v85, v68
	v_sub_f32_e32 v68, v142, v73
	v_exp_f32_e32 v81, v68
	v_pk_mul_f32 v[68:69], v[64:65], v[72:73] op_sel_hi:[1,0]
	v_mul_f32_e32 v64, 0x3e38aa3b, v168
	v_cndmask_b32_e32 v74, v64, v181, vcc
	v_mul_f32_e32 v64, 0x3e38aa3b, v169
	v_cndmask_b32_e64 v80, v64, v181, s[6:7]
	v_mul_f32_e32 v64, 0x3e38aa3b, v170
	v_cndmask_b32_e64 v82, v64, v181, s[8:9]
	v_mul_f32_e32 v64, 0x3e38aa3b, v171
	v_cndmask_b32_e64 v84, v64, v181, s[10:11]
	v_mul_f32_e32 v64, 0x3e38aa3b, v184
	v_cndmask_b32_e64 v86, v64, v181, s[12:13]
	v_mul_f32_e32 v64, 0x3e38aa3b, v185
	v_cndmask_b32_e64 v88, v64, v181, s[14:15]
	v_mul_f32_e32 v64, 0x3e38aa3b, v186
	v_cndmask_b32_e64 v140, v64, v181, s[16:17]
	v_mul_f32_e32 v64, 0x3e38aa3b, v187
	v_cndmask_b32_e64 v142, v64, v181, s[18:19]
	v_mul_f32_e32 v64, 0x3e38aa3b, v188
	v_cndmask_b32_e64 v160, v64, v181, s[20:21]
	v_mul_f32_e32 v64, 0x3e38aa3b, v189
	v_cndmask_b32_e64 v161, v64, v181, s[22:23]
	v_mul_f32_e32 v64, 0x3e38aa3b, v190
	v_cndmask_b32_e64 v172, v64, v181, s[24:25]
	v_mul_f32_e32 v64, 0x3e38aa3b, v191
	v_cndmask_b32_e64 v173, v64, v181, s[26:27]
	v_mul_f32_e32 v64, 0x3e38aa3b, v192
	v_cndmask_b32_e64 v184, v64, v181, s[28:29]
	v_mul_f32_e32 v64, 0x3e38aa3b, v193
	v_cndmask_b32_e64 v185, v64, v181, s[30:31]
	v_mul_f32_e32 v64, 0x3e38aa3b, v194
	v_cndmask_b32_e64 v186, v64, v181, s[34:35]
	v_mul_f32_e32 v64, 0x3e38aa3b, v195
	v_cndmask_b32_e64 v187, v64, v181, s[36:37]
	v_max3_f32 v64, v74, s68, v80
	v_max3_f32 v64, v64, v82, v84
	v_max3_f32 v64, v64, v86, v88
	v_max3_f32 v64, v64, v140, v142
	v_max3_f32 v64, v64, v160, v161
	v_max3_f32 v64, v64, v172, v173
	v_max3_f32 v144, v64, v184, v185
	v_max3_f32 v144, v144, v186, v187
	v_mov_b32_e32 v146, v144
	s_nop 1
	v_permlane16_swap_b32_e32 v144, v146
	v_max_f32_e32 v144, v144, v146
	v_mov_b32_e32 v146, v144
	s_nop 1
	v_permlane32_swap_b32_e32 v144, v146
	v_max3_f32 v167, v78, v144, v146
	v_sub_f32_e32 v74, v74, v167
	v_exp_f32_e32 v158, v74
	v_sub_f32_e32 v74, v80, v167
	v_exp_f32_e32 v156, v74
	v_sub_f32_e32 v74, v82, v167
	v_exp_f32_e32 v154, v74
	v_sub_f32_e32 v74, v84, v167
	v_exp_f32_e32 v152, v74
	v_sub_f32_e32 v74, v86, v167
	v_exp_f32_e32 v150, v74
	v_sub_f32_e32 v74, v88, v167
	v_exp_f32_e32 v148, v74
	v_sub_f32_e32 v74, v140, v167
	v_exp_f32_e32 v146, v74
	v_sub_f32_e32 v74, v142, v167
	v_exp_f32_e32 v144, v74
	v_sub_f32_e32 v74, v160, v167
	v_exp_f32_e32 v142, v74
	v_sub_f32_e32 v74, v161, v167
	v_exp_f32_e32 v140, v74
	v_sub_f32_e32 v74, v172, v167
	v_exp_f32_e32 v86, v74
	v_sub_f32_e32 v74, v173, v167
	v_sub_f32_e32 v188, v78, v167
	v_exp_f32_e32 v82, v74
	v_sub_f32_e32 v74, v184, v167
	v_sub_f32_e32 v80, v186, v167
	v_exp_f32_e32 v78, v74
	v_sub_f32_e32 v74, v185, v167
	v_exp_f32_e32 v160, v188
	v_exp_f32_e32 v84, v80
	v_sub_f32_e32 v80, v187, v167
	v_exp_f32_e32 v74, v74
	v_exp_f32_e32 v80, v80
	v_pk_mul_f32 v[58:59], v[58:59], v[72:73] op_sel_hi:[1,0]
	v_pk_mul_f32 v[56:57], v[56:57], v[72:73] op_sel_hi:[1,0]
	v_pk_mul_f32 v[54:55], v[54:55], v[72:73] op_sel_hi:[1,0]
	v_pk_mul_f32 v[52:53], v[52:53], v[72:73] op_sel_hi:[1,0]
	v_pk_mul_f32 v[62:63], v[62:63], v[72:73] op_sel_hi:[1,0]
	v_pk_mul_f32 v[60:61], v[60:61], v[72:73] op_sel_hi:[1,0]
	v_pk_mul_f32 v[70:71], v[66:67], v[72:73] op_sel_hi:[1,0]
	v_cvt_pk_bf16_f32 v64, v143, v141
	v_cvt_pk_bf16_f32 v65, v87, v83
	v_cvt_pk_bf16_f32 v66, v79, v75
	v_cvt_pk_bf16_f32 v67, v85, v81
	v_pk_mul_f32 v[42:43], v[42:43], v[160:161] op_sel_hi:[1,0]
	v_pk_mul_f32 v[40:41], v[40:41], v[160:161] op_sel_hi:[1,0]
	v_pk_mul_f32 v[38:39], v[38:39], v[160:161] op_sel_hi:[1,0]
	v_pk_mul_f32 v[36:37], v[36:37], v[160:161] op_sel_hi:[1,0]
	v_pk_mul_f32 v[46:47], v[46:47], v[160:161] op_sel_hi:[1,0]
	v_pk_mul_f32 v[44:45], v[44:45], v[160:161] op_sel_hi:[1,0]
	v_pk_mul_f32 v[50:51], v[50:51], v[160:161] op_sel_hi:[1,0]
	v_pk_mul_f32 v[48:49], v[48:49], v[160:161] op_sel_hi:[1,0]
	v_cvt_pk_bf16_f32 v168, v159, v157
	v_cvt_pk_bf16_f32 v169, v155, v153
	v_cvt_pk_bf16_f32 v170, v151, v149
	v_cvt_pk_bf16_f32 v171, v147, v145
	v_cvt_pk_bf16_f32 v184, v158, v156
	v_cvt_pk_bf16_f32 v185, v154, v152
	v_cvt_pk_bf16_f32 v186, v150, v148
	v_cvt_pk_bf16_f32 v187, v146, v144
	v_cvt_pk_bf16_f32 v188, v142, v140
	v_cvt_pk_bf16_f32 v189, v86, v82
	v_cvt_pk_bf16_f32 v190, v78, v74
	v_cvt_pk_bf16_f32 v191, v84, v80
	s_setprio 1
	ds_read_b64_tr_b16 v[206:207], v77 offset:31232
	ds_read_b64_tr_b16 v[204:205], v77 offset:28672
	ds_read_b64_tr_b16 v[208:209], v77 offset:28704
	ds_read_b64_tr_b16 v[210:211], v77 offset:31264
	ds_read_b64_tr_b16 v[212:213], v77 offset:33792
	ds_read_b64_tr_b16 v[214:215], v77 offset:36352
	ds_read_b64_tr_b16 v[216:217], v77 offset:33824
	ds_read_b64_tr_b16 v[218:219], v77 offset:36384
	ds_read_b64_tr_b16 v[220:221], v77 offset:28736
	ds_read_b64_tr_b16 v[222:223], v77 offset:31296
	ds_read_b64_tr_b16 v[224:225], v77 offset:33856
	ds_read_b64_tr_b16 v[226:227], v77 offset:36416
	ds_read_b64_tr_b16 v[228:229], v77 offset:28768
	ds_read_b64_tr_b16 v[230:231], v77 offset:31328
	ds_read_b64_tr_b16 v[232:233], v77 offset:33888
	ds_read_b64_tr_b16 v[234:235], v77 offset:36448
	s_waitcnt lgkmcnt(14)
	v_mfma_f32_16x16x32_bf16 v[56:59], v[204:207], v[168:171], v[56:59]
	v_mfma_f32_16x16x32_bf16 v[40:43], v[204:207], v[184:187], v[40:43]
	s_waitcnt lgkmcnt(10)
	v_mfma_f32_16x16x32_bf16 v[56:59], v[212:215], v[64:67], v[56:59]
	v_mfma_f32_16x16x32_bf16 v[40:43], v[212:215], v[188:191], v[40:43]
	v_mfma_f32_16x16x32_bf16 v[52:55], v[208:211], v[168:171], v[52:55]
	v_mfma_f32_16x16x32_bf16 v[36:39], v[208:211], v[184:187], v[36:39]
	s_waitcnt lgkmcnt(8)
	v_mfma_f32_16x16x32_bf16 v[52:55], v[216:219], v[64:67], v[52:55]
	v_mfma_f32_16x16x32_bf16 v[36:39], v[216:219], v[188:191], v[36:39]
	s_waitcnt lgkmcnt(6)
	v_mfma_f32_16x16x32_bf16 v[60:63], v[220:223], v[168:171], v[60:63]
	v_mfma_f32_16x16x32_bf16 v[44:47], v[220:223], v[184:187], v[44:47]
	s_waitcnt lgkmcnt(4)
	v_mfma_f32_16x16x32_bf16 v[60:63], v[224:227], v[64:67], v[60:63]
	v_mfma_f32_16x16x32_bf16 v[44:47], v[224:227], v[188:191], v[44:47]
	s_waitcnt lgkmcnt(2)
	v_mfma_f32_16x16x32_bf16 v[68:71], v[228:231], v[168:171], v[68:71]
	v_mfma_f32_16x16x32_bf16 v[48:51], v[228:231], v[184:187], v[48:51]
	s_waitcnt lgkmcnt(0)
	v_mfma_f32_16x16x32_bf16 v[64:67], v[232:235], v[64:67], v[68:71]
	v_mfma_f32_16x16x32_bf16 v[48:51], v[232:235], v[188:191], v[48:51]
	s_nop 3
	s_setprio 0
	s_add_i32 s12, s82, 1
	s_cmp_ge_i32 s12, s44
	s_cbranch_scc1 .LBB0_3060
	s_bitcmp1_b32 s12, 0
	s_cselect_b32 s6, 0x9800, 0
	v_add3_u32 v71, s6, v99, v98
	v_add3_u32 v68, s6, v162, v98
	v_add3_u32 v69, s6, v107, v98
	v_add3_u32 v70, s6, v105, v98
	s_waitcnt vmcnt(0)
	ds_write_b128 v71, v[20:23]
	ds_write_b128 v70, v[24:27]
	ds_write_b128 v69, v[28:31] offset:18432
	ds_write_b128 v68, v[32:35] offset:18432

.Lnm1_entry:
	s_setprio 1
	v_or_b32_e32 v68, s83, v94
	v_add_u32_e32 v88, v68, v163
	ds_read_b128 v[204:207], v88 offset:2304
	ds_read_b128 v[208:211], v88
	ds_read_b128 v[212:215], v88 offset:4608
	ds_read_b128 v[216:219], v88 offset:6912
	ds_read_b128 v[220:223], v88 offset:64
	ds_read_b128 v[224:227], v88 offset:2368
	ds_read_b128 v[228:231], v88 offset:4672
	ds_read_b128 v[232:235], v88 offset:6976
	s_waitcnt lgkmcnt(7)
	v_mfma_f32_16x16x32_bf16 v[82:85], v[204:207], v[4:7], v[0:3]
	v_mfma_f32_16x16x32_bf16 v[108:111], v[204:207], v[12:15], v[0:3]
	s_waitcnt lgkmcnt(5)
	v_mfma_f32_16x16x32_bf16 v[112:115], v[212:215], v[4:7], v[0:3]
	v_mfma_f32_16x16x32_bf16 v[116:119], v[212:215], v[12:15], v[0:3]
	s_waitcnt lgkmcnt(4)
	v_mfma_f32_16x16x32_bf16 v[120:123], v[216:219], v[4:7], v[0:3]
	v_mfma_f32_16x16x32_bf16 v[124:127], v[216:219], v[12:15], v[0:3]
	v_mfma_f32_16x16x32_bf16 v[74:77], v[208:211], v[4:7], v[0:3]
	v_mfma_f32_16x16x32_bf16 v[68:71], v[208:211], v[12:15], v[0:3]
	s_waitcnt lgkmcnt(3)
	v_mfma_f32_16x16x32_bf16 v[128:131], v[220:223], v[8:11], v[74:77]
	v_mfma_f32_16x16x32_bf16 v[76:79], v[220:223], v[16:19], v[68:71]
	s_waitcnt lgkmcnt(2)
	v_mfma_f32_16x16x32_bf16 v[132:135], v[224:227], v[8:11], v[82:85]
	v_mfma_f32_16x16x32_bf16 v[80:83], v[224:227], v[16:19], v[108:111]
	s_waitcnt lgkmcnt(1)
	v_mfma_f32_16x16x32_bf16 v[108:111], v[228:231], v[8:11], v[112:115]
	v_mfma_f32_16x16x32_bf16 v[84:87], v[228:231], v[16:19], v[116:119]
	s_waitcnt lgkmcnt(0)
	v_mfma_f32_16x16x32_bf16 v[112:115], v[232:235], v[8:11], v[120:123]
	v_mfma_f32_16x16x32_bf16 v[142:145], v[232:235], v[16:19], v[124:127]
	s_nop 1
	s_setprio 0
	v_mul_f32_e32 v68, 0x3e38aa3b, v128
	v_mul_f32_e32 v69, 0x3e38aa3b, v129
	v_mul_f32_e32 v71, 0x3e38aa3b, v130
	v_mul_f32_e32 v72, 0x3e38aa3b, v131
	v_max3_f32 v70, v68, s68, v69
	v_mul_f32_e32 v74, 0x3e38aa3b, v132
	v_mul_f32_e32 v75, 0x3e38aa3b, v133
	v_max3_f32 v70, v70, v71, v72
	v_mul_f32_e32 v106, 0x3e38aa3b, v134
	v_mul_f32_e32 v116, 0x3e38aa3b, v135
	v_max3_f32 v70, v70, v74, v75
	v_mul_f32_e32 v108, 0x3e38aa3b, v108
	v_mul_f32_e32 v109, 0x3e38aa3b, v109
	v_max3_f32 v70, v70, v106, v116
	v_mul_f32_e32 v110, 0x3e38aa3b, v110
	v_mul_f32_e32 v111, 0x3e38aa3b, v111
	v_max3_f32 v70, v70, v108, v109
	v_mul_f32_e32 v112, 0x3e38aa3b, v112
	v_mul_f32_e32 v113, 0x3e38aa3b, v113
	v_max3_f32 v70, v70, v110, v111
	v_mul_f32_e32 v114, 0x3e38aa3b, v114
	v_mul_f32_e32 v115, 0x3e38aa3b, v115
	v_max3_f32 v70, v70, v112, v113
	v_mov_b32_e32 v118, v115
	v_max3_f32 v70, v70, v114, v118
	v_mov_b32_e32 v115, v70
	s_nop 1
	v_permlane16_swap_b32_e32 v70, v115
	v_max_f32_e32 v70, v70, v115
	v_mov_b32_e32 v115, v70
	s_nop 1
	v_permlane32_swap_b32_e32 v70, v115
	v_max3_f32 v140, v73, v70, v115
	v_sub_f32_e32 v68, v68, v140
	v_exp_f32_e32 v139, v68
	v_sub_f32_e32 v68, v69, v140
	v_exp_f32_e32 v137, v68
	v_sub_f32_e32 v68, v71, v140
	v_exp_f32_e32 v135, v68
	v_sub_f32_e32 v68, v72, v140
	v_exp_f32_e32 v133, v68
	v_sub_f32_e32 v68, v74, v140
	v_exp_f32_e32 v131, v68
	v_sub_f32_e32 v68, v75, v140
	v_exp_f32_e32 v129, v68
	v_sub_f32_e32 v68, v106, v140
	v_exp_f32_e32 v127, v68
	v_sub_f32_e32 v68, v116, v140
	v_exp_f32_e32 v125, v68
	v_sub_f32_e32 v68, v108, v140
	v_mul_f32_e32 v76, 0x3e38aa3b, v76
	v_exp_f32_e32 v123, v68
	v_sub_f32_e32 v68, v109, v140
	v_exp_f32_e32 v121, v68
	v_sub_f32_e32 v68, v110, v140
	v_mul_f32_e32 v77, 0x3e38aa3b, v77
	v_mul_f32_e32 v78, 0x3e38aa3b, v78
	v_mov_b32_e32 v110, v78
	v_mul_f32_e32 v78, 0x3e38aa3b, v79
	v_max3_f32 v108, v76, s68, v77
	v_mov_b32_e32 v79, v78
	v_mul_f32_e32 v80, 0x3e38aa3b, v80
	v_mul_f32_e32 v81, 0x3e38aa3b, v81
	v_exp_f32_e32 v119, v68
	v_sub_f32_e32 v68, v111, v140
	v_max3_f32 v78, v108, v110, v79
	v_mul_f32_e32 v82, 0x3e38aa3b, v82
	v_mul_f32_e32 v83, 0x3e38aa3b, v83
	v_exp_f32_e32 v115, v68
	v_sub_f32_e32 v68, v112, v140
	v_max3_f32 v78, v78, v80, v81
	v_mul_f32_e32 v84, 0x3e38aa3b, v84
	v_mul_f32_e32 v85, 0x3e38aa3b, v85
	v_exp_f32_e32 v111, v68
	v_sub_f32_e32 v68, v113, v140
	v_max3_f32 v78, v78, v82, v83
	v_mul_f32_e32 v86, 0x3e38aa3b, v86
	v_mul_f32_e32 v87, 0x3e38aa3b, v87
	v_exp_f32_e32 v109, v68
	v_sub_f32_e32 v68, v114, v140
	v_max3_f32 v78, v78, v84, v85
	v_mul_f32_e32 v108, 0x3e38aa3b, v142
	v_mul_f32_e32 v112, 0x3e38aa3b, v143
	v_mul_f32_e32 v114, 0x3e38aa3b, v144
	v_max3_f32 v78, v78, v86, v87
	v_mov_b32_e32 v116, v114
	v_mul_f32_e32 v114, 0x3e38aa3b, v145
	v_max3_f32 v78, v78, v108, v112
	v_mov_b32_e32 v141, v114
	v_max3_f32 v78, v78, v116, v141
	v_mov_b32_e32 v114, v78
	s_nop 1
	v_permlane16_swap_b32_e32 v78, v114
	v_max_f32_e32 v78, v78, v114
	v_mov_b32_e32 v114, v78
	s_nop 1
	v_permlane32_swap_b32_e32 v78, v114
	v_max3_f32 v78, v167, v78, v114
	v_sub_f32_e32 v76, v76, v78
	v_exp_f32_e32 v138, v76
	v_sub_f32_e32 v76, v77, v78
	v_exp_f32_e32 v136, v76
	v_sub_f32_e32 v76, v110, v78
	v_exp_f32_e32 v134, v76
	v_sub_f32_e32 v76, v79, v78
	v_exp_f32_e32 v132, v76
	v_sub_f32_e32 v76, v80, v78
	v_exp_f32_e32 v130, v76
	v_sub_f32_e32 v76, v81, v78
	v_exp_f32_e32 v128, v76
	v_sub_f32_e32 v76, v82, v78
	v_exp_f32_e32 v126, v76
	v_sub_f32_e32 v76, v83, v78
	v_exp_f32_e32 v124, v76
	v_sub_f32_e32 v76, v84, v78
	v_exp_f32_e32 v122, v76
	v_sub_f32_e32 v76, v85, v78
	v_exp_f32_e32 v120, v76
	v_sub_f32_e32 v76, v86, v78
	v_exp_f32_e32 v117, v68
	v_sub_f32_e32 v68, v118, v140
	v_exp_f32_e32 v118, v76
	v_sub_f32_e32 v76, v87, v78
	v_exp_f32_e32 v114, v76
	v_sub_f32_e32 v76, v108, v78
	v_sub_f32_e32 v77, v116, v78
	v_sub_f32_e32 v70, v73, v140
	v_sub_f32_e32 v142, v167, v78
	v_exp_f32_e32 v110, v76
	v_sub_f32_e32 v76, v112, v78
	v_exp_f32_e32 v116, v77
	v_sub_f32_e32 v77, v141, v78
	v_exp_f32_e32 v106, v70
	v_exp_f32_e32 v113, v68
	v_exp_f32_e32 v108, v76
	v_exp_f32_e32 v76, v142
	v_exp_f32_e32 v112, v77
	v_pk_mul_f32 v[58:59], v[58:59], v[106:107] op_sel_hi:[1,0]
	v_pk_mul_f32 v[56:57], v[56:57], v[106:107] op_sel_hi:[1,0]
	v_pk_mul_f32 v[54:55], v[54:55], v[106:107] op_sel_hi:[1,0]
	v_pk_mul_f32 v[52:53], v[52:53], v[106:107] op_sel_hi:[1,0]
	v_pk_mul_f32 v[62:63], v[62:63], v[106:107] op_sel_hi:[1,0]
	v_pk_mul_f32 v[60:61], v[60:61], v[106:107] op_sel_hi:[1,0]
	v_pk_mul_f32 v[70:71], v[66:67], v[106:107] op_sel_hi:[1,0]
	v_pk_mul_f32 v[68:69], v[64:65], v[106:107] op_sel_hi:[1,0]
	v_cvt_pk_bf16_f32 v72, v139, v137
	v_cvt_pk_bf16_f32 v73, v135, v133
	v_cvt_pk_bf16_f32 v74, v131, v129
	v_cvt_pk_bf16_f32 v75, v127, v125
	v_cvt_pk_bf16_f32 v64, v123, v121
	v_cvt_pk_bf16_f32 v65, v119, v115
	v_cvt_pk_bf16_f32 v66, v111, v109
	v_cvt_pk_bf16_f32 v67, v117, v113
	v_pk_mul_f32 v[42:43], v[42:43], v[76:77] op_sel_hi:[1,0]
	v_pk_mul_f32 v[40:41], v[40:41], v[76:77] op_sel_hi:[1,0]
	v_pk_mul_f32 v[38:39], v[38:39], v[76:77] op_sel_hi:[1,0]
	v_pk_mul_f32 v[36:37], v[36:37], v[76:77] op_sel_hi:[1,0]
	v_pk_mul_f32 v[46:47], v[46:47], v[76:77] op_sel_hi:[1,0]
	v_pk_mul_f32 v[44:45], v[44:45], v[76:77] op_sel_hi:[1,0]
	v_pk_mul_f32 v[50:51], v[50:51], v[76:77] op_sel_hi:[1,0]
	v_pk_mul_f32 v[48:49], v[48:49], v[76:77] op_sel_hi:[1,0]
	v_cvt_pk_bf16_f32 v80, v138, v136
	v_cvt_pk_bf16_f32 v81, v134, v132
	v_cvt_pk_bf16_f32 v82, v130, v128
	v_cvt_pk_bf16_f32 v83, v126, v124
	v_cvt_pk_bf16_f32 v84, v122, v120
	v_cvt_pk_bf16_f32 v85, v118, v114
	v_cvt_pk_bf16_f32 v86, v110, v108
	v_cvt_pk_bf16_f32 v87, v116, v112
	s_setprio 1
	v_add3_u32 v77, s83, v164, v165
	ds_read_b64_tr_b16 v[206:207], v77 offset:20992
	ds_read_b64_tr_b16 v[204:205], v77 offset:18432
	ds_read_b64_tr_b16 v[208:209], v77 offset:18464
	ds_read_b64_tr_b16 v[210:211], v77 offset:21024
	ds_read_b64_tr_b16 v[212:213], v77 offset:23552
	ds_read_b64_tr_b16 v[214:215], v77 offset:26112
	ds_read_b64_tr_b16 v[216:217], v77 offset:23584
	ds_read_b64_tr_b16 v[218:219], v77 offset:26144
	ds_read_b64_tr_b16 v[220:221], v77 offset:18496
	ds_read_b64_tr_b16 v[222:223], v77 offset:21056
	ds_read_b64_tr_b16 v[224:225], v77 offset:23616
	ds_read_b64_tr_b16 v[226:227], v77 offset:26176
	ds_read_b64_tr_b16 v[228:229], v77 offset:18528
	ds_read_b64_tr_b16 v[230:231], v77 offset:21088
	ds_read_b64_tr_b16 v[232:233], v77 offset:23648
	ds_read_b64_tr_b16 v[234:235], v77 offset:26208
	s_waitcnt lgkmcnt(14)
	v_mfma_f32_16x16x32_bf16 v[56:59], v[204:207], v[72:75], v[56:59]
	v_mfma_f32_16x16x32_bf16 v[40:43], v[204:207], v[80:83], v[40:43]
	s_waitcnt lgkmcnt(10)
	v_mfma_f32_16x16x32_bf16 v[56:59], v[212:215], v[64:67], v[56:59]
	v_mfma_f32_16x16x32_bf16 v[40:43], v[212:215], v[84:87], v[40:43]
	v_mfma_f32_16x16x32_bf16 v[52:55], v[208:211], v[72:75], v[52:55]
	v_mfma_f32_16x16x32_bf16 v[36:39], v[208:211], v[80:83], v[36:39]
	s_waitcnt lgkmcnt(8)
	v_mfma_f32_16x16x32_bf16 v[52:55], v[216:219], v[64:67], v[52:55]
	v_mfma_f32_16x16x32_bf16 v[36:39], v[216:219], v[84:87], v[36:39]
	s_waitcnt lgkmcnt(6)
	v_mfma_f32_16x16x32_bf16 v[60:63], v[220:223], v[72:75], v[60:63]
	v_mfma_f32_16x16x32_bf16 v[44:47], v[220:223], v[80:83], v[44:47]
	s_waitcnt lgkmcnt(4)
	v_mfma_f32_16x16x32_bf16 v[60:63], v[224:227], v[64:67], v[60:63]
	v_mfma_f32_16x16x32_bf16 v[44:47], v[224:227], v[84:87], v[44:47]
	s_waitcnt lgkmcnt(2)
	v_mfma_f32_16x16x32_bf16 v[68:71], v[228:231], v[72:75], v[68:71]
	v_mfma_f32_16x16x32_bf16 v[48:51], v[228:231], v[80:83], v[48:51]
	s_waitcnt lgkmcnt(0)
	v_mfma_f32_16x16x32_bf16 v[64:67], v[232:235], v[64:67], v[68:71]
	v_mfma_f32_16x16x32_bf16 v[48:51], v[232:235], v[84:87], v[48:51]
	s_nop 3
	s_setprio 0
	s_setprio 1
	ds_read_b128 v[204:207], v88 offset:9216
	ds_read_b128 v[208:211], v88 offset:9280
	ds_read_b128 v[212:215], v88 offset:11520
	ds_read_b128 v[216:219], v88 offset:13824
	ds_read_b128 v[220:223], v88 offset:16128
	ds_read_b128 v[224:227], v88 offset:11584
	ds_read_b128 v[228:231], v88 offset:13888
	ds_read_b128 v[232:235], v88 offset:16192
	s_waitcnt lgkmcnt(7)
	v_mfma_f32_16x16x32_bf16 v[72:75], v[204:207], v[4:7], v[0:3]
	v_mfma_f32_16x16x32_bf16 v[68:71], v[204:207], v[12:15], v[0:3]
	s_waitcnt lgkmcnt(6)
	v_mfma_f32_16x16x32_bf16 v[168:171], v[208:211], v[16:19], v[68:71]
	v_mfma_f32_16x16x32_bf16 v[72:75], v[208:211], v[8:11], v[72:75]
	s_waitcnt lgkmcnt(5)
	v_mfma_f32_16x16x32_bf16 v[84:87], v[212:215], v[4:7], v[0:3]
	v_mfma_f32_16x16x32_bf16 v[80:83], v[212:215], v[12:15], v[0:3]
	s_waitcnt lgkmcnt(2)
	v_mfma_f32_16x16x32_bf16 v[84:87], v[224:227], v[8:11], v[84:87]
	v_mfma_f32_16x16x32_bf16 v[184:187], v[224:227], v[16:19], v[80:83]
	v_mfma_f32_16x16x32_bf16 v[146:149], v[216:219], v[4:7], v[0:3]
	v_mfma_f32_16x16x32_bf16 v[142:145], v[216:219], v[12:15], v[0:3]
	s_waitcnt lgkmcnt(1)
	v_mfma_f32_16x16x32_bf16 v[80:83], v[228:231], v[8:11], v[146:149]
	v_mfma_f32_16x16x32_bf16 v[188:191], v[228:231], v[16:19], v[142:145]
	v_mfma_f32_16x16x32_bf16 v[154:157], v[220:223], v[4:7], v[0:3]
	v_mfma_f32_16x16x32_bf16 v[150:153], v[220:223], v[12:15], v[0:3]
	s_waitcnt lgkmcnt(0)
	v_mfma_f32_16x16x32_bf16 v[142:145], v[232:235], v[8:11], v[154:157]
	v_mfma_f32_16x16x32_bf16 v[192:195], v[232:235], v[16:19], v[150:153]
	s_nop 0
	s_setprio 0
	v_mul_f32_e32 v68, 0x3e38aa3b, v72
	v_mul_f32_e32 v71, 0x3e38aa3b, v74
	v_mul_f32_e32 v69, 0x3e38aa3b, v73
	v_mul_f32_e32 v72, 0x3e38aa3b, v75
	v_mul_f32_e32 v73, 0x3e38aa3b, v84
	v_mov_b32_e32 v74, v73
	v_mul_f32_e32 v73, 0x3e38aa3b, v85
	v_mov_b32_e32 v75, v73
	v_mul_f32_e32 v73, 0x3e38aa3b, v86
	v_mov_b32_e32 v79, v73
	v_mul_f32_e32 v73, 0x3e38aa3b, v87
	v_mov_b32_e32 v84, v73
	v_mul_f32_e32 v73, 0x3e38aa3b, v80
	v_mov_b32_e32 v80, v73
	v_mul_f32_e32 v73, 0x3e38aa3b, v81
	v_mov_b32_e32 v81, v73
	v_mul_f32_e32 v73, 0x3e38aa3b, v82
	v_mov_b32_e32 v82, v73
	v_mul_f32_e32 v73, 0x3e38aa3b, v83
	v_mov_b32_e32 v83, v73
	v_mul_f32_e32 v73, 0x3e38aa3b, v142
	v_max3_f32 v70, v68, s68, v69
	v_mov_b32_e32 v85, v73
	v_max3_f32 v70, v70, v71, v72
	v_mul_f32_e32 v73, 0x3e38aa3b, v143
	v_max3_f32 v70, v70, v74, v75
	v_mov_b32_e32 v86, v73
	v_max3_f32 v70, v70, v79, v84
	v_mul_f32_e32 v73, 0x3e38aa3b, v144
	v_max3_f32 v70, v70, v80, v81
	v_mov_b32_e32 v88, v73
	v_max3_f32 v70, v70, v82, v83
	v_mul_f32_e32 v73, 0x3e38aa3b, v145
	v_max3_f32 v70, v70, v85, v86
	v_mov_b32_e32 v142, v73
	v_max3_f32 v70, v70, v88, v142
	v_mov_b32_e32 v73, v70
	s_nop 1
	v_permlane16_swap_b32_e32 v70, v73
	v_max_f32_e32 v70, v70, v73
	v_mov_b32_e32 v73, v70
	s_nop 1
	v_permlane32_swap_b32_e32 v70, v73
	v_max3_f32 v73, v140, v70, v73
	v_sub_f32_e32 v68, v68, v73
	v_exp_f32_e32 v159, v68
	v_sub_f32_e32 v68, v69, v73
	v_exp_f32_e32 v157, v68
	v_sub_f32_e32 v68, v71, v73
	v_exp_f32_e32 v155, v68
	v_sub_f32_e32 v68, v72, v73
	v_exp_f32_e32 v153, v68
	v_sub_f32_e32 v68, v74, v73
	v_exp_f32_e32 v151, v68
	v_sub_f32_e32 v68, v75, v73
	v_exp_f32_e32 v149, v68
	v_sub_f32_e32 v68, v79, v73
	v_exp_f32_e32 v147, v68
	v_sub_f32_e32 v68, v84, v73
	v_exp_f32_e32 v145, v68
	v_sub_f32_e32 v68, v80, v73
	v_exp_f32_e32 v143, v68
	v_sub_f32_e32 v68, v81, v73
	v_exp_f32_e32 v141, v68
	v_sub_f32_e32 v68, v82, v73
	v_sub_f32_e32 v70, v140, v73
	v_exp_f32_e32 v87, v68
	v_sub_f32_e32 v68, v83, v73
	v_exp_f32_e32 v83, v68
	v_sub_f32_e32 v68, v85, v73
	v_exp_f32_e32 v72, v70
	v_exp_f32_e32 v79, v68
	v_sub_f32_e32 v68, v86, v73
	v_exp_f32_e32 v75, v68
	v_sub_f32_e32 v68, v88, v73
	v_exp_f32_e32 v85, v68
	v_sub_f32_e32 v68, v142, v73
	v_exp_f32_e32 v81, v68
	v_pk_mul_f32 v[68:69], v[64:65], v[72:73] op_sel_hi:[1,0]
	v_mul_f32_e32 v64, 0x3e38aa3b, v168
	v_mov_b32_e32 v74, v64
	v_mul_f32_e32 v64, 0x3e38aa3b, v169
	v_mov_b32_e32 v80, v64
	v_mul_f32_e32 v64, 0x3e38aa3b, v170
	v_mov_b32_e32 v82, v64
	v_mul_f32_e32 v64, 0x3e38aa3b, v171
	v_mov_b32_e32 v84, v64
	v_mul_f32_e32 v64, 0x3e38aa3b, v184
	v_mov_b32_e32 v86, v64
	v_mul_f32_e32 v64, 0x3e38aa3b, v185
	v_mov_b32_e32 v88, v64
	v_mul_f32_e32 v64, 0x3e38aa3b, v186
	v_mov_b32_e32 v140, v64
	v_mul_f32_e32 v64, 0x3e38aa3b, v187
	v_mov_b32_e32 v142, v64
	v_mul_f32_e32 v64, 0x3e38aa3b, v188
	v_mov_b32_e32 v160, v64
	v_mul_f32_e32 v64, 0x3e38aa3b, v189
	v_mov_b32_e32 v161, v64
	v_mul_f32_e32 v64, 0x3e38aa3b, v190
	v_mov_b32_e32 v172, v64
	v_mul_f32_e32 v64, 0x3e38aa3b, v191
	v_mov_b32_e32 v173, v64
	v_mul_f32_e32 v64, 0x3e38aa3b, v192
	v_mov_b32_e32 v184, v64
	v_mul_f32_e32 v64, 0x3e38aa3b, v193
	v_mov_b32_e32 v185, v64
	v_mul_f32_e32 v64, 0x3e38aa3b, v194
	v_mov_b32_e32 v186, v64
	v_mul_f32_e32 v64, 0x3e38aa3b, v195
	v_mov_b32_e32 v187, v64
	v_max3_f32 v64, v74, s68, v80
	v_max3_f32 v64, v64, v82, v84
	v_max3_f32 v64, v64, v86, v88
	v_max3_f32 v64, v64, v140, v142
	v_max3_f32 v64, v64, v160, v161
	v_max3_f32 v64, v64, v172, v173
	v_max3_f32 v144, v64, v184, v185
	v_max3_f32 v144, v144, v186, v187
	v_mov_b32_e32 v146, v144
	s_nop 1
	v_permlane16_swap_b32_e32 v144, v146
	v_max_f32_e32 v144, v144, v146
	v_mov_b32_e32 v146, v144
	s_nop 1
	v_permlane32_swap_b32_e32 v144, v146
	v_max3_f32 v167, v78, v144, v146
	v_sub_f32_e32 v74, v74, v167
	v_exp_f32_e32 v158, v74
	v_sub_f32_e32 v74, v80, v167
	v_exp_f32_e32 v156, v74
	v_sub_f32_e32 v74, v82, v167
	v_exp_f32_e32 v154, v74
	v_sub_f32_e32 v74, v84, v167
	v_exp_f32_e32 v152, v74
	v_sub_f32_e32 v74, v86, v167
	v_exp_f32_e32 v150, v74
	v_sub_f32_e32 v74, v88, v167
	v_exp_f32_e32 v148, v74
	v_sub_f32_e32 v74, v140, v167
	v_exp_f32_e32 v146, v74
	v_sub_f32_e32 v74, v142, v167
	v_exp_f32_e32 v144, v74
	v_sub_f32_e32 v74, v160, v167
	v_exp_f32_e32 v142, v74
	v_sub_f32_e32 v74, v161, v167
	v_exp_f32_e32 v140, v74
	v_sub_f32_e32 v74, v172, v167
	v_exp_f32_e32 v86, v74
	v_sub_f32_e32 v74, v173, v167
	v_sub_f32_e32 v188, v78, v167
	v_exp_f32_e32 v82, v74
	v_sub_f32_e32 v74, v184, v167
	v_sub_f32_e32 v80, v186, v167
	v_exp_f32_e32 v78, v74
	v_sub_f32_e32 v74, v185, v167
	v_exp_f32_e32 v160, v188
	v_exp_f32_e32 v84, v80
	v_sub_f32_e32 v80, v187, v167
	v_exp_f32_e32 v74, v74
	v_exp_f32_e32 v80, v80
	v_pk_mul_f32 v[58:59], v[58:59], v[72:73] op_sel_hi:[1,0]
	v_pk_mul_f32 v[56:57], v[56:57], v[72:73] op_sel_hi:[1,0]
	v_pk_mul_f32 v[54:55], v[54:55], v[72:73] op_sel_hi:[1,0]
	v_pk_mul_f32 v[52:53], v[52:53], v[72:73] op_sel_hi:[1,0]
	v_pk_mul_f32 v[62:63], v[62:63], v[72:73] op_sel_hi:[1,0]
	v_pk_mul_f32 v[60:61], v[60:61], v[72:73] op_sel_hi:[1,0]
	v_pk_mul_f32 v[70:71], v[66:67], v[72:73] op_sel_hi:[1,0]
	v_cvt_pk_bf16_f32 v64, v143, v141
	v_cvt_pk_bf16_f32 v65, v87, v83
	v_cvt_pk_bf16_f32 v66, v79, v75
	v_cvt_pk_bf16_f32 v67, v85, v81
	v_pk_mul_f32 v[42:43], v[42:43], v[160:161] op_sel_hi:[1,0]
	v_pk_mul_f32 v[40:41], v[40:41], v[160:161] op_sel_hi:[1,0]
	v_pk_mul_f32 v[38:39], v[38:39], v[160:161] op_sel_hi:[1,0]
	v_pk_mul_f32 v[36:37], v[36:37], v[160:161] op_sel_hi:[1,0]
	v_pk_mul_f32 v[46:47], v[46:47], v[160:161] op_sel_hi:[1,0]
	v_pk_mul_f32 v[44:45], v[44:45], v[160:161] op_sel_hi:[1,0]
	v_pk_mul_f32 v[50:51], v[50:51], v[160:161] op_sel_hi:[1,0]
	v_pk_mul_f32 v[48:49], v[48:49], v[160:161] op_sel_hi:[1,0]
	v_cvt_pk_bf16_f32 v168, v159, v157
	v_cvt_pk_bf16_f32 v169, v155, v153
	v_cvt_pk_bf16_f32 v170, v151, v149
	v_cvt_pk_bf16_f32 v171, v147, v145
	v_cvt_pk_bf16_f32 v184, v158, v156
	v_cvt_pk_bf16_f32 v185, v154, v152
	v_cvt_pk_bf16_f32 v186, v150, v148
	v_cvt_pk_bf16_f32 v187, v146, v144
	v_cvt_pk_bf16_f32 v188, v142, v140
	v_cvt_pk_bf16_f32 v189, v86, v82
	v_cvt_pk_bf16_f32 v190, v78, v74
	v_cvt_pk_bf16_f32 v191, v84, v80
	s_setprio 1
	ds_read_b64_tr_b16 v[206:207], v77 offset:31232
	ds_read_b64_tr_b16 v[204:205], v77 offset:28672
	ds_read_b64_tr_b16 v[208:209], v77 offset:28704
	ds_read_b64_tr_b16 v[210:211], v77 offset:31264
	ds_read_b64_tr_b16 v[212:213], v77 offset:33792
	ds_read_b64_tr_b16 v[214:215], v77 offset:36352
	ds_read_b64_tr_b16 v[216:217], v77 offset:33824
	ds_read_b64_tr_b16 v[218:219], v77 offset:36384
	ds_read_b64_tr_b16 v[220:221], v77 offset:28736
	ds_read_b64_tr_b16 v[222:223], v77 offset:31296
	ds_read_b64_tr_b16 v[224:225], v77 offset:33856
	ds_read_b64_tr_b16 v[226:227], v77 offset:36416
	ds_read_b64_tr_b16 v[228:229], v77 offset:28768
	ds_read_b64_tr_b16 v[230:231], v77 offset:31328
	ds_read_b64_tr_b16 v[232:233], v77 offset:33888
	ds_read_b64_tr_b16 v[234:235], v77 offset:36448
	s_waitcnt lgkmcnt(14)
	v_mfma_f32_16x16x32_bf16 v[56:59], v[204:207], v[168:171], v[56:59]
	v_mfma_f32_16x16x32_bf16 v[40:43], v[204:207], v[184:187], v[40:43]
	s_waitcnt lgkmcnt(10)
	v_mfma_f32_16x16x32_bf16 v[56:59], v[212:215], v[64:67], v[56:59]
	v_mfma_f32_16x16x32_bf16 v[40:43], v[212:215], v[188:191], v[40:43]
	v_mfma_f32_16x16x32_bf16 v[52:55], v[208:211], v[168:171], v[52:55]
	v_mfma_f32_16x16x32_bf16 v[36:39], v[208:211], v[184:187], v[36:39]
	s_waitcnt lgkmcnt(8)
	v_mfma_f32_16x16x32_bf16 v[52:55], v[216:219], v[64:67], v[52:55]
	v_mfma_f32_16x16x32_bf16 v[36:39], v[216:219], v[188:191], v[36:39]
	s_waitcnt lgkmcnt(6)
	v_mfma_f32_16x16x32_bf16 v[60:63], v[220:223], v[168:171], v[60:63]
	v_mfma_f32_16x16x32_bf16 v[44:47], v[220:223], v[184:187], v[44:47]
	s_waitcnt lgkmcnt(4)
	v_mfma_f32_16x16x32_bf16 v[60:63], v[224:227], v[64:67], v[60:63]
	v_mfma_f32_16x16x32_bf16 v[44:47], v[224:227], v[188:191], v[44:47]
	s_waitcnt lgkmcnt(2)
	v_mfma_f32_16x16x32_bf16 v[68:71], v[228:231], v[168:171], v[68:71]
	v_mfma_f32_16x16x32_bf16 v[48:51], v[228:231], v[184:187], v[48:51]
	s_waitcnt lgkmcnt(0)
	v_mfma_f32_16x16x32_bf16 v[64:67], v[232:235], v[64:67], v[68:71]
	v_mfma_f32_16x16x32_bf16 v[48:51], v[232:235], v[188:191], v[48:51]
	s_nop 3
	s_setprio 0
	s_add_i32 s12, s82, 1
	s_cmp_ge_i32 s12, s44
	s_cbranch_scc1 .Lnm1_b3060
	s_bitcmp1_b32 s12, 0
	s_cselect_b32 s6, 0x9800, 0
	v_add3_u32 v71, s6, v99, v98
	v_add3_u32 v68, s6, v162, v98
	v_add3_u32 v69, s6, v107, v98
	v_add3_u32 v70, s6, v105, v98
	s_waitcnt vmcnt(0)
	ds_write_b128 v71, v[20:23]
	ds_write_b128 v70, v[24:27]
	ds_write_b128 v69, v[28:31] offset:18432
	ds_write_b128 v68, v[32:35] offset:18432

.Lnm1_b3065:
	v_pk_add_f32 v[68:69], v[138:139], 0 op_sel_hi:[1,0]
	v_pk_add_f32 v[70:71], v[158:159], 0 op_sel_hi:[1,0]
	v_pk_add_f32 v[68:69], v[136:137], v[68:69]
	v_pk_add_f32 v[70:71], v[156:157], v[70:71]
	v_pk_add_f32 v[68:69], v[134:135], v[68:69]
	v_pk_add_f32 v[70:71], v[154:155], v[70:71]
	v_pk_add_f32 v[68:69], v[132:133], v[68:69]
	v_pk_add_f32 v[70:71], v[152:153], v[70:71]
	v_pk_add_f32 v[68:69], v[130:131], v[68:69]
	v_pk_add_f32 v[70:71], v[150:151], v[70:71]
	v_pk_add_f32 v[68:69], v[128:129], v[68:69]
	v_pk_add_f32 v[70:71], v[148:149], v[70:71]
	v_pk_add_f32 v[68:69], v[126:127], v[68:69]
	v_pk_add_f32 v[70:71], v[146:147], v[70:71]
	v_pk_add_f32 v[68:69], v[124:125], v[68:69]
	v_pk_add_f32 v[70:71], v[144:145], v[70:71]
	v_pk_add_f32 v[68:69], v[122:123], v[68:69]
	v_pk_add_f32 v[70:71], v[142:143], v[70:71]
	v_pk_add_f32 v[68:69], v[120:121], v[68:69]
	v_pk_add_f32 v[70:71], v[140:141], v[70:71]
	v_pk_add_f32 v[68:69], v[118:119], v[68:69]
	v_pk_add_f32 v[70:71], v[86:87], v[70:71]
	v_pk_add_f32 v[68:69], v[114:115], v[68:69]
	v_pk_add_f32 v[70:71], v[82:83], v[70:71]
	v_pk_add_f32 v[68:69], v[110:111], v[68:69]
	v_pk_add_f32 v[70:71], v[78:79], v[70:71]
	v_pk_add_f32 v[68:69], v[108:109], v[68:69]
	v_pk_add_f32 v[70:71], v[74:75], v[70:71]
	v_pk_add_f32 v[68:69], v[116:117], v[68:69]
	s_addk_i32 s81, 0x80
	v_pk_add_f32 v[68:69], v[112:113], v[68:69]
	v_mov_b32_e32 v77, v106
	v_pk_add_f32 v[70:71], v[84:85], v[70:71]
	s_add_u32 s72, s72, 0x80
	v_pk_fma_f32 v[68:69], v[96:97], v[76:77], v[68:69]
	v_pk_add_f32 v[70:71], v[80:81], v[70:71]
	v_mov_b32_e32 v161, v72
	s_addc_u32 s73, s73, 0
	v_pk_fma_f32 v[96:97], v[68:69], v[160:161], v[70:71]
	s_cmp_lg_u32 s44, s12
	s_waitcnt lgkmcnt(0)
	s_barrier
	s_cbranch_scc0 .LBB0_3068
	s_mov_b32 s82, s12
	s_branch .LBB0_3058

.LBB0_3387:
	s_or_b64 exec, exec, s[10:11]
	s_nop 0
	v_or_b32_e32 v120, 0x80, v144
	v_cmp_gt_i32_e64 s[10:11], s81, v120
	s_and_saveexec_b64 s[42:43], s[10:11]
	s_cbranch_execz .LBB0_3389
	v_max_f32_e32 v116, 0, v116
	v_max_f32_e32 v117, 0, v117
	v_max_f32_e32 v118, 0, v118
	v_max_f32_e32 v119, 0, v119
	v_max_f32_e32 v112, 0, v112
	v_max_f32_e32 v113, 0, v113
	v_max_f32_e32 v114, 0, v114
	v_max_f32_e32 v115, 0, v115
	v_pk_mul_f32 v[116:117], v[116:117], v[116:117]
	v_pk_mul_f32 v[118:119], v[118:119], v[118:119]
	v_pk_mul_f32 v[112:113], v[112:113], v[112:113]
	v_pk_mul_f32 v[114:115], v[114:115], v[114:115]
	v_cvt_pk_bf16_f32 v112, v112, v113
	v_cvt_pk_bf16_f32 v113, v114, v115
	v_cvt_pk_bf16_f32 v114, v116, v117
	v_cvt_pk_bf16_f32 v115, v118, v119
	flat_store_dwordx4 v[148:149], v[112:115] offset:256
